# as previous + GEMM K-loops: each half takes its pre-MMA barrier after its first 4 MFMAs (MFMA work overlaps the phase hand-off)
# speedup vs baseline: 1.0002x; 1.0002x over previous
; #define PG8_STAGE(bufoff, gbase, voff) do { _Pragma("unroll") for (int _i = 0; _i < 2; ++_i) \
;         __builtin_amdgcn_global_load_lds((const unsigned*)((const char*)(gbase) + (voff)[_i]), (LAS unsigned*)(lds + (bufoff) + ldsw + _i * 8192), 16, 0, 0); } while (0)
; #define PG8_LDA(dst, b, h) do { _Pragma("unroll") for (int m = 0; m < 4; ++m) _Pragma("unroll") for (int k = 0; k < 2; ++k) dst[m][k] = *(const LAS bf16x8*)(lds + PG8_SA(b, h) + aoff + m * 2048 + k * 1024); } while (0)
; #define PG8_LDB(dst, b, h) do { _Pragma("unroll") for (int n = 0; n < 2; ++n) _Pragma("unroll") for (int k = 0; k < 2; ++k) dst[n][k] = *(const LAS bf16x8*)(lds + PG8_SB(b, h) + boff + n * 2048 + k * 1024); } while (0)
; #define PG8_WAIT_V(n) asm volatile("s_waitcnt vmcnt(" #n ")" ::: "memory")
; #define PG8_BAR __builtin_amdgcn_s_barrier()
; template <class Epi>
; __device__ __forceinline__ void gemm_phase(LAS unsigned char* lds, const Gemm g, const StaticOrder& S, const Epi& E, int wave_s) {
;     ...
;         for (int t = 0; t < nt; t += 2) {
;             const bool last = (t == nt - 2);
;             const char* a1 = cA + (size_t)(t + 1) * kstep;
;             const char* a2 = last ? nA : cA + (size_t)(t + 2) * kstep; const char* b2 = last ? nB : cB + (size_t)(t + 2) * kstep;
;             const char* a3 = a2 + kstep; const char* b3 = b2 + kstep;
;             PG8_LDB(B0, 0, 0); PG8_LDB(B1, 0, 1); PG8_SCHED; PG8_LDA(At, 0, 0); PG8_STAGE(PG8_SA(1, 1), a1 + hstepA, voffA);
;             PG8_WAIT_V(8); PG8_WAIT_L(0); PG8_BAR; PG8_MMA(0, 0, At, B0); PG8_MMA(0, 1, At, B1); PG8_BAR; PG8_SCHED;
;             PG8_LDA(At, 0, 1); PG8_STAGE(PG8_SB(0, 0), b2, voffB); PG8_STAGE(PG8_SB(0, 1), b2 + hstepB, voffB); PG8_STAGE(PG8_SA(0, 0), a2, voffA);
;             PG8_WAIT_V(8); PG8_WAIT_L(0); PG8_BAR; PG8_MMA(1, 0, At, B0); PG8_MMA(1, 1, At, B1); PG8_BAR; PG8_SCHED;
;             PG8_LDB(B0, 1, 0); PG8_LDB(B1, 1, 1); PG8_SCHED; PG8_LDA(At, 1, 0); PG8_STAGE(PG8_SA(0, 1), a2 + hstepA, voffA);
;             PG8_WAIT_V(8); PG8_WAIT_L(0); PG8_BAR; PG8_MMA(0, 0, At, B0); PG8_MMA(0, 1, At, B1); PG8_BAR; PG8_SCHED;
;             PG8_LDA(At, 1, 1); PG8_STAGE(PG8_SB(1, 0), b3, voffB); PG8_STAGE(PG8_SB(1, 1), b3 + hstepB, voffB); PG8_STAGE(PG8_SA(1, 0), a3, voffA);
;             PG8_WAIT_V(8); PG8_WAIT_L(0); PG8_BAR; PG8_MMA(1, 0, At, B0); PG8_MMA(1, 1, At, B1); PG8_BAR; PG8_SCHED;
.LBB0_195:
	s_add_u32 s20, s18, 0xfff80080
	s_addc_u32 s21, s19, -1
	s_add_i32 s70, 0, 0x10000
	s_cmp_eq_u32 s67, 28
	s_cselect_b32 s23, s13, s21
	s_cselect_b32 s22, s57, s20
	v_add_u32_e32 v147, s70, v145
	s_cselect_b32 s21, s11, s66
	s_cselect_b32 s20, s64, s65
	s_add_i32 s72, 0, 0x14000
	ds_read_b128 v[140:143], v147
	ds_read_b128 v[148:151], v147 offset:1024
	ds_read_b128 v[152:155], v147 offset:2048
	ds_read_b128 v[156:159], v147 offset:3072
	v_add_u32_e32 v147, s72, v145
	ds_read_b128 v[160:163], v147
	ds_read_b128 v[164:167], v147 offset:1024
	ds_read_b128 v[168:171], v147 offset:2048
	ds_read_b128 v[172:175], v147 offset:3072
	s_add_i32 m0, s29, 0xc000
	ds_read_b128 v[176:179], v146
	ds_read_b128 v[180:183], v146 offset:1024
	ds_read_b128 v[184:187], v146 offset:2048
	ds_read_b128 v[188:191], v146 offset:3072
	ds_read_b128 v[192:195], v146 offset:4096
	ds_read_b128 v[196:199], v146 offset:5120
	ds_read_b128 v[200:203], v146 offset:6144
	ds_read_b128 v[212:215], v146 offset:7168
	global_load_lds_dwordx4 v138, s[18:19]
	s_add_i32 m0, s29, 0xe000
	s_nop 0
	global_load_lds_dwordx4 v136, s[18:19]
	s_waitcnt vmcnt(8)
	s_waitcnt lgkmcnt(0)
	s_setprio 1
	s_waitcnt lgkmcnt(0)
	v_mfma_f32_16x16x32_bf16 v[126:129], v[140:143], v[176:179], v[126:129]
	v_mfma_f32_16x16x32_bf16 v[122:125], v[152:155], v[176:179], v[122:125]
	v_mfma_f32_16x16x32_bf16 v[118:121], v[140:143], v[184:187], v[118:121]
	v_mfma_f32_16x16x32_bf16 v[110:113], v[152:155], v[184:187], v[110:113]
	s_barrier
	v_mfma_f32_16x16x32_bf16 v[102:105], v[140:143], v[192:195], v[102:105]
	v_mfma_f32_16x16x32_bf16 v[94:97], v[152:155], v[192:195], v[94:97]
	v_mfma_f32_16x16x32_bf16 v[86:89], v[140:143], v[200:203], v[86:89]
	v_mfma_f32_16x16x32_bf16 v[78:81], v[152:155], v[200:203], v[78:81]
	v_mfma_f32_16x16x32_bf16 v[126:129], v[148:151], v[180:183], v[126:129]
	v_mfma_f32_16x16x32_bf16 v[122:125], v[156:159], v[180:183], v[122:125]
	v_mfma_f32_16x16x32_bf16 v[118:121], v[148:151], v[188:191], v[118:121]
	v_mfma_f32_16x16x32_bf16 v[110:113], v[156:159], v[188:191], v[110:113]
	v_mfma_f32_16x16x32_bf16 v[102:105], v[148:151], v[196:199], v[102:105]
	v_mfma_f32_16x16x32_bf16 v[94:97], v[156:159], v[196:199], v[94:97]
	v_mfma_f32_16x16x32_bf16 v[86:89], v[148:151], v[212:215], v[86:89]
	v_mfma_f32_16x16x32_bf16 v[78:81], v[156:159], v[212:215], v[78:81]
	s_setprio 0
	s_setprio 1
	v_mfma_f32_16x16x32_bf16 v[114:117], v[160:163], v[176:179], v[114:117]
	v_mfma_f32_16x16x32_bf16 v[106:109], v[168:171], v[176:179], v[106:109]
	v_mfma_f32_16x16x32_bf16 v[98:101], v[160:163], v[184:187], v[98:101]
	v_mfma_f32_16x16x32_bf16 v[90:93], v[168:171], v[184:187], v[90:93]
	v_mfma_f32_16x16x32_bf16 v[82:85], v[160:163], v[192:195], v[82:85]
	v_mfma_f32_16x16x32_bf16 v[74:77], v[168:171], v[192:195], v[74:77]
	v_mfma_f32_16x16x32_bf16 v[70:73], v[160:163], v[200:203], v[70:73]
	v_mfma_f32_16x16x32_bf16 v[66:69], v[168:171], v[200:203], v[66:69]
	v_mfma_f32_16x16x32_bf16 v[114:117], v[164:167], v[180:183], v[114:117]
	v_mfma_f32_16x16x32_bf16 v[106:109], v[172:175], v[180:183], v[106:109]
	v_mfma_f32_16x16x32_bf16 v[98:101], v[164:167], v[188:191], v[98:101]
	v_mfma_f32_16x16x32_bf16 v[90:93], v[172:175], v[188:191], v[90:93]
	v_mfma_f32_16x16x32_bf16 v[82:85], v[164:167], v[196:199], v[82:85]
	v_mfma_f32_16x16x32_bf16 v[74:77], v[172:175], v[196:199], v[74:77]
	v_mfma_f32_16x16x32_bf16 v[70:73], v[164:167], v[212:215], v[70:73]
	v_mfma_f32_16x16x32_bf16 v[66:69], v[172:175], v[212:215], v[66:69]
	s_setprio 0
	s_barrier
	s_add_i32 s70, s70, s28
	v_lshl_add_u64 v[208:209], s[20:21], 0, v[0:1]
	s_mov_b32 m0, s70
	ds_read_b128 v[176:179], v146 offset:16384
	ds_read_b128 v[180:183], v146 offset:17408
	ds_read_b128 v[184:187], v146 offset:18432
	ds_read_b128 v[188:191], v146 offset:19456
	ds_read_b128 v[192:195], v146 offset:20480
	ds_read_b128 v[196:199], v146 offset:21504
	ds_read_b128 v[200:203], v146 offset:22528
	ds_read_b128 v[212:215], v146 offset:23552
	global_load_lds_dwordx4 v[208:209], off
	s_add_i32 m0, s70, 0x2000
	s_add_u32 s70, s20, 0x80000
	v_lshl_add_u64 v[210:211], s[20:21], 0, v[130:131]
	s_addc_u32 s71, s21, 0
	s_add_i32 s72, s72, s28
	global_load_lds_dwordx4 v[210:211], off
	s_mov_b32 m0, s72
	v_lshl_add_u64 v[226:227], s[22:23], 0, v[132:133]
	global_load_lds_dwordx4 v0, s[70:71]
	s_add_i32 m0, s72, 0x2000
	s_nop 0
	global_load_lds_dwordx4 v130, s[70:71]
	v_lshl_add_u64 v[216:217], s[22:23], 0, v[134:135]
	s_mov_b32 m0, s29
	s_nop 0
	global_load_lds_dwordx4 v[216:217], off
	s_mov_b32 m0, s30
	s_nop 0
	global_load_lds_dwordx4 v[226:227], off
	s_waitcnt vmcnt(8)
	s_waitcnt lgkmcnt(0)
	s_setprio 1
	s_waitcnt lgkmcnt(0)
	v_mfma_f32_16x16x32_bf16 v[62:65], v[140:143], v[176:179], v[62:65]
	v_mfma_f32_16x16x32_bf16 v[58:61], v[152:155], v[176:179], v[58:61]
	v_mfma_f32_16x16x32_bf16 v[54:57], v[140:143], v[184:187], v[54:57]
	v_mfma_f32_16x16x32_bf16 v[46:49], v[152:155], v[184:187], v[46:49]
	s_barrier
; #define PG8_STAGE(bufoff, gbase, voff) do { _Pragma("unroll") for (int _i = 0; _i < 2; ++_i) \
;         __builtin_amdgcn_global_load_lds((const unsigned*)((const char*)(gbase) + (voff)[_i]), (LAS unsigned*)(lds + (bufoff) + ldsw + _i * 8192), 16, 0, 0); } while (0)
; #define PG8_LDA(dst, b, h) do { _Pragma("unroll") for (int m = 0; m < 4; ++m) _Pragma("unroll") for (int k = 0; k < 2; ++k) dst[m][k] = *(const LAS bf16x8*)(lds + PG8_SA(b, h) + aoff + m * 2048 + k * 1024); } while (0)
; #define PG8_LDB(dst, b, h) do { _Pragma("unroll") for (int n = 0; n < 2; ++n) _Pragma("unroll") for (int k = 0; k < 2; ++k) dst[n][k] = *(const LAS bf16x8*)(lds + PG8_SB(b, h) + boff + n * 2048 + k * 1024); } while (0)
; #define PG8_MMA(ai, bj, At, Bt) do { __builtin_amdgcn_s_setprio(1); _Pragma("unroll") for (int m = 0; m < 4; ++m) _Pragma("unroll") for (int n = 0; n < 2; ++n) _Pragma("unroll") for (int k = 0; k < 2; ++k) \
;         acc[ai][bj][m][n] = __builtin_amdgcn_mfma_f32_16x16x32_bf16(Bt[n][k], At[m][k], acc[ai][bj][m][n], 0, 0, 0); __builtin_amdgcn_s_setprio(0); } while (0)
; #define PG8_WAIT_V(n) asm volatile("s_waitcnt vmcnt(" #n ")" ::: "memory")
; #define PG8_WAIT_L(n) asm volatile("s_waitcnt lgkmcnt(" #n ")" ::: "memory")
; #define PG8_BAR __builtin_amdgcn_s_barrier()
; #define PG8_SCHED __builtin_amdgcn_sched_barrier(0)
; template <class Epi>
; __device__ __forceinline__ void gemm_phase(LAS unsigned char* lds, const Gemm g, const StaticOrder& S, const Epi& E, int wave_s) {
;     ...
;             PG8_WAIT_V(8); PG8_WAIT_L(0); PG8_BAR; PG8_MMA(0, 0, At, B0); PG8_MMA(0, 1, At, B1); PG8_BAR; PG8_SCHED;
;             PG8_LDA(At, 0, 1); PG8_STAGE(PG8_SB(0, 0), b2, voffB); PG8_STAGE(PG8_SB(0, 1), b2 + hstepB, voffB); PG8_STAGE(PG8_SA(0, 0), a2, voffA);
;             PG8_WAIT_V(8); PG8_WAIT_L(0); PG8_BAR; PG8_MMA(1, 0, At, B0); PG8_MMA(1, 1, At, B1); PG8_BAR; PG8_SCHED;
;             PG8_LDB(B0, 1, 0); PG8_LDB(B1, 1, 1); PG8_SCHED; PG8_LDA(At, 1, 0); PG8_STAGE(PG8_SA(0, 1), a2 + hstepA, voffA);
;             PG8_WAIT_V(8); PG8_WAIT_L(0); PG8_BAR; PG8_MMA(0, 0, At, B0); PG8_MMA(0, 1, At, B1); PG8_BAR; PG8_SCHED;
;             PG8_LDA(At, 1, 1); PG8_STAGE(PG8_SB(1, 0), b3, voffB); PG8_STAGE(PG8_SB(1, 1), b3 + hstepB, voffB); PG8_STAGE(PG8_SA(1, 0), a3, voffA);
	v_mfma_f32_16x16x32_bf16 v[38:41], v[140:143], v[192:195], v[38:41]
	v_mfma_f32_16x16x32_bf16 v[30:33], v[152:155], v[192:195], v[30:33]
	v_mfma_f32_16x16x32_bf16 v[22:25], v[140:143], v[200:203], v[22:25]
	v_mfma_f32_16x16x32_bf16 v[14:17], v[152:155], v[200:203], v[14:17]
	v_mfma_f32_16x16x32_bf16 v[62:65], v[148:151], v[180:183], v[62:65]
	v_mfma_f32_16x16x32_bf16 v[58:61], v[156:159], v[180:183], v[58:61]
	v_mfma_f32_16x16x32_bf16 v[54:57], v[148:151], v[188:191], v[54:57]
	v_mfma_f32_16x16x32_bf16 v[46:49], v[156:159], v[188:191], v[46:49]
	v_mfma_f32_16x16x32_bf16 v[38:41], v[148:151], v[196:199], v[38:41]
	v_mfma_f32_16x16x32_bf16 v[30:33], v[156:159], v[196:199], v[30:33]
	v_mfma_f32_16x16x32_bf16 v[22:25], v[148:151], v[212:215], v[22:25]
	v_mfma_f32_16x16x32_bf16 v[14:17], v[156:159], v[212:215], v[14:17]
	s_setprio 0
	s_setprio 1
	v_mfma_f32_16x16x32_bf16 v[50:53], v[160:163], v[176:179], v[50:53]
	v_mfma_f32_16x16x32_bf16 v[42:45], v[168:171], v[176:179], v[42:45]
	v_mfma_f32_16x16x32_bf16 v[34:37], v[160:163], v[184:187], v[34:37]
	v_mfma_f32_16x16x32_bf16 v[26:29], v[168:171], v[184:187], v[26:29]
	v_mfma_f32_16x16x32_bf16 v[18:21], v[160:163], v[192:195], v[18:21]
	v_mfma_f32_16x16x32_bf16 v[10:13], v[168:171], v[192:195], v[10:13]
	v_mfma_f32_16x16x32_bf16 v[6:9], v[160:163], v[200:203], v[6:9]
	v_mfma_f32_16x16x32_bf16 v[2:5], v[168:171], v[200:203], v[2:5]
	v_mfma_f32_16x16x32_bf16 v[50:53], v[164:167], v[180:183], v[50:53]
	v_mfma_f32_16x16x32_bf16 v[42:45], v[172:175], v[180:183], v[42:45]
	v_mfma_f32_16x16x32_bf16 v[34:37], v[164:167], v[188:191], v[34:37]
	v_mfma_f32_16x16x32_bf16 v[26:29], v[172:175], v[188:191], v[26:29]
	v_mfma_f32_16x16x32_bf16 v[18:21], v[164:167], v[196:199], v[18:21]
	v_mfma_f32_16x16x32_bf16 v[10:13], v[172:175], v[196:199], v[10:13]
	v_mfma_f32_16x16x32_bf16 v[6:9], v[164:167], v[212:215], v[6:9]
	v_mfma_f32_16x16x32_bf16 v[2:5], v[172:175], v[212:215], v[2:5]
	s_setprio 0
	s_barrier
	s_add_i32 s70, 0, 0x18000
	v_add_u32_e32 v147, s70, v145
	s_add_i32 s71, 0, 0x1c000
	ds_read_b128 v[140:143], v147
	ds_read_b128 v[148:151], v147 offset:1024
	ds_read_b128 v[152:155], v147 offset:2048
	ds_read_b128 v[156:159], v147 offset:3072
	v_add_u32_e32 v147, s71, v145
	ds_read_b128 v[160:163], v147
	ds_read_b128 v[164:167], v147 offset:1024
	ds_read_b128 v[168:171], v147 offset:2048
	ds_read_b128 v[172:175], v147 offset:3072
	s_add_u32 s22, s22, 0x80000
	s_addc_u32 s23, s23, 0
	s_mov_b32 m0, s31
	ds_read_b128 v[176:179], v146 offset:32768
	ds_read_b128 v[180:183], v146 offset:33792
	ds_read_b128 v[184:187], v146 offset:34816
	ds_read_b128 v[188:191], v146 offset:35840
	ds_read_b128 v[192:195], v146 offset:36864
	ds_read_b128 v[196:199], v146 offset:37888
	ds_read_b128 v[200:203], v146 offset:38912
	ds_read_b128 v[212:215], v146 offset:39936
	global_load_lds_dwordx4 v134, s[22:23]
	v_lshl_add_u64 v[228:229], s[22:23], 0, v[132:133]
	s_mov_b32 m0, s34
	s_nop 0
	global_load_lds_dwordx4 v[228:229], off
	s_waitcnt vmcnt(8)
	s_waitcnt lgkmcnt(0)
	s_setprio 1
	s_waitcnt lgkmcnt(0)
	v_mfma_f32_16x16x32_bf16 v[126:129], v[140:143], v[176:179], v[126:129]
	v_mfma_f32_16x16x32_bf16 v[122:125], v[152:155], v[176:179], v[122:125]
	v_mfma_f32_16x16x32_bf16 v[118:121], v[140:143], v[184:187], v[118:121]
	v_mfma_f32_16x16x32_bf16 v[110:113], v[152:155], v[184:187], v[110:113]
	s_barrier
	v_mfma_f32_16x16x32_bf16 v[102:105], v[140:143], v[192:195], v[102:105]
	v_mfma_f32_16x16x32_bf16 v[94:97], v[152:155], v[192:195], v[94:97]
	v_mfma_f32_16x16x32_bf16 v[86:89], v[140:143], v[200:203], v[86:89]
	v_mfma_f32_16x16x32_bf16 v[78:81], v[152:155], v[200:203], v[78:81]
	v_mfma_f32_16x16x32_bf16 v[126:129], v[148:151], v[180:183], v[126:129]
	v_mfma_f32_16x16x32_bf16 v[122:125], v[156:159], v[180:183], v[122:125]
	v_mfma_f32_16x16x32_bf16 v[118:121], v[148:151], v[188:191], v[118:121]
	v_mfma_f32_16x16x32_bf16 v[110:113], v[156:159], v[188:191], v[110:113]
	v_mfma_f32_16x16x32_bf16 v[102:105], v[148:151], v[196:199], v[102:105]
	v_mfma_f32_16x16x32_bf16 v[94:97], v[156:159], v[196:199], v[94:97]
	v_mfma_f32_16x16x32_bf16 v[86:89], v[148:151], v[212:215], v[86:89]
	v_mfma_f32_16x16x32_bf16 v[78:81], v[156:159], v[212:215], v[78:81]
	s_setprio 0
	s_setprio 1
	v_mfma_f32_16x16x32_bf16 v[114:117], v[160:163], v[176:179], v[114:117]
	v_mfma_f32_16x16x32_bf16 v[106:109], v[168:171], v[176:179], v[106:109]
	v_mfma_f32_16x16x32_bf16 v[98:101], v[160:163], v[184:187], v[98:101]
	v_mfma_f32_16x16x32_bf16 v[90:93], v[168:171], v[184:187], v[90:93]
	v_mfma_f32_16x16x32_bf16 v[82:85], v[160:163], v[192:195], v[82:85]
	v_mfma_f32_16x16x32_bf16 v[74:77], v[168:171], v[192:195], v[74:77]
	v_mfma_f32_16x16x32_bf16 v[70:73], v[160:163], v[200:203], v[70:73]
	v_mfma_f32_16x16x32_bf16 v[66:69], v[168:171], v[200:203], v[66:69]
	v_mfma_f32_16x16x32_bf16 v[114:117], v[164:167], v[180:183], v[114:117]
	v_mfma_f32_16x16x32_bf16 v[106:109], v[172:175], v[180:183], v[106:109]
	v_mfma_f32_16x16x32_bf16 v[98:101], v[164:167], v[188:191], v[98:101]
	v_mfma_f32_16x16x32_bf16 v[90:93], v[172:175], v[188:191], v[90:93]
	v_mfma_f32_16x16x32_bf16 v[82:85], v[164:167], v[196:199], v[82:85]
	v_mfma_f32_16x16x32_bf16 v[74:77], v[172:175], v[196:199], v[74:77]
	v_mfma_f32_16x16x32_bf16 v[70:73], v[164:167], v[212:215], v[70:73]
	v_mfma_f32_16x16x32_bf16 v[66:69], v[172:175], v[212:215], v[66:69]
	s_setprio 0
	s_barrier
; #define PG8_STAGE(bufoff, gbase, voff) do { _Pragma("unroll") for (int _i = 0; _i < 2; ++_i) \
;         __builtin_amdgcn_global_load_lds((const unsigned*)((const char*)(gbase) + (voff)[_i]), (LAS unsigned*)(lds + (bufoff) + ldsw + _i * 8192), 16, 0, 0); } while (0)
; #define PG8_LDA(dst, b, h) do { _Pragma("unroll") for (int m = 0; m < 4; ++m) _Pragma("unroll") for (int k = 0; k < 2; ++k) dst[m][k] = *(const LAS bf16x8*)(lds + PG8_SA(b, h) + aoff + m * 2048 + k * 1024); } while (0)
; #define PG8_MMA(ai, bj, At, Bt) do { __builtin_amdgcn_s_setprio(1); _Pragma("unroll") for (int m = 0; m < 4; ++m) _Pragma("unroll") for (int n = 0; n < 2; ++n) _Pragma("unroll") for (int k = 0; k < 2; ++k) \
;         acc[ai][bj][m][n] = __builtin_amdgcn_mfma_f32_16x16x32_bf16(Bt[n][k], At[m][k], acc[ai][bj][m][n], 0, 0, 0); __builtin_amdgcn_s_setprio(0); } while (0)
; #define PG8_WAIT_V(n) asm volatile("s_waitcnt vmcnt(" #n ")" ::: "memory")
; #define PG8_WAIT_L(n) asm volatile("s_waitcnt lgkmcnt(" #n ")" ::: "memory")
; #define PG8_BAR __builtin_amdgcn_s_barrier()
; #define PG8_SCHED __builtin_amdgcn_sched_barrier(0)
; template <class Epi>
; __device__ __forceinline__ void gemm_phase(LAS unsigned char* lds, const Gemm g, const StaticOrder& S, const Epi& E, int wave_s) {
;     ...
;             PG8_LDA(At, 1, 1); PG8_STAGE(PG8_SB(1, 0), b3, voffB); PG8_STAGE(PG8_SB(1, 1), b3 + hstepB, voffB); PG8_STAGE(PG8_SA(1, 0), a3, voffA);
;             PG8_WAIT_V(8); PG8_WAIT_L(0); PG8_BAR; PG8_MMA(1, 0, At, B0); PG8_MMA(1, 1, At, B1); PG8_BAR; PG8_SCHED;
;         }
;         if (wr == 0) PG8_BAR;
	s_add_i32 s22, s70, s28
	v_lshl_add_u64 v[208:209], v[208:209], 0, s[42:43]
	s_mov_b32 m0, s22
	ds_read_b128 v[176:179], v146 offset:49152
	ds_read_b128 v[180:183], v146 offset:50176
	ds_read_b128 v[184:187], v146 offset:51200
	ds_read_b128 v[188:191], v146 offset:52224
	ds_read_b128 v[192:195], v146 offset:53248
	ds_read_b128 v[196:199], v146 offset:54272
	ds_read_b128 v[200:203], v146 offset:55296
	ds_read_b128 v[212:215], v146 offset:56320
	global_load_lds_dwordx4 v[208:209], off
	s_add_i32 m0, s22, 0x2000
	s_add_u32 s20, s20, 0x80080
	v_lshl_add_u64 v[208:209], v[210:211], 0, s[42:43]
	s_addc_u32 s21, s21, 0
	s_add_i32 s22, s71, s28
	global_load_lds_dwordx4 v[208:209], off
	s_mov_b32 m0, s22
	s_nop 0
	global_load_lds_dwordx4 v0, s[20:21]
	s_add_i32 m0, s22, 0x2000
	s_nop 0
	global_load_lds_dwordx4 v130, s[20:21]
	v_lshl_add_u64 v[208:209], v[216:217], 0, s[42:43]
	s_mov_b32 m0, s38
	s_nop 0
	global_load_lds_dwordx4 v[208:209], off
	v_lshl_add_u64 v[208:209], v[226:227], 0, s[42:43]
	s_mov_b32 m0, s39
	s_nop 0
	global_load_lds_dwordx4 v[208:209], off
	s_waitcnt vmcnt(8)
	s_waitcnt lgkmcnt(0)
	s_setprio 1
	s_waitcnt lgkmcnt(0)
	v_mfma_f32_16x16x32_bf16 v[62:65], v[140:143], v[176:179], v[62:65]
	v_mfma_f32_16x16x32_bf16 v[58:61], v[152:155], v[176:179], v[58:61]
	v_mfma_f32_16x16x32_bf16 v[54:57], v[140:143], v[184:187], v[54:57]
	v_mfma_f32_16x16x32_bf16 v[46:49], v[152:155], v[184:187], v[46:49]
	s_barrier
	v_mfma_f32_16x16x32_bf16 v[38:41], v[140:143], v[192:195], v[38:41]
	v_mfma_f32_16x16x32_bf16 v[30:33], v[152:155], v[192:195], v[30:33]
	v_mfma_f32_16x16x32_bf16 v[22:25], v[140:143], v[200:203], v[22:25]
	v_mfma_f32_16x16x32_bf16 v[14:17], v[152:155], v[200:203], v[14:17]
	v_mfma_f32_16x16x32_bf16 v[62:65], v[148:151], v[180:183], v[62:65]
	v_mfma_f32_16x16x32_bf16 v[58:61], v[156:159], v[180:183], v[58:61]
	v_mfma_f32_16x16x32_bf16 v[54:57], v[148:151], v[188:191], v[54:57]
	v_mfma_f32_16x16x32_bf16 v[46:49], v[156:159], v[188:191], v[46:49]
	v_mfma_f32_16x16x32_bf16 v[38:41], v[148:151], v[196:199], v[38:41]
	v_mfma_f32_16x16x32_bf16 v[30:33], v[156:159], v[196:199], v[30:33]
	v_mfma_f32_16x16x32_bf16 v[22:25], v[148:151], v[212:215], v[22:25]
	v_mfma_f32_16x16x32_bf16 v[14:17], v[156:159], v[212:215], v[14:17]
	s_setprio 0
	s_setprio 1
	v_mfma_f32_16x16x32_bf16 v[50:53], v[160:163], v[176:179], v[50:53]
	v_mfma_f32_16x16x32_bf16 v[42:45], v[168:171], v[176:179], v[42:45]
	v_mfma_f32_16x16x32_bf16 v[34:37], v[160:163], v[184:187], v[34:37]
	v_mfma_f32_16x16x32_bf16 v[26:29], v[168:171], v[184:187], v[26:29]
	v_mfma_f32_16x16x32_bf16 v[18:21], v[160:163], v[192:195], v[18:21]
	v_mfma_f32_16x16x32_bf16 v[10:13], v[168:171], v[192:195], v[10:13]
	v_mfma_f32_16x16x32_bf16 v[6:9], v[160:163], v[200:203], v[6:9]
	v_mfma_f32_16x16x32_bf16 v[2:5], v[168:171], v[200:203], v[2:5]
	v_mfma_f32_16x16x32_bf16 v[50:53], v[164:167], v[180:183], v[50:53]
	v_mfma_f32_16x16x32_bf16 v[42:45], v[172:175], v[180:183], v[42:45]
	v_mfma_f32_16x16x32_bf16 v[34:37], v[164:167], v[188:191], v[34:37]
	v_mfma_f32_16x16x32_bf16 v[26:29], v[172:175], v[188:191], v[26:29]
	v_mfma_f32_16x16x32_bf16 v[18:21], v[164:167], v[196:199], v[18:21]
	v_mfma_f32_16x16x32_bf16 v[10:13], v[172:175], v[196:199], v[10:13]
	v_mfma_f32_16x16x32_bf16 v[6:9], v[164:167], v[212:215], v[6:9]
	v_mfma_f32_16x16x32_bf16 v[2:5], v[172:175], v[212:215], v[2:5]
	s_setprio 0
	s_barrier
	s_add_i32 s67, s67, 2
	s_add_u32 s65, s65, 0x100
	s_addc_u32 s66, s66, 0
	s_add_u32 s18, s18, 0x100
	s_addc_u32 s19, s19, 0
	s_cmp_gt_u32 s67, 29
	s_cbranch_scc0 .LBB0_195
	s_and_b64 vcc, exec, s[8:9]
	s_cbranch_vccz .LBB0_198
	s_barrier

; #define PG8_STAGE(bufoff, gbase, voff) do { _Pragma("unroll") for (int _i = 0; _i < 2; ++_i) \
;         __builtin_amdgcn_global_load_lds((const unsigned*)((const char*)(gbase) + (voff)[_i]), (LAS unsigned*)(lds + (bufoff) + ldsw + _i * 8192), 16, 0, 0); } while (0)
; #define PG8_LDA(dst, b, h) do { _Pragma("unroll") for (int m = 0; m < 4; ++m) _Pragma("unroll") for (int k = 0; k < 2; ++k) dst[m][k] = *(const LAS bf16x8*)(lds + PG8_SA(b, h) + aoff + m * 2048 + k * 1024); } while (0)
; #define PG8_LDB(dst, b, h) do { _Pragma("unroll") for (int n = 0; n < 2; ++n) _Pragma("unroll") for (int k = 0; k < 2; ++k) dst[n][k] = *(const LAS bf16x8*)(lds + PG8_SB(b, h) + boff + n * 2048 + k * 1024); } while (0)
; #define PG8_MMA(ai, bj, At, Bt) do { __builtin_amdgcn_s_setprio(1); _Pragma("unroll") for (int m = 0; m < 4; ++m) _Pragma("unroll") for (int n = 0; n < 2; ++n) _Pragma("unroll") for (int k = 0; k < 2; ++k) \
;         acc[ai][bj][m][n] = __builtin_amdgcn_mfma_f32_16x16x32_bf16(Bt[n][k], At[m][k], acc[ai][bj][m][n], 0, 0, 0); __builtin_amdgcn_s_setprio(0); } while (0)
; #define PG8_WAIT_V(n) asm volatile("s_waitcnt vmcnt(" #n ")" ::: "memory")
; #define PG8_WAIT_L(n) asm volatile("s_waitcnt lgkmcnt(" #n ")" ::: "memory")
; #define PG8_BAR __builtin_amdgcn_s_barrier()
; #define PG8_SCHED __builtin_amdgcn_sched_barrier(0)
; template <class Epi>
; __device__ __forceinline__ void gemm_phase(LAS unsigned char* lds, const Gemm g, const StaticOrder& S, const Epi& E, int wave_s) {
;     ...
;         for (int t = 0; t < nt; t += 2) {
;             const bool last = (t == nt - 2);
;             const char* a1 = cA + (size_t)(t + 1) * kstep;
;             const char* a2 = last ? nA : cA + (size_t)(t + 2) * kstep; const char* b2 = last ? nB : cB + (size_t)(t + 2) * kstep;
;             const char* a3 = a2 + kstep; const char* b3 = b2 + kstep;
;             PG8_LDB(B0, 0, 0); PG8_LDB(B1, 0, 1); PG8_SCHED; PG8_LDA(At, 0, 0); PG8_STAGE(PG8_SA(1, 1), a1 + hstepA, voffA);
;             PG8_WAIT_V(8); PG8_WAIT_L(0); PG8_BAR; PG8_MMA(0, 0, At, B0); PG8_MMA(0, 1, At, B1); PG8_BAR; PG8_SCHED;
;             PG8_LDA(At, 0, 1); PG8_STAGE(PG8_SB(0, 0), b2, voffB); PG8_STAGE(PG8_SB(0, 1), b2 + hstepB, voffB); PG8_STAGE(PG8_SA(0, 0), a2, voffA);
;             PG8_WAIT_V(8); PG8_WAIT_L(0); PG8_BAR; PG8_MMA(1, 0, At, B0); PG8_MMA(1, 1, At, B1); PG8_BAR; PG8_SCHED;
.LBB0_309:
	s_add_i32 s70, 0, 0x10000
	s_add_i32 s66, 0, 0x14000
	v_add_u32_e32 v0, s70, v151
	v_add_u32_e32 v10, s66, v151
	ds_read_b128 v[12:15], v0
	ds_read_b128 v[16:19], v0 offset:1024
	ds_read_b128 v[20:23], v0 offset:2048
	ds_read_b128 v[24:27], v0 offset:3072
	ds_read_b128 v[28:31], v10
	ds_read_b128 v[32:35], v10 offset:1024
	ds_read_b128 v[36:39], v10 offset:2048
	ds_read_b128 v[40:43], v10 offset:3072
	s_add_u32 s4, s22, 0x110080
	s_addc_u32 s5, s23, 0
	s_add_i32 s73, s31, 0xc000
	s_mov_b32 m0, s73
	ds_read_b128 v[2:5], v155
	ds_read_b128 v[6:9], v155 offset:1024
	ds_read_b128 v[44:47], v155 offset:2048
	ds_read_b128 v[48:51], v155 offset:3072
	ds_read_b128 v[52:55], v155 offset:4096
	ds_read_b128 v[56:59], v155 offset:5120
	ds_read_b128 v[60:63], v155 offset:6144
	ds_read_b128 v[64:67], v155 offset:7168
	global_load_lds_dwordx4 v136, s[4:5]
	v_lshl_add_u64 v[68:69], s[4:5], 0, v[132:133]
	s_add_i32 s4, s31, 0xe000
	s_mov_b32 m0, s4
	s_nop 0
	global_load_lds_dwordx4 v[68:69], off
	s_waitcnt vmcnt(8)
	s_waitcnt lgkmcnt(0)
	s_setprio 1
	s_waitcnt lgkmcnt(0)
	v_mfma_f32_16x16x32_bf16 v[68:71], v[12:15], v[2:5], 0
	v_mfma_f32_16x16x32_bf16 v[72:75], v[20:23], v[2:5], 0
	v_mfma_f32_16x16x32_bf16 v[76:79], v[12:15], v[44:47], 0
	v_mfma_f32_16x16x32_bf16 v[80:83], v[20:23], v[44:47], 0
	s_barrier
	v_mfma_f32_16x16x32_bf16 v[84:87], v[12:15], v[52:55], 0
	v_mfma_f32_16x16x32_bf16 v[88:91], v[20:23], v[52:55], 0
	v_mfma_f32_16x16x32_bf16 v[92:95], v[12:15], v[60:63], 0
	v_mfma_f32_16x16x32_bf16 v[96:99], v[20:23], v[60:63], 0
	v_mfma_f32_16x16x32_bf16 v[68:71], v[16:19], v[6:9], v[68:71]
	v_mfma_f32_16x16x32_bf16 v[72:75], v[24:27], v[6:9], v[72:75]
	v_mfma_f32_16x16x32_bf16 v[76:79], v[16:19], v[48:51], v[76:79]
	v_mfma_f32_16x16x32_bf16 v[80:83], v[24:27], v[48:51], v[80:83]
	v_mfma_f32_16x16x32_bf16 v[84:87], v[16:19], v[56:59], v[84:87]
	v_mfma_f32_16x16x32_bf16 v[88:91], v[24:27], v[56:59], v[88:91]
	v_mfma_f32_16x16x32_bf16 v[92:95], v[16:19], v[64:67], v[92:95]
	v_mfma_f32_16x16x32_bf16 v[96:99], v[24:27], v[64:67], v[96:99]
	s_setprio 0
	s_setprio 1
	v_mfma_f32_16x16x32_bf16 v[100:103], v[28:31], v[2:5], 0
	v_mfma_f32_16x16x32_bf16 v[2:5], v[36:39], v[2:5], 0
	v_mfma_f32_16x16x32_bf16 v[104:107], v[40:43], v[6:9], v[2:5]
	v_mfma_f32_16x16x32_bf16 v[2:5], v[28:31], v[44:47], 0
	v_mfma_f32_16x16x32_bf16 v[108:111], v[32:35], v[48:51], v[2:5]
	v_mfma_f32_16x16x32_bf16 v[2:5], v[36:39], v[44:47], 0
	v_mfma_f32_16x16x32_bf16 v[44:47], v[40:43], v[48:51], v[2:5]
	v_mfma_f32_16x16x32_bf16 v[2:5], v[28:31], v[52:55], 0
	v_mfma_f32_16x16x32_bf16 v[48:51], v[32:35], v[56:59], v[2:5]
	v_mfma_f32_16x16x32_bf16 v[2:5], v[36:39], v[52:55], 0
	v_mfma_f32_16x16x32_bf16 v[52:55], v[40:43], v[56:59], v[2:5]
	v_mfma_f32_16x16x32_bf16 v[2:5], v[28:31], v[60:63], 0
	v_mfma_f32_16x16x32_bf16 v[56:59], v[32:35], v[64:67], v[2:5]
	v_mfma_f32_16x16x32_bf16 v[2:5], v[36:39], v[60:63], 0
	v_mfma_f32_16x16x32_bf16 v[100:103], v[32:35], v[6:9], v[100:103]
	v_mfma_f32_16x16x32_bf16 v[60:63], v[40:43], v[64:67], v[2:5]
	s_setprio 0
	s_barrier
	s_nop 3
	v_lshl_add_u64 v[2:3], s[24:25], 0, v[134:135]
	s_mov_b64 s[82:83], 0x100
	s_add_i32 s70, s70, s30
	v_lshl_add_u64 v[4:5], v[2:3], 0, s[82:83]
	s_mov_b32 m0, s70
	s_add_i32 s5, s70, 0x2000
	ds_read_b128 v[64:67], v155 offset:16384
	ds_read_b128 v[112:115], v155 offset:17408
	ds_read_b128 v[116:119], v155 offset:18432
	ds_read_b128 v[120:123], v155 offset:19456
	ds_read_b128 v[124:127], v155 offset:20480
	ds_read_b128 v[138:141], v155 offset:21504
	ds_read_b128 v[142:145], v155 offset:22528
	ds_read_b128 v[146:149], v155 offset:23552
	global_load_lds_dwordx4 v[4:5], off
	v_lshl_add_u64 v[4:5], s[24:25], 0, v[130:131]
	s_add_u32 s78, s24, 0x18100
	v_lshl_add_u64 v[6:7], v[4:5], 0, s[82:83]
	s_mov_b32 m0, s5
	s_addc_u32 s79, s25, 0
	s_add_i32 s66, s66, s30
	global_load_lds_dwordx4 v[6:7], off
	s_mov_b32 m0, s66
	s_add_i32 s67, s66, 0x2000
	global_load_lds_dwordx4 v134, s[78:79]
	s_mov_b32 m0, s67
	s_nop 0
	global_load_lds_dwordx4 v130, s[78:79]
	v_lshl_add_u64 v[6:7], s[22:23], 0, v[136:137]
	v_lshl_add_u64 v[8:9], v[6:7], 0, s[82:83]
	s_mov_b32 m0, s31
	s_nop 0
	global_load_lds_dwordx4 v[8:9], off
	v_lshl_add_u64 v[8:9], s[22:23], 0, v[132:133]
	v_lshl_add_u64 v[128:129], v[8:9], 0, s[82:83]
	s_mov_b32 m0, s34
	s_nop 0
	global_load_lds_dwordx4 v[128:129], off
	s_waitcnt vmcnt(8)
	s_waitcnt lgkmcnt(0)
	s_setprio 1
	s_waitcnt lgkmcnt(0)
	v_mfma_f32_16x16x32_bf16 v[156:159], v[12:15], v[64:67], 0
	v_mfma_f32_16x16x32_bf16 v[164:167], v[12:15], v[116:119], 0
	v_mfma_f32_16x16x32_bf16 v[172:175], v[12:15], v[124:127], 0
	v_mfma_f32_16x16x32_bf16 v[12:15], v[12:15], v[142:145], 0
	s_barrier
; #define PG8_STAGE(bufoff, gbase, voff) do { _Pragma("unroll") for (int _i = 0; _i < 2; ++_i) \
;         __builtin_amdgcn_global_load_lds((const unsigned*)((const char*)(gbase) + (voff)[_i]), (LAS unsigned*)(lds + (bufoff) + ldsw + _i * 8192), 16, 0, 0); } while (0)
; #define PG8_LDA(dst, b, h) do { _Pragma("unroll") for (int m = 0; m < 4; ++m) _Pragma("unroll") for (int k = 0; k < 2; ++k) dst[m][k] = *(const LAS bf16x8*)(lds + PG8_SA(b, h) + aoff + m * 2048 + k * 1024); } while (0)
; #define PG8_LDB(dst, b, h) do { _Pragma("unroll") for (int n = 0; n < 2; ++n) _Pragma("unroll") for (int k = 0; k < 2; ++k) dst[n][k] = *(const LAS bf16x8*)(lds + PG8_SB(b, h) + boff + n * 2048 + k * 1024); } while (0)
; #define PG8_MMA(ai, bj, At, Bt) do { __builtin_amdgcn_s_setprio(1); _Pragma("unroll") for (int m = 0; m < 4; ++m) _Pragma("unroll") for (int n = 0; n < 2; ++n) _Pragma("unroll") for (int k = 0; k < 2; ++k) \
;         acc[ai][bj][m][n] = __builtin_amdgcn_mfma_f32_16x16x32_bf16(Bt[n][k], At[m][k], acc[ai][bj][m][n], 0, 0, 0); __builtin_amdgcn_s_setprio(0); } while (0)
; #define PG8_WAIT_V(n) asm volatile("s_waitcnt vmcnt(" #n ")" ::: "memory")
; #define PG8_WAIT_L(n) asm volatile("s_waitcnt lgkmcnt(" #n ")" ::: "memory")
; #define PG8_BAR __builtin_amdgcn_s_barrier()
; #define PG8_SCHED __builtin_amdgcn_sched_barrier(0)
; template <class Epi>
; __device__ __forceinline__ void gemm_phase(LAS unsigned char* lds, const Gemm g, const StaticOrder& S, const Epi& E, int wave_s) {
;     ...
;             PG8_WAIT_V(8); PG8_WAIT_L(0); PG8_BAR; PG8_MMA(0, 0, At, B0); PG8_MMA(0, 1, At, B1); PG8_BAR; PG8_SCHED;
;             PG8_LDA(At, 0, 1); PG8_STAGE(PG8_SB(0, 0), b2, voffB); PG8_STAGE(PG8_SB(0, 1), b2 + hstepB, voffB); PG8_STAGE(PG8_SA(0, 0), a2, voffA);
;             PG8_WAIT_V(8); PG8_WAIT_L(0); PG8_BAR; PG8_MMA(1, 0, At, B0); PG8_MMA(1, 1, At, B1); PG8_BAR; PG8_SCHED;
;             PG8_LDB(B0, 1, 0); PG8_LDB(B1, 1, 1); PG8_SCHED; PG8_LDA(At, 1, 0); PG8_STAGE(PG8_SA(0, 1), a2 + hstepA, voffA);
;             PG8_WAIT_V(8); PG8_WAIT_L(0); PG8_BAR; PG8_MMA(0, 0, At, B0); PG8_MMA(0, 1, At, B1); PG8_BAR; PG8_SCHED;
	v_mfma_f32_16x16x32_bf16 v[156:159], v[16:19], v[112:115], v[156:159]
	v_mfma_f32_16x16x32_bf16 v[160:163], v[20:23], v[64:67], 0
	v_mfma_f32_16x16x32_bf16 v[164:167], v[16:19], v[120:123], v[164:167]
	v_mfma_f32_16x16x32_bf16 v[168:171], v[20:23], v[116:119], 0
	v_mfma_f32_16x16x32_bf16 v[172:175], v[16:19], v[138:141], v[172:175]
	v_mfma_f32_16x16x32_bf16 v[176:179], v[20:23], v[124:127], 0
	v_mfma_f32_16x16x32_bf16 v[14:17], v[16:19], v[146:149], v[12:15]
	v_mfma_f32_16x16x32_bf16 v[18:21], v[20:23], v[142:145], 0
	v_mfma_f32_16x16x32_bf16 v[18:21], v[24:27], v[146:149], v[18:21]
	v_mfma_f32_16x16x32_bf16 v[160:163], v[24:27], v[112:115], v[160:163]
	v_mfma_f32_16x16x32_bf16 v[168:171], v[24:27], v[120:123], v[168:171]
	v_mfma_f32_16x16x32_bf16 v[176:179], v[24:27], v[138:141], v[176:179]
	s_setprio 0
	s_setprio 1
	v_mfma_f32_16x16x32_bf16 v[22:25], v[28:31], v[64:67], 0
	v_mfma_f32_16x16x32_bf16 v[64:67], v[36:39], v[64:67], 0
	v_mfma_f32_16x16x32_bf16 v[22:25], v[32:35], v[112:115], v[22:25]
	v_mfma_f32_16x16x32_bf16 v[64:67], v[40:43], v[112:115], v[64:67]
	v_mfma_f32_16x16x32_bf16 v[112:115], v[28:31], v[116:119], 0
	v_mfma_f32_16x16x32_bf16 v[116:119], v[36:39], v[116:119], 0
	v_mfma_f32_16x16x32_bf16 v[112:115], v[32:35], v[120:123], v[112:115]
	v_mfma_f32_16x16x32_bf16 v[116:119], v[40:43], v[120:123], v[116:119]
	v_mfma_f32_16x16x32_bf16 v[120:123], v[28:31], v[124:127], 0
	v_mfma_f32_16x16x32_bf16 v[26:29], v[28:31], v[142:145], 0
	v_mfma_f32_16x16x32_bf16 v[120:123], v[32:35], v[138:141], v[120:123]
	v_mfma_f32_16x16x32_bf16 v[124:127], v[36:39], v[124:127], 0
	v_mfma_f32_16x16x32_bf16 v[26:29], v[32:35], v[146:149], v[26:29]
	v_mfma_f32_16x16x32_bf16 v[30:33], v[36:39], v[142:145], 0
	v_mfma_f32_16x16x32_bf16 v[124:127], v[40:43], v[138:141], v[124:127]
	v_mfma_f32_16x16x32_bf16 v[30:33], v[40:43], v[146:149], v[30:33]
	s_setprio 0
	s_barrier
	s_add_i32 s71, 0, 0x18000
	s_add_i32 s72, 0, 0x1c000
	v_add_u32_e32 v11, s71, v151
	v_add_u32_e32 v12, s72, v151
	ds_read_b128 v[34:37], v11
	ds_read_b128 v[38:41], v11 offset:1024
	ds_read_b128 v[138:141], v11 offset:2048
	ds_read_b128 v[142:145], v11 offset:3072
	ds_read_b128 v[146:149], v12
	ds_read_b128 v[180:183], v12 offset:1024
	ds_read_b128 v[184:187], v12 offset:2048
	ds_read_b128 v[188:191], v12 offset:3072
	s_add_u32 s78, s22, 0x110100
	s_addc_u32 s79, s23, 0
	s_mov_b32 m0, s35
	ds_read_b128 v[192:195], v155 offset:32768
	ds_read_b128 v[196:199], v155 offset:33792
	ds_read_b128 v[200:203], v155 offset:34816
	ds_read_b128 v[212:215], v155 offset:35840
	ds_read_b128 v[226:229], v155 offset:36864
	ds_read_b128 v[230:233], v155 offset:37888
	ds_read_b128 v[234:237], v155 offset:38912
	ds_read_b128 v[238:241], v155 offset:39936
	global_load_lds_dwordx4 v136, s[78:79]
	v_lshl_add_u64 v[42:43], s[78:79], 0, v[132:133]
	s_mov_b32 m0, s37
	s_nop 0
	global_load_lds_dwordx4 v[42:43], off
	s_waitcnt vmcnt(8)
	s_waitcnt lgkmcnt(0)
	s_setprio 1
	s_waitcnt lgkmcnt(0)
	v_mfma_f32_16x16x32_bf16 v[68:71], v[34:37], v[192:195], v[68:71]
	v_mfma_f32_16x16x32_bf16 v[72:75], v[138:141], v[192:195], v[72:75]
	v_mfma_f32_16x16x32_bf16 v[76:79], v[34:37], v[200:203], v[76:79]
	v_mfma_f32_16x16x32_bf16 v[80:83], v[138:141], v[200:203], v[80:83]
	s_barrier
	v_mfma_f32_16x16x32_bf16 v[84:87], v[34:37], v[226:229], v[84:87]
	v_mfma_f32_16x16x32_bf16 v[88:91], v[138:141], v[226:229], v[88:91]
	v_mfma_f32_16x16x32_bf16 v[92:95], v[34:37], v[234:237], v[92:95]
	v_mfma_f32_16x16x32_bf16 v[96:99], v[138:141], v[234:237], v[96:99]
	v_mfma_f32_16x16x32_bf16 v[68:71], v[38:41], v[196:199], v[68:71]
	v_mfma_f32_16x16x32_bf16 v[72:75], v[142:145], v[196:199], v[72:75]
	v_mfma_f32_16x16x32_bf16 v[76:79], v[38:41], v[212:215], v[76:79]
	v_mfma_f32_16x16x32_bf16 v[80:83], v[142:145], v[212:215], v[80:83]
	v_mfma_f32_16x16x32_bf16 v[84:87], v[38:41], v[230:233], v[84:87]
	v_mfma_f32_16x16x32_bf16 v[88:91], v[142:145], v[230:233], v[88:91]
	v_mfma_f32_16x16x32_bf16 v[92:95], v[38:41], v[238:241], v[92:95]
	v_mfma_f32_16x16x32_bf16 v[96:99], v[142:145], v[238:241], v[96:99]
	s_setprio 0
	s_setprio 1
	v_mfma_f32_16x16x32_bf16 v[100:103], v[146:149], v[192:195], v[100:103]
	v_mfma_f32_16x16x32_bf16 v[104:107], v[184:187], v[192:195], v[104:107]
	v_mfma_f32_16x16x32_bf16 v[108:111], v[146:149], v[200:203], v[108:111]
	v_mfma_f32_16x16x32_bf16 v[42:45], v[184:187], v[200:203], v[44:47]
	v_mfma_f32_16x16x32_bf16 v[46:49], v[146:149], v[226:229], v[48:51]
	v_mfma_f32_16x16x32_bf16 v[50:53], v[184:187], v[226:229], v[52:55]
	v_mfma_f32_16x16x32_bf16 v[54:57], v[146:149], v[234:237], v[56:59]
	v_mfma_f32_16x16x32_bf16 v[58:61], v[184:187], v[234:237], v[60:63]
	v_mfma_f32_16x16x32_bf16 v[100:103], v[180:183], v[196:199], v[100:103]
	v_mfma_f32_16x16x32_bf16 v[104:107], v[188:191], v[196:199], v[104:107]
	v_mfma_f32_16x16x32_bf16 v[108:111], v[180:183], v[212:215], v[108:111]
	v_mfma_f32_16x16x32_bf16 v[42:45], v[188:191], v[212:215], v[42:45]
	v_mfma_f32_16x16x32_bf16 v[46:49], v[180:183], v[230:233], v[46:49]
	v_mfma_f32_16x16x32_bf16 v[50:53], v[188:191], v[230:233], v[50:53]
	v_mfma_f32_16x16x32_bf16 v[54:57], v[180:183], v[238:241], v[54:57]
	v_mfma_f32_16x16x32_bf16 v[58:61], v[188:191], v[238:241], v[58:61]
	s_setprio 0
	s_barrier
; #define PG8_STAGE(bufoff, gbase, voff) do { _Pragma("unroll") for (int _i = 0; _i < 2; ++_i) \
;         __builtin_amdgcn_global_load_lds((const unsigned*)((const char*)(gbase) + (voff)[_i]), (LAS unsigned*)(lds + (bufoff) + ldsw + _i * 8192), 16, 0, 0); } while (0)
; #define PG8_LDA(dst, b, h) do { _Pragma("unroll") for (int m = 0; m < 4; ++m) _Pragma("unroll") for (int k = 0; k < 2; ++k) dst[m][k] = *(const LAS bf16x8*)(lds + PG8_SA(b, h) + aoff + m * 2048 + k * 1024); } while (0)
; #define PG8_LDB(dst, b, h) do { _Pragma("unroll") for (int n = 0; n < 2; ++n) _Pragma("unroll") for (int k = 0; k < 2; ++k) dst[n][k] = *(const LAS bf16x8*)(lds + PG8_SB(b, h) + boff + n * 2048 + k * 1024); } while (0)
; #define PG8_MMA(ai, bj, At, Bt) do { __builtin_amdgcn_s_setprio(1); _Pragma("unroll") for (int m = 0; m < 4; ++m) _Pragma("unroll") for (int n = 0; n < 2; ++n) _Pragma("unroll") for (int k = 0; k < 2; ++k) \
;         acc[ai][bj][m][n] = __builtin_amdgcn_mfma_f32_16x16x32_bf16(Bt[n][k], At[m][k], acc[ai][bj][m][n], 0, 0, 0); __builtin_amdgcn_s_setprio(0); } while (0)
; #define PG8_WAIT_V(n) asm volatile("s_waitcnt vmcnt(" #n ")" ::: "memory")
; #define PG8_BAR __builtin_amdgcn_s_barrier()
; template <class Epi>
; __device__ __forceinline__ void gemm_phase(LAS unsigned char* lds, const Gemm g, const StaticOrder& S, const Epi& E, int wave_s) {
;     ...
;             PG8_LDB(B0, 0, 0); PG8_LDB(B1, 0, 1); PG8_SCHED; PG8_LDA(At, 0, 0); PG8_STAGE(PG8_SA(1, 1), a1 + hstepA, voffA);
;             PG8_WAIT_V(8); PG8_WAIT_L(0); PG8_BAR; PG8_MMA(0, 0, At, B0); PG8_MMA(0, 1, At, B1); PG8_BAR; PG8_SCHED;
;             PG8_LDA(At, 0, 1); PG8_STAGE(PG8_SB(0, 0), b2, voffB); PG8_STAGE(PG8_SB(0, 1), b2 + hstepB, voffB); PG8_STAGE(PG8_SA(0, 0), a2, voffA);
;             PG8_WAIT_V(8); PG8_WAIT_L(0); PG8_BAR; PG8_MMA(1, 0, At, B0); PG8_MMA(1, 1, At, B1); PG8_BAR; PG8_SCHED;
;             PG8_LDB(B0, 1, 0); PG8_LDB(B1, 1, 1); PG8_SCHED; PG8_LDA(At, 1, 0); PG8_STAGE(PG8_SA(0, 1), a2 + hstepA, voffA);
;             PG8_WAIT_V(8); PG8_WAIT_L(0); PG8_BAR; PG8_MMA(0, 0, At, B0); PG8_MMA(0, 1, At, B1); PG8_BAR; PG8_SCHED;
;             PG8_LDA(At, 1, 1); PG8_STAGE(PG8_SB(1, 0), b3, voffB); PG8_STAGE(PG8_SB(1, 1), b3 + hstepB, voffB); PG8_STAGE(PG8_SA(1, 0), a3, voffA);
;             PG8_WAIT_V(8); PG8_WAIT_L(0); PG8_BAR; PG8_MMA(1, 0, At, B0); PG8_MMA(1, 1, At, B1); PG8_BAR; PG8_SCHED;
	s_add_i32 s79, s71, s30
	s_mov_b64 s[88:89], 0x180
	s_add_i32 s71, s79, 0x2000
	v_lshl_add_u64 v[62:63], v[2:3], 0, s[88:89]
	s_mov_b32 m0, s79
	s_add_u32 s82, s24, 0x18180
	ds_read_b128 v[192:195], v155 offset:49152
	ds_read_b128 v[196:199], v155 offset:50176
	ds_read_b128 v[200:203], v155 offset:51200
	ds_read_b128 v[212:215], v155 offset:52224
	ds_read_b128 v[226:229], v155 offset:53248
	ds_read_b128 v[230:233], v155 offset:54272
	ds_read_b128 v[234:237], v155 offset:55296
	ds_read_b128 v[238:241], v155 offset:56320
	global_load_lds_dwordx4 v[62:63], off
	v_lshl_add_u64 v[62:63], v[4:5], 0, s[88:89]
	s_mov_b32 m0, s71
	s_addc_u32 s83, s25, 0
	s_add_i32 s72, s72, s30
	global_load_lds_dwordx4 v[62:63], off
	s_mov_b32 m0, s72
	s_add_i32 s78, s72, 0x2000
	global_load_lds_dwordx4 v134, s[82:83]
	s_mov_b32 m0, s78
	s_nop 0
	global_load_lds_dwordx4 v130, s[82:83]
	v_lshl_add_u64 v[62:63], v[6:7], 0, s[88:89]
	s_mov_b32 m0, s40
	s_nop 0
	global_load_lds_dwordx4 v[62:63], off
	v_lshl_add_u64 v[62:63], v[8:9], 0, s[88:89]
	s_mov_b32 m0, s41
	s_nop 0
	global_load_lds_dwordx4 v[62:63], off
	s_waitcnt vmcnt(8)
	s_waitcnt lgkmcnt(0)
	s_setprio 1
	s_waitcnt lgkmcnt(0)
	v_mfma_f32_16x16x32_bf16 v[14:17], v[34:37], v[234:237], v[14:17]
	v_mfma_f32_16x16x32_bf16 v[18:21], v[138:141], v[234:237], v[18:21]
	v_mfma_f32_16x16x32_bf16 v[156:159], v[34:37], v[192:195], v[156:159]
	v_mfma_f32_16x16x32_bf16 v[160:163], v[138:141], v[192:195], v[160:163]
	s_barrier
	v_mfma_f32_16x16x32_bf16 v[164:167], v[34:37], v[200:203], v[164:167]
	v_mfma_f32_16x16x32_bf16 v[168:171], v[138:141], v[200:203], v[168:171]
	v_mfma_f32_16x16x32_bf16 v[172:175], v[34:37], v[226:229], v[172:175]
	v_mfma_f32_16x16x32_bf16 v[176:179], v[138:141], v[226:229], v[176:179]
	v_mfma_f32_16x16x32_bf16 v[14:17], v[38:41], v[238:241], v[14:17]
	v_mfma_f32_16x16x32_bf16 v[18:21], v[142:145], v[238:241], v[18:21]
	v_mfma_f32_16x16x32_bf16 v[156:159], v[38:41], v[196:199], v[156:159]
	v_mfma_f32_16x16x32_bf16 v[160:163], v[142:145], v[196:199], v[160:163]
	v_mfma_f32_16x16x32_bf16 v[164:167], v[38:41], v[212:215], v[164:167]
	v_mfma_f32_16x16x32_bf16 v[168:171], v[142:145], v[212:215], v[168:171]
	v_mfma_f32_16x16x32_bf16 v[172:175], v[38:41], v[230:233], v[172:175]
	v_mfma_f32_16x16x32_bf16 v[176:179], v[142:145], v[230:233], v[176:179]
	s_setprio 0
	s_setprio 1
	v_mfma_f32_16x16x32_bf16 v[22:25], v[146:149], v[192:195], v[22:25]
	v_mfma_f32_16x16x32_bf16 v[34:37], v[184:187], v[192:195], v[64:67]
	v_mfma_f32_16x16x32_bf16 v[38:41], v[146:149], v[200:203], v[112:115]
	v_mfma_f32_16x16x32_bf16 v[62:65], v[184:187], v[200:203], v[116:119]
	v_mfma_f32_16x16x32_bf16 v[112:115], v[146:149], v[226:229], v[120:123]
	v_mfma_f32_16x16x32_bf16 v[116:119], v[184:187], v[226:229], v[124:127]
	v_mfma_f32_16x16x32_bf16 v[26:29], v[146:149], v[234:237], v[26:29]
	v_mfma_f32_16x16x32_bf16 v[30:33], v[184:187], v[234:237], v[30:33]
	v_mfma_f32_16x16x32_bf16 v[22:25], v[180:183], v[196:199], v[22:25]
	v_mfma_f32_16x16x32_bf16 v[34:37], v[188:191], v[196:199], v[34:37]
	v_mfma_f32_16x16x32_bf16 v[38:41], v[180:183], v[212:215], v[38:41]
	v_mfma_f32_16x16x32_bf16 v[62:65], v[188:191], v[212:215], v[62:65]
	v_mfma_f32_16x16x32_bf16 v[112:115], v[180:183], v[230:233], v[112:115]
	v_mfma_f32_16x16x32_bf16 v[116:119], v[188:191], v[230:233], v[116:119]
	v_mfma_f32_16x16x32_bf16 v[26:29], v[180:183], v[238:241], v[26:29]
	v_mfma_f32_16x16x32_bf16 v[30:33], v[188:191], v[238:241], v[30:33]
	s_setprio 0
	s_barrier
	ds_read_b128 v[120:123], v0
	ds_read_b128 v[124:127], v0 offset:1024
	ds_read_b128 v[138:141], v0 offset:2048
	ds_read_b128 v[142:145], v0 offset:3072
	ds_read_b128 v[146:149], v10
	ds_read_b128 v[180:183], v10 offset:1024
	ds_read_b128 v[184:187], v10 offset:2048
	ds_read_b128 v[188:191], v10 offset:3072
	s_add_u32 s82, s22, 0x110180
	s_addc_u32 s83, s23, 0
	s_mov_b32 m0, s73
	ds_read_b128 v[192:195], v155
	ds_read_b128 v[196:199], v155 offset:1024
	ds_read_b128 v[200:203], v155 offset:2048
	ds_read_b128 v[212:215], v155 offset:3072
	ds_read_b128 v[226:229], v155 offset:4096
	ds_read_b128 v[230:233], v155 offset:5120
	ds_read_b128 v[234:237], v155 offset:6144
	ds_read_b128 v[238:241], v155 offset:7168
	global_load_lds_dwordx4 v136, s[82:83]
	v_lshl_add_u64 v[66:67], s[82:83], 0, v[132:133]
	s_mov_b32 m0, s4
	s_nop 0
	global_load_lds_dwordx4 v[66:67], off
	s_waitcnt vmcnt(8)
	s_waitcnt lgkmcnt(0)
	s_setprio 1
	s_waitcnt lgkmcnt(0)
	v_mfma_f32_16x16x32_bf16 v[66:69], v[120:123], v[192:195], v[68:71]
	v_mfma_f32_16x16x32_bf16 v[70:73], v[138:141], v[192:195], v[72:75]
	v_mfma_f32_16x16x32_bf16 v[74:77], v[120:123], v[200:203], v[76:79]
	v_mfma_f32_16x16x32_bf16 v[78:81], v[138:141], v[200:203], v[80:83]
	s_barrier
; #define PG8_STAGE(bufoff, gbase, voff) do { _Pragma("unroll") for (int _i = 0; _i < 2; ++_i) \
;         __builtin_amdgcn_global_load_lds((const unsigned*)((const char*)(gbase) + (voff)[_i]), (LAS unsigned*)(lds + (bufoff) + ldsw + _i * 8192), 16, 0, 0); } while (0)
; #define PG8_LDA(dst, b, h) do { _Pragma("unroll") for (int m = 0; m < 4; ++m) _Pragma("unroll") for (int k = 0; k < 2; ++k) dst[m][k] = *(const LAS bf16x8*)(lds + PG8_SA(b, h) + aoff + m * 2048 + k * 1024); } while (0)
; #define PG8_LDB(dst, b, h) do { _Pragma("unroll") for (int n = 0; n < 2; ++n) _Pragma("unroll") for (int k = 0; k < 2; ++k) dst[n][k] = *(const LAS bf16x8*)(lds + PG8_SB(b, h) + boff + n * 2048 + k * 1024); } while (0)
; #define PG8_MMA(ai, bj, At, Bt) do { __builtin_amdgcn_s_setprio(1); _Pragma("unroll") for (int m = 0; m < 4; ++m) _Pragma("unroll") for (int n = 0; n < 2; ++n) _Pragma("unroll") for (int k = 0; k < 2; ++k) \
;         acc[ai][bj][m][n] = __builtin_amdgcn_mfma_f32_16x16x32_bf16(Bt[n][k], At[m][k], acc[ai][bj][m][n], 0, 0, 0); __builtin_amdgcn_s_setprio(0); } while (0)
; #define PG8_WAIT_V(n) asm volatile("s_waitcnt vmcnt(" #n ")" ::: "memory")
; #define PG8_WAIT_L(n) asm volatile("s_waitcnt lgkmcnt(" #n ")" ::: "memory")
; #define PG8_BAR __builtin_amdgcn_s_barrier()
; #define PG8_SCHED __builtin_amdgcn_sched_barrier(0)
; template <class Epi>
; __device__ __forceinline__ void gemm_phase(LAS unsigned char* lds, const Gemm g, const StaticOrder& S, const Epi& E, int wave_s) {
;     ...
;             PG8_LDB(B0, 0, 0); PG8_LDB(B1, 0, 1); PG8_SCHED; PG8_LDA(At, 0, 0); PG8_STAGE(PG8_SA(1, 1), a1 + hstepA, voffA);
;             PG8_WAIT_V(8); PG8_WAIT_L(0); PG8_BAR; PG8_MMA(0, 0, At, B0); PG8_MMA(0, 1, At, B1); PG8_BAR; PG8_SCHED;
;             PG8_LDA(At, 0, 1); PG8_STAGE(PG8_SB(0, 0), b2, voffB); PG8_STAGE(PG8_SB(0, 1), b2 + hstepB, voffB); PG8_STAGE(PG8_SA(0, 0), a2, voffA);
;             PG8_WAIT_V(8); PG8_WAIT_L(0); PG8_BAR; PG8_MMA(1, 0, At, B0); PG8_MMA(1, 1, At, B1); PG8_BAR; PG8_SCHED;
	v_mfma_f32_16x16x32_bf16 v[82:85], v[120:123], v[226:229], v[84:87]
	v_mfma_f32_16x16x32_bf16 v[86:89], v[138:141], v[226:229], v[88:91]
	v_mfma_f32_16x16x32_bf16 v[90:93], v[120:123], v[234:237], v[92:95]
	v_mfma_f32_16x16x32_bf16 v[94:97], v[138:141], v[234:237], v[96:99]
	v_mfma_f32_16x16x32_bf16 v[66:69], v[124:127], v[196:199], v[66:69]
	v_mfma_f32_16x16x32_bf16 v[70:73], v[142:145], v[196:199], v[70:73]
	v_mfma_f32_16x16x32_bf16 v[74:77], v[124:127], v[212:215], v[74:77]
	v_mfma_f32_16x16x32_bf16 v[78:81], v[142:145], v[212:215], v[78:81]
	v_mfma_f32_16x16x32_bf16 v[82:85], v[124:127], v[230:233], v[82:85]
	v_mfma_f32_16x16x32_bf16 v[86:89], v[142:145], v[230:233], v[86:89]
	v_mfma_f32_16x16x32_bf16 v[90:93], v[124:127], v[238:241], v[90:93]
	v_mfma_f32_16x16x32_bf16 v[94:97], v[142:145], v[238:241], v[94:97]
	s_setprio 0
	s_setprio 1
	v_mfma_f32_16x16x32_bf16 v[98:101], v[146:149], v[192:195], v[100:103]
	v_mfma_f32_16x16x32_bf16 v[102:105], v[184:187], v[192:195], v[104:107]
	v_mfma_f32_16x16x32_bf16 v[106:109], v[146:149], v[200:203], v[108:111]
	v_mfma_f32_16x16x32_bf16 v[42:45], v[184:187], v[200:203], v[42:45]
	v_mfma_f32_16x16x32_bf16 v[46:49], v[146:149], v[226:229], v[46:49]
	v_mfma_f32_16x16x32_bf16 v[50:53], v[184:187], v[226:229], v[50:53]
	v_mfma_f32_16x16x32_bf16 v[54:57], v[146:149], v[234:237], v[54:57]
	v_mfma_f32_16x16x32_bf16 v[58:61], v[184:187], v[234:237], v[58:61]
	v_mfma_f32_16x16x32_bf16 v[98:101], v[180:183], v[196:199], v[98:101]
	v_mfma_f32_16x16x32_bf16 v[102:105], v[188:191], v[196:199], v[102:105]
	v_mfma_f32_16x16x32_bf16 v[106:109], v[180:183], v[212:215], v[106:109]
	v_mfma_f32_16x16x32_bf16 v[42:45], v[188:191], v[212:215], v[42:45]
	v_mfma_f32_16x16x32_bf16 v[46:49], v[180:183], v[230:233], v[46:49]
	v_mfma_f32_16x16x32_bf16 v[50:53], v[188:191], v[230:233], v[50:53]
	v_mfma_f32_16x16x32_bf16 v[54:57], v[180:183], v[238:241], v[54:57]
	v_mfma_f32_16x16x32_bf16 v[58:61], v[188:191], v[238:241], v[58:61]
	s_setprio 0
	s_barrier
	s_mov_b64 s[88:89], 0x200
	s_mov_b32 m0, s70
	v_lshl_add_u64 v[110:111], v[2:3], 0, s[88:89]
	s_add_u32 s82, s24, 0x18200
	ds_read_b128 v[192:195], v155 offset:16384
	ds_read_b128 v[196:199], v155 offset:17408
	ds_read_b128 v[200:203], v155 offset:18432
	ds_read_b128 v[212:215], v155 offset:19456
	ds_read_b128 v[226:229], v155 offset:20480
	ds_read_b128 v[230:233], v155 offset:21504
	ds_read_b128 v[234:237], v155 offset:22528
	ds_read_b128 v[238:241], v155 offset:23552
	global_load_lds_dwordx4 v[110:111], off
	v_lshl_add_u64 v[110:111], v[4:5], 0, s[88:89]
	s_mov_b32 m0, s5
	s_addc_u32 s83, s25, 0
	global_load_lds_dwordx4 v[110:111], off
	s_mov_b32 m0, s66
	s_nop 0
	global_load_lds_dwordx4 v134, s[82:83]
	s_mov_b32 m0, s67
	s_nop 0
	global_load_lds_dwordx4 v130, s[82:83]
	v_lshl_add_u64 v[110:111], v[6:7], 0, s[88:89]
	s_mov_b32 m0, s31
	s_nop 0
	global_load_lds_dwordx4 v[110:111], off
	v_lshl_add_u64 v[110:111], v[8:9], 0, s[88:89]
	s_mov_b32 m0, s34
	s_nop 0
	global_load_lds_dwordx4 v[110:111], off
	s_waitcnt vmcnt(8)
	s_waitcnt lgkmcnt(0)
	s_setprio 1
	s_waitcnt lgkmcnt(0)
	v_mfma_f32_16x16x32_bf16 v[14:17], v[120:123], v[234:237], v[14:17]
	v_mfma_f32_16x16x32_bf16 v[18:21], v[138:141], v[234:237], v[18:21]
	v_mfma_f32_16x16x32_bf16 v[156:159], v[120:123], v[192:195], v[156:159]
	v_mfma_f32_16x16x32_bf16 v[160:163], v[138:141], v[192:195], v[160:163]
	s_barrier
	v_mfma_f32_16x16x32_bf16 v[164:167], v[120:123], v[200:203], v[164:167]
	v_mfma_f32_16x16x32_bf16 v[168:171], v[138:141], v[200:203], v[168:171]
	v_mfma_f32_16x16x32_bf16 v[172:175], v[120:123], v[226:229], v[172:175]
	v_mfma_f32_16x16x32_bf16 v[176:179], v[138:141], v[226:229], v[176:179]
	v_mfma_f32_16x16x32_bf16 v[14:17], v[124:127], v[238:241], v[14:17]
	v_mfma_f32_16x16x32_bf16 v[18:21], v[142:145], v[238:241], v[18:21]
	v_mfma_f32_16x16x32_bf16 v[156:159], v[124:127], v[196:199], v[156:159]
	v_mfma_f32_16x16x32_bf16 v[160:163], v[142:145], v[196:199], v[160:163]
	v_mfma_f32_16x16x32_bf16 v[164:167], v[124:127], v[212:215], v[164:167]
	v_mfma_f32_16x16x32_bf16 v[168:171], v[142:145], v[212:215], v[168:171]
	v_mfma_f32_16x16x32_bf16 v[172:175], v[124:127], v[230:233], v[172:175]
	v_mfma_f32_16x16x32_bf16 v[176:179], v[142:145], v[230:233], v[176:179]
	s_setprio 0
	s_setprio 1
	v_mfma_f32_16x16x32_bf16 v[22:25], v[146:149], v[192:195], v[22:25]
	v_mfma_f32_16x16x32_bf16 v[34:37], v[184:187], v[192:195], v[34:37]
	v_mfma_f32_16x16x32_bf16 v[38:41], v[146:149], v[200:203], v[38:41]
	v_mfma_f32_16x16x32_bf16 v[62:65], v[184:187], v[200:203], v[62:65]
	v_mfma_f32_16x16x32_bf16 v[110:113], v[146:149], v[226:229], v[112:115]
	v_mfma_f32_16x16x32_bf16 v[114:117], v[184:187], v[226:229], v[116:119]
	v_mfma_f32_16x16x32_bf16 v[26:29], v[146:149], v[234:237], v[26:29]
	v_mfma_f32_16x16x32_bf16 v[30:33], v[184:187], v[234:237], v[30:33]
	v_mfma_f32_16x16x32_bf16 v[22:25], v[180:183], v[196:199], v[22:25]
	v_mfma_f32_16x16x32_bf16 v[34:37], v[188:191], v[196:199], v[34:37]
	v_mfma_f32_16x16x32_bf16 v[38:41], v[180:183], v[212:215], v[38:41]
	v_mfma_f32_16x16x32_bf16 v[62:65], v[188:191], v[212:215], v[62:65]
	v_mfma_f32_16x16x32_bf16 v[110:113], v[180:183], v[230:233], v[110:113]
	v_mfma_f32_16x16x32_bf16 v[114:117], v[188:191], v[230:233], v[114:117]
	v_mfma_f32_16x16x32_bf16 v[26:29], v[180:183], v[238:241], v[26:29]
	v_mfma_f32_16x16x32_bf16 v[30:33], v[188:191], v[238:241], v[30:33]
	s_setprio 0
	s_barrier
; #define PG8_STAGE(bufoff, gbase, voff) do { _Pragma("unroll") for (int _i = 0; _i < 2; ++_i) \
;         __builtin_amdgcn_global_load_lds((const unsigned*)((const char*)(gbase) + (voff)[_i]), (LAS unsigned*)(lds + (bufoff) + ldsw + _i * 8192), 16, 0, 0); } while (0)
; #define PG8_LDA(dst, b, h) do { _Pragma("unroll") for (int m = 0; m < 4; ++m) _Pragma("unroll") for (int k = 0; k < 2; ++k) dst[m][k] = *(const LAS bf16x8*)(lds + PG8_SA(b, h) + aoff + m * 2048 + k * 1024); } while (0)
; #define PG8_LDB(dst, b, h) do { _Pragma("unroll") for (int n = 0; n < 2; ++n) _Pragma("unroll") for (int k = 0; k < 2; ++k) dst[n][k] = *(const LAS bf16x8*)(lds + PG8_SB(b, h) + boff + n * 2048 + k * 1024); } while (0)
; #define PG8_MMA(ai, bj, At, Bt) do { __builtin_amdgcn_s_setprio(1); _Pragma("unroll") for (int m = 0; m < 4; ++m) _Pragma("unroll") for (int n = 0; n < 2; ++n) _Pragma("unroll") for (int k = 0; k < 2; ++k) \
;         acc[ai][bj][m][n] = __builtin_amdgcn_mfma_f32_16x16x32_bf16(Bt[n][k], At[m][k], acc[ai][bj][m][n], 0, 0, 0); __builtin_amdgcn_s_setprio(0); } while (0)
; #define PG8_WAIT_V(n) asm volatile("s_waitcnt vmcnt(" #n ")" ::: "memory")
; #define PG8_WAIT_L(n) asm volatile("s_waitcnt lgkmcnt(" #n ")" ::: "memory")
; #define PG8_BAR __builtin_amdgcn_s_barrier()
; #define PG8_SCHED __builtin_amdgcn_sched_barrier(0)
; template <class Epi>
; __device__ __forceinline__ void gemm_phase(LAS unsigned char* lds, const Gemm g, const StaticOrder& S, const Epi& E, int wave_s) {
;     ...
;             PG8_WAIT_V(8); PG8_WAIT_L(0); PG8_BAR; PG8_MMA(1, 0, At, B0); PG8_MMA(1, 1, At, B1); PG8_BAR; PG8_SCHED;
;             PG8_LDB(B0, 1, 0); PG8_LDB(B1, 1, 1); PG8_SCHED; PG8_LDA(At, 1, 0); PG8_STAGE(PG8_SA(0, 1), a2 + hstepA, voffA);
;             PG8_WAIT_V(8); PG8_WAIT_L(0); PG8_BAR; PG8_MMA(0, 0, At, B0); PG8_MMA(0, 1, At, B1); PG8_BAR; PG8_SCHED;
;             PG8_LDA(At, 1, 1); PG8_STAGE(PG8_SB(1, 0), b3, voffB); PG8_STAGE(PG8_SB(1, 1), b3 + hstepB, voffB); PG8_STAGE(PG8_SA(1, 0), a3, voffA);
;             PG8_WAIT_V(8); PG8_WAIT_L(0); PG8_BAR; PG8_MMA(1, 0, At, B0); PG8_MMA(1, 1, At, B1); PG8_BAR; PG8_SCHED;
	ds_read_b128 v[118:121], v11
	ds_read_b128 v[122:125], v11 offset:1024
	ds_read_b128 v[126:129], v11 offset:2048
	ds_read_b128 v[138:141], v11 offset:3072
	ds_read_b128 v[142:145], v12
	ds_read_b128 v[146:149], v12 offset:1024
	ds_read_b128 v[180:183], v12 offset:2048
	ds_read_b128 v[184:187], v12 offset:3072
	s_add_u32 s82, s22, 0x110200
	s_addc_u32 s83, s23, 0
	s_mov_b32 m0, s35
	ds_read_b128 v[188:191], v155 offset:32768
	ds_read_b128 v[192:195], v155 offset:33792
	ds_read_b128 v[196:199], v155 offset:34816
	ds_read_b128 v[200:203], v155 offset:35840
	ds_read_b128 v[212:215], v155 offset:36864
	ds_read_b128 v[226:229], v155 offset:37888
	ds_read_b128 v[230:233], v155 offset:38912
	ds_read_b128 v[234:237], v155 offset:39936
	global_load_lds_dwordx4 v136, s[82:83]
	s_mov_b32 m0, s37
	s_nop 0
	global_load_lds_dwordx4 v132, s[82:83]
	s_waitcnt vmcnt(8)
	s_waitcnt lgkmcnt(0)
	s_setprio 1
	s_waitcnt lgkmcnt(0)
	v_mfma_f32_16x16x32_bf16 v[66:69], v[118:121], v[188:191], v[66:69]
	v_mfma_f32_16x16x32_bf16 v[70:73], v[126:129], v[188:191], v[70:73]
	v_mfma_f32_16x16x32_bf16 v[74:77], v[118:121], v[196:199], v[74:77]
	v_mfma_f32_16x16x32_bf16 v[78:81], v[126:129], v[196:199], v[78:81]
	s_barrier
	v_mfma_f32_16x16x32_bf16 v[82:85], v[118:121], v[212:215], v[82:85]
	v_mfma_f32_16x16x32_bf16 v[86:89], v[126:129], v[212:215], v[86:89]
	v_mfma_f32_16x16x32_bf16 v[90:93], v[118:121], v[230:233], v[90:93]
	v_mfma_f32_16x16x32_bf16 v[94:97], v[126:129], v[230:233], v[94:97]
	v_mfma_f32_16x16x32_bf16 v[66:69], v[122:125], v[192:195], v[66:69]
	v_mfma_f32_16x16x32_bf16 v[70:73], v[138:141], v[192:195], v[70:73]
	v_mfma_f32_16x16x32_bf16 v[74:77], v[122:125], v[200:203], v[74:77]
	v_mfma_f32_16x16x32_bf16 v[78:81], v[138:141], v[200:203], v[78:81]
	v_mfma_f32_16x16x32_bf16 v[82:85], v[122:125], v[226:229], v[82:85]
	v_mfma_f32_16x16x32_bf16 v[86:89], v[138:141], v[226:229], v[86:89]
	v_mfma_f32_16x16x32_bf16 v[90:93], v[122:125], v[234:237], v[90:93]
	v_mfma_f32_16x16x32_bf16 v[94:97], v[138:141], v[234:237], v[94:97]
	s_setprio 0
	s_setprio 1
	v_mfma_f32_16x16x32_bf16 v[98:101], v[142:145], v[188:191], v[98:101]
	v_mfma_f32_16x16x32_bf16 v[102:105], v[180:183], v[188:191], v[102:105]
	v_mfma_f32_16x16x32_bf16 v[106:109], v[142:145], v[196:199], v[106:109]
	v_mfma_f32_16x16x32_bf16 v[42:45], v[180:183], v[196:199], v[42:45]
	v_mfma_f32_16x16x32_bf16 v[46:49], v[142:145], v[212:215], v[46:49]
	v_mfma_f32_16x16x32_bf16 v[50:53], v[180:183], v[212:215], v[50:53]
	v_mfma_f32_16x16x32_bf16 v[54:57], v[142:145], v[230:233], v[54:57]
	v_mfma_f32_16x16x32_bf16 v[58:61], v[180:183], v[230:233], v[58:61]
	v_mfma_f32_16x16x32_bf16 v[98:101], v[146:149], v[192:195], v[98:101]
	v_mfma_f32_16x16x32_bf16 v[102:105], v[184:187], v[192:195], v[102:105]
	v_mfma_f32_16x16x32_bf16 v[106:109], v[146:149], v[200:203], v[106:109]
	v_mfma_f32_16x16x32_bf16 v[42:45], v[184:187], v[200:203], v[42:45]
	v_mfma_f32_16x16x32_bf16 v[46:49], v[146:149], v[226:229], v[46:49]
	v_mfma_f32_16x16x32_bf16 v[50:53], v[184:187], v[226:229], v[50:53]
	v_mfma_f32_16x16x32_bf16 v[54:57], v[146:149], v[234:237], v[54:57]
	v_mfma_f32_16x16x32_bf16 v[58:61], v[184:187], v[234:237], v[58:61]
	s_setprio 0
	s_barrier
	s_mov_b64 s[82:83], 0x280
	s_mov_b32 m0, s79
	v_lshl_add_u64 v[2:3], v[2:3], 0, s[82:83]
	s_add_u32 s24, s24, 0x18280
	ds_read_b128 v[188:191], v155 offset:49152
	ds_read_b128 v[192:195], v155 offset:50176
	ds_read_b128 v[196:199], v155 offset:51200
	ds_read_b128 v[200:203], v155 offset:52224
	ds_read_b128 v[212:215], v155 offset:53248
	ds_read_b128 v[226:229], v155 offset:54272
	ds_read_b128 v[230:233], v155 offset:55296
	ds_read_b128 v[234:237], v155 offset:56320
	global_load_lds_dwordx4 v[2:3], off
	v_lshl_add_u64 v[2:3], v[4:5], 0, s[82:83]
	s_mov_b32 m0, s71
	s_addc_u32 s25, s25, 0
	global_load_lds_dwordx4 v[2:3], off
	s_mov_b32 m0, s72
	s_nop 0
	global_load_lds_dwordx4 v134, s[24:25]
	s_mov_b32 m0, s78
	s_nop 0
	global_load_lds_dwordx4 v130, s[24:25]
	v_lshl_add_u64 v[2:3], v[6:7], 0, s[82:83]
	s_mov_b32 m0, s40
	s_nop 0
	global_load_lds_dwordx4 v[2:3], off
	v_lshl_add_u64 v[2:3], v[8:9], 0, s[82:83]
	s_mov_b32 m0, s41
	s_nop 0
	global_load_lds_dwordx4 v[2:3], off
	s_waitcnt vmcnt(8)
	s_waitcnt lgkmcnt(0)
	s_setprio 1
	s_waitcnt lgkmcnt(0)
	v_mfma_f32_16x16x32_bf16 v[2:5], v[118:121], v[188:191], v[156:159]
	v_mfma_f32_16x16x32_bf16 v[6:9], v[126:129], v[188:191], v[160:163]
	v_mfma_f32_16x16x32_bf16 v[14:17], v[118:121], v[230:233], v[14:17]
	v_mfma_f32_16x16x32_bf16 v[18:21], v[126:129], v[230:233], v[18:21]
	s_barrier
	v_mfma_f32_16x16x32_bf16 v[2:5], v[122:125], v[192:195], v[2:5]
	v_mfma_f32_16x16x32_bf16 v[6:9], v[138:141], v[192:195], v[6:9]
	v_mfma_f32_16x16x32_bf16 v[156:159], v[118:121], v[196:199], v[164:167]
	v_mfma_f32_16x16x32_bf16 v[160:163], v[126:129], v[196:199], v[168:171]
	v_mfma_f32_16x16x32_bf16 v[164:167], v[118:121], v[212:215], v[172:175]
	v_mfma_f32_16x16x32_bf16 v[168:171], v[126:129], v[212:215], v[176:179]
	v_mfma_f32_16x16x32_bf16 v[14:17], v[122:125], v[234:237], v[14:17]
	v_mfma_f32_16x16x32_bf16 v[18:21], v[138:141], v[234:237], v[18:21]
	v_mfma_f32_16x16x32_bf16 v[156:159], v[122:125], v[200:203], v[156:159]
	v_mfma_f32_16x16x32_bf16 v[160:163], v[138:141], v[200:203], v[160:163]
	v_mfma_f32_16x16x32_bf16 v[164:167], v[122:125], v[226:229], v[164:167]
	v_mfma_f32_16x16x32_bf16 v[168:171], v[138:141], v[226:229], v[168:171]
	s_setprio 0
	s_setprio 1
	v_mfma_f32_16x16x32_bf16 v[22:25], v[142:145], v[188:191], v[22:25]
	v_mfma_f32_16x16x32_bf16 v[34:37], v[180:183], v[188:191], v[34:37]
	v_mfma_f32_16x16x32_bf16 v[38:41], v[142:145], v[196:199], v[38:41]
	v_mfma_f32_16x16x32_bf16 v[62:65], v[180:183], v[196:199], v[62:65]
	v_mfma_f32_16x16x32_bf16 v[110:113], v[142:145], v[212:215], v[110:113]
	v_mfma_f32_16x16x32_bf16 v[114:117], v[180:183], v[212:215], v[114:117]
	v_mfma_f32_16x16x32_bf16 v[26:29], v[142:145], v[230:233], v[26:29]
	v_mfma_f32_16x16x32_bf16 v[30:33], v[180:183], v[230:233], v[30:33]
	v_mfma_f32_16x16x32_bf16 v[22:25], v[146:149], v[192:195], v[22:25]
	v_mfma_f32_16x16x32_bf16 v[34:37], v[184:187], v[192:195], v[34:37]
	v_mfma_f32_16x16x32_bf16 v[38:41], v[146:149], v[200:203], v[38:41]
	v_mfma_f32_16x16x32_bf16 v[62:65], v[184:187], v[200:203], v[62:65]
	v_mfma_f32_16x16x32_bf16 v[110:113], v[146:149], v[226:229], v[110:113]
	v_mfma_f32_16x16x32_bf16 v[114:117], v[184:187], v[226:229], v[114:117]
	v_mfma_f32_16x16x32_bf16 v[26:29], v[146:149], v[234:237], v[26:29]
	v_mfma_f32_16x16x32_bf16 v[30:33], v[184:187], v[234:237], v[30:33]
	s_setprio 0
	s_barrier
; #define PG8_STAGE(bufoff, gbase, voff) do { _Pragma("unroll") for (int _i = 0; _i < 2; ++_i) \
;         __builtin_amdgcn_global_load_lds((const unsigned*)((const char*)(gbase) + (voff)[_i]), (LAS unsigned*)(lds + (bufoff) + ldsw + _i * 8192), 16, 0, 0); } while (0)
; #define PG8_LDA(dst, b, h) do { _Pragma("unroll") for (int m = 0; m < 4; ++m) _Pragma("unroll") for (int k = 0; k < 2; ++k) dst[m][k] = *(const LAS bf16x8*)(lds + PG8_SA(b, h) + aoff + m * 2048 + k * 1024); } while (0)
; #define PG8_LDB(dst, b, h) do { _Pragma("unroll") for (int n = 0; n < 2; ++n) _Pragma("unroll") for (int k = 0; k < 2; ++k) dst[n][k] = *(const LAS bf16x8*)(lds + PG8_SB(b, h) + boff + n * 2048 + k * 1024); } while (0)
; #define PG8_MMA(ai, bj, At, Bt) do { __builtin_amdgcn_s_setprio(1); _Pragma("unroll") for (int m = 0; m < 4; ++m) _Pragma("unroll") for (int n = 0; n < 2; ++n) _Pragma("unroll") for (int k = 0; k < 2; ++k) \
;         acc[ai][bj][m][n] = __builtin_amdgcn_mfma_f32_16x16x32_bf16(Bt[n][k], At[m][k], acc[ai][bj][m][n], 0, 0, 0); __builtin_amdgcn_s_setprio(0); } while (0)
; #define PG8_WAIT_V(n) asm volatile("s_waitcnt vmcnt(" #n ")" ::: "memory")
; #define PG8_WAIT_L(n) asm volatile("s_waitcnt lgkmcnt(" #n ")" ::: "memory")
; #define PG8_BAR __builtin_amdgcn_s_barrier()
; #define PG8_SCHED __builtin_amdgcn_sched_barrier(0)
; template <class Epi>
; __device__ __forceinline__ void gemm_phase(LAS unsigned char* lds, const Gemm g, const StaticOrder& S, const Epi& E, int wave_s) {
;     ...
;             const char* a2 = last ? nA : cA + (size_t)(t + 2) * kstep; const char* b2 = last ? nB : cB + (size_t)(t + 2) * kstep;
;             const char* a3 = a2 + kstep; const char* b3 = b2 + kstep;
;             PG8_LDB(B0, 0, 0); PG8_LDB(B1, 0, 1); PG8_SCHED; PG8_LDA(At, 0, 0); PG8_STAGE(PG8_SA(1, 1), a1 + hstepA, voffA);
;             PG8_WAIT_V(8); PG8_WAIT_L(0); PG8_BAR; PG8_MMA(0, 0, At, B0); PG8_MMA(0, 1, At, B1); PG8_BAR; PG8_SCHED;
;             PG8_LDA(At, 0, 1); PG8_STAGE(PG8_SB(0, 0), b2, voffB); PG8_STAGE(PG8_SB(0, 1), b2 + hstepB, voffB); PG8_STAGE(PG8_SA(0, 0), a2, voffA);
;             PG8_WAIT_V(8); PG8_WAIT_L(0); PG8_BAR; PG8_MMA(1, 0, At, B0); PG8_MMA(1, 1, At, B1); PG8_BAR; PG8_SCHED;
	ds_read_b128 v[118:121], v0
	ds_read_b128 v[122:125], v0 offset:1024
	ds_read_b128 v[126:129], v0 offset:2048
	ds_read_b128 v[138:141], v0 offset:3072
	ds_read_b128 v[142:145], v10
	ds_read_b128 v[146:149], v10 offset:1024
	ds_read_b128 v[172:175], v10 offset:2048
	ds_read_b128 v[176:179], v10 offset:3072
	s_add_u32 s22, s22, 0x110280
	s_addc_u32 s23, s23, 0
	s_mov_b32 m0, s73
	ds_read_b128 v[180:183], v155
	ds_read_b128 v[184:187], v155 offset:1024
	ds_read_b128 v[188:191], v155 offset:2048
	ds_read_b128 v[192:195], v155 offset:3072
	ds_read_b128 v[196:199], v155 offset:4096
	ds_read_b128 v[200:203], v155 offset:5120
	ds_read_b128 v[212:215], v155 offset:6144
	ds_read_b128 v[226:229], v155 offset:7168
	global_load_lds_dwordx4 v136, s[22:23]
	s_mov_b32 m0, s4
	s_nop 0
	global_load_lds_dwordx4 v132, s[22:23]
	s_waitcnt vmcnt(8)
	s_waitcnt lgkmcnt(0)
	s_setprio 1
	s_waitcnt lgkmcnt(0)
	v_mfma_f32_16x16x32_bf16 v[66:69], v[118:121], v[180:183], v[66:69]
	v_mfma_f32_16x16x32_bf16 v[70:73], v[126:129], v[180:183], v[70:73]
	v_mfma_f32_16x16x32_bf16 v[74:77], v[118:121], v[188:191], v[74:77]
	v_mfma_f32_16x16x32_bf16 v[78:81], v[126:129], v[188:191], v[78:81]
	s_barrier
	v_mfma_f32_16x16x32_bf16 v[82:85], v[118:121], v[196:199], v[82:85]
	v_mfma_f32_16x16x32_bf16 v[86:89], v[126:129], v[196:199], v[86:89]
	v_mfma_f32_16x16x32_bf16 v[90:93], v[118:121], v[212:215], v[90:93]
	v_mfma_f32_16x16x32_bf16 v[66:69], v[122:125], v[184:187], v[66:69]
	v_mfma_f32_16x16x32_bf16 v[70:73], v[138:141], v[184:187], v[70:73]
	v_mfma_f32_16x16x32_bf16 v[74:77], v[122:125], v[192:195], v[74:77]
	v_mfma_f32_16x16x32_bf16 v[78:81], v[138:141], v[192:195], v[78:81]
	v_mfma_f32_16x16x32_bf16 v[82:85], v[122:125], v[200:203], v[82:85]
	v_mfma_f32_16x16x32_bf16 v[86:89], v[138:141], v[200:203], v[86:89]
	v_mfma_f32_16x16x32_bf16 v[230:233], v[122:125], v[226:229], v[90:93]
	v_mfma_f32_16x16x32_bf16 v[90:93], v[126:129], v[212:215], v[94:97]
	v_mfma_f32_16x16x32_bf16 v[234:237], v[138:141], v[226:229], v[90:93]
	s_setprio 0
	s_setprio 1
	v_mfma_f32_16x16x32_bf16 v[90:93], v[142:145], v[180:183], v[98:101]
	v_mfma_f32_16x16x32_bf16 v[98:101], v[146:149], v[184:187], v[90:93]
	v_mfma_f32_16x16x32_bf16 v[90:93], v[172:175], v[180:183], v[102:105]
	v_mfma_f32_16x16x32_bf16 v[42:45], v[172:175], v[188:191], v[42:45]
	v_mfma_f32_16x16x32_bf16 v[46:49], v[142:145], v[196:199], v[46:49]
	v_mfma_f32_16x16x32_bf16 v[50:53], v[172:175], v[196:199], v[50:53]
	v_mfma_f32_16x16x32_bf16 v[54:57], v[142:145], v[212:215], v[54:57]
	v_mfma_f32_16x16x32_bf16 v[58:61], v[172:175], v[212:215], v[58:61]
	v_mfma_f32_16x16x32_bf16 v[102:105], v[176:179], v[184:187], v[90:93]
	v_mfma_f32_16x16x32_bf16 v[90:93], v[142:145], v[188:191], v[106:109]
	v_mfma_f32_16x16x32_bf16 v[42:45], v[176:179], v[192:195], v[42:45]
	v_mfma_f32_16x16x32_bf16 v[46:49], v[146:149], v[200:203], v[46:49]
	v_mfma_f32_16x16x32_bf16 v[50:53], v[176:179], v[200:203], v[50:53]
	v_mfma_f32_16x16x32_bf16 v[54:57], v[146:149], v[226:229], v[54:57]
	v_mfma_f32_16x16x32_bf16 v[58:61], v[176:179], v[226:229], v[58:61]
	v_mfma_f32_16x16x32_bf16 v[180:183], v[146:149], v[192:195], v[90:93]
	s_setprio 0
	s_barrier
	s_mov_b32 m0, s70
	v_lshl_add_u64 v[152:153], s[20:21], 0, v[134:135]
	s_add_u32 s4, s20, 0x18000
	ds_read_b128 v[90:93], v155 offset:16384
	ds_read_b128 v[94:97], v155 offset:17408
	ds_read_b128 v[106:109], v155 offset:18432
	ds_read_b128 v[184:187], v155 offset:19456
	ds_read_b128 v[188:191], v155 offset:20480
	ds_read_b128 v[192:195], v155 offset:21504
	ds_read_b128 v[196:199], v155 offset:22528
	ds_read_b128 v[200:203], v155 offset:23552
	global_load_lds_dwordx4 v[152:153], off
	v_lshl_add_u64 v[216:217], s[20:21], 0, v[130:131]
	s_mov_b32 m0, s5
	s_addc_u32 s5, s21, 0
	global_load_lds_dwordx4 v[216:217], off
	s_mov_b32 m0, s66
	v_lshl_add_u64 v[204:205], s[18:19], 0, v[136:137]
	global_load_lds_dwordx4 v134, s[4:5]
	v_lshl_add_u64 v[208:209], s[4:5], 0, v[130:131]
	s_mov_b32 m0, s67
	v_lshl_add_u64 v[206:207], s[18:19], 0, v[132:133]
	global_load_lds_dwordx4 v[208:209], off
	s_mov_b32 m0, s31
	s_nop 0
	global_load_lds_dwordx4 v[204:205], off
	s_mov_b32 m0, s34
	s_nop 0
	global_load_lds_dwordx4 v[206:207], off
	s_waitcnt vmcnt(8)
	s_waitcnt lgkmcnt(0)
	s_setprio 1
	s_waitcnt lgkmcnt(0)
	v_mfma_f32_16x16x32_bf16 v[2:5], v[118:121], v[90:93], v[2:5]
	v_mfma_f32_16x16x32_bf16 v[6:9], v[126:129], v[90:93], v[6:9]
	v_mfma_f32_16x16x32_bf16 v[14:17], v[118:121], v[196:199], v[14:17]
	v_mfma_f32_16x16x32_bf16 v[18:21], v[126:129], v[196:199], v[18:21]
	s_barrier
	v_mfma_f32_16x16x32_bf16 v[2:5], v[122:125], v[94:97], v[2:5]
	v_mfma_f32_16x16x32_bf16 v[6:9], v[138:141], v[94:97], v[6:9]
	v_mfma_f32_16x16x32_bf16 v[156:159], v[118:121], v[106:109], v[156:159]
	v_mfma_f32_16x16x32_bf16 v[160:163], v[126:129], v[106:109], v[160:163]
	v_mfma_f32_16x16x32_bf16 v[164:167], v[118:121], v[188:191], v[164:167]
	v_mfma_f32_16x16x32_bf16 v[168:171], v[126:129], v[188:191], v[168:171]
	v_mfma_f32_16x16x32_bf16 v[14:17], v[122:125], v[200:203], v[14:17]
	v_mfma_f32_16x16x32_bf16 v[18:21], v[138:141], v[200:203], v[18:21]
	v_mfma_f32_16x16x32_bf16 v[156:159], v[122:125], v[184:187], v[156:159]
	v_mfma_f32_16x16x32_bf16 v[160:163], v[138:141], v[184:187], v[160:163]
	v_mfma_f32_16x16x32_bf16 v[164:167], v[122:125], v[192:195], v[164:167]
	v_mfma_f32_16x16x32_bf16 v[168:171], v[138:141], v[192:195], v[168:171]
	s_setprio 0
	s_setprio 1
	v_mfma_f32_16x16x32_bf16 v[62:65], v[172:175], v[106:109], v[62:65]
	v_mfma_f32_16x16x32_bf16 v[22:25], v[142:145], v[90:93], v[22:25]
	v_mfma_f32_16x16x32_bf16 v[34:37], v[172:175], v[90:93], v[34:37]
	v_mfma_f32_16x16x32_bf16 v[38:41], v[142:145], v[106:109], v[38:41]
	v_mfma_f32_16x16x32_bf16 v[138:141], v[176:179], v[184:187], v[62:65]
	v_mfma_f32_16x16x32_bf16 v[62:65], v[142:145], v[188:191], v[110:113]
	v_mfma_f32_16x16x32_bf16 v[26:29], v[142:145], v[196:199], v[26:29]
	v_mfma_f32_16x16x32_bf16 v[22:25], v[146:149], v[94:97], v[22:25]
	v_mfma_f32_16x16x32_bf16 v[34:37], v[176:179], v[94:97], v[34:37]
	v_mfma_f32_16x16x32_bf16 v[38:41], v[146:149], v[184:187], v[38:41]
	v_mfma_f32_16x16x32_bf16 v[184:187], v[146:149], v[192:195], v[62:65]
	v_mfma_f32_16x16x32_bf16 v[62:65], v[172:175], v[188:191], v[114:117]
	v_mfma_f32_16x16x32_bf16 v[142:145], v[146:149], v[200:203], v[26:29]
	v_mfma_f32_16x16x32_bf16 v[26:29], v[172:175], v[196:199], v[30:33]
	v_mfma_f32_16x16x32_bf16 v[188:191], v[176:179], v[192:195], v[62:65]
	v_mfma_f32_16x16x32_bf16 v[146:149], v[176:179], v[200:203], v[26:29]
	s_setprio 0
	s_barrier
; #define PG8_STAGE(bufoff, gbase, voff) do { _Pragma("unroll") for (int _i = 0; _i < 2; ++_i) \
;         __builtin_amdgcn_global_load_lds((const unsigned*)((const char*)(gbase) + (voff)[_i]), (LAS unsigned*)(lds + (bufoff) + ldsw + _i * 8192), 16, 0, 0); } while (0)
; #define PG8_LDA(dst, b, h) do { _Pragma("unroll") for (int m = 0; m < 4; ++m) _Pragma("unroll") for (int k = 0; k < 2; ++k) dst[m][k] = *(const LAS bf16x8*)(lds + PG8_SA(b, h) + aoff + m * 2048 + k * 1024); } while (0)
; #define PG8_LDB(dst, b, h) do { _Pragma("unroll") for (int n = 0; n < 2; ++n) _Pragma("unroll") for (int k = 0; k < 2; ++k) dst[n][k] = *(const LAS bf16x8*)(lds + PG8_SB(b, h) + boff + n * 2048 + k * 1024); } while (0)
; #define PG8_MMA(ai, bj, At, Bt) do { __builtin_amdgcn_s_setprio(1); _Pragma("unroll") for (int m = 0; m < 4; ++m) _Pragma("unroll") for (int n = 0; n < 2; ++n) _Pragma("unroll") for (int k = 0; k < 2; ++k) \
;         acc[ai][bj][m][n] = __builtin_amdgcn_mfma_f32_16x16x32_bf16(Bt[n][k], At[m][k], acc[ai][bj][m][n], 0, 0, 0); __builtin_amdgcn_s_setprio(0); } while (0)
; #define PG8_WAIT_V(n) asm volatile("s_waitcnt vmcnt(" #n ")" ::: "memory")
; #define PG8_WAIT_L(n) asm volatile("s_waitcnt lgkmcnt(" #n ")" ::: "memory")
; #define PG8_BAR __builtin_amdgcn_s_barrier()
; #define PG8_SCHED __builtin_amdgcn_sched_barrier(0)
; template <class Epi>
; __device__ __forceinline__ void gemm_phase(LAS unsigned char* lds, const Gemm g, const StaticOrder& S, const Epi& E, int wave_s) {
;     ...
;             PG8_WAIT_V(8); PG8_WAIT_L(0); PG8_BAR; PG8_MMA(1, 0, At, B0); PG8_MMA(1, 1, At, B1); PG8_BAR; PG8_SCHED;
;             PG8_LDB(B0, 1, 0); PG8_LDB(B1, 1, 1); PG8_SCHED; PG8_LDA(At, 1, 0); PG8_STAGE(PG8_SA(0, 1), a2 + hstepA, voffA);
;             PG8_WAIT_V(8); PG8_WAIT_L(0); PG8_BAR; PG8_MMA(0, 0, At, B0); PG8_MMA(0, 1, At, B1); PG8_BAR; PG8_SCHED;
;             PG8_LDA(At, 1, 1); PG8_STAGE(PG8_SB(1, 0), b3, voffB); PG8_STAGE(PG8_SB(1, 1), b3 + hstepB, voffB); PG8_STAGE(PG8_SA(1, 0), a3, voffA);
;             PG8_WAIT_V(8); PG8_WAIT_L(0); PG8_BAR; PG8_MMA(1, 0, At, B0); PG8_MMA(1, 1, At, B1); PG8_BAR; PG8_SCHED;
;         }
;         if (wr == 0) PG8_BAR;
	ds_read_b128 v[172:175], v11
	ds_read_b128 v[176:179], v11 offset:1024
	ds_read_b128 v[192:195], v11 offset:2048
	ds_read_b128 v[196:199], v11 offset:3072
	ds_read_b128 v[200:203], v12
	ds_read_b128 v[212:215], v12 offset:1024
	ds_read_b128 v[226:229], v12 offset:2048
	ds_read_b128 v[238:241], v12 offset:3072
	s_add_u32 s4, s18, 0x110000
	s_addc_u32 s5, s19, 0
	s_mov_b32 m0, s35
	ds_read_b128 v[10:13], v155 offset:32768
	ds_read_b128 v[26:29], v155 offset:33792
	ds_read_b128 v[30:33], v155 offset:34816
	ds_read_b128 v[62:65], v155 offset:35840
	ds_read_b128 v[242:245], v155 offset:36864
	ds_read_b128 v[246:249], v155 offset:37888
	ds_read_b128 v[250:253], v155 offset:38912
	ds_read_b128 v[208:211], v155 offset:39936
	global_load_lds_dwordx4 v136, s[4:5]
	v_lshl_add_u64 v[90:91], s[4:5], 0, v[132:133]
	s_mov_b32 m0, s37
	s_nop 0
	global_load_lds_dwordx4 v[90:91], off
	s_waitcnt vmcnt(8)
	s_waitcnt lgkmcnt(0)
	s_setprio 1
	s_waitcnt lgkmcnt(0)
	v_mfma_f32_16x16x32_bf16 v[66:69], v[172:175], v[10:13], v[66:69]
	v_mfma_f32_16x16x32_bf16 v[126:129], v[176:179], v[26:29], v[66:69]
	v_mfma_f32_16x16x32_bf16 v[66:69], v[192:195], v[10:13], v[70:73]
	v_mfma_f32_16x16x32_bf16 v[122:125], v[196:199], v[26:29], v[66:69]
	s_barrier
	v_mfma_f32_16x16x32_bf16 v[66:69], v[172:175], v[30:33], v[74:77]
	v_mfma_f32_16x16x32_bf16 v[110:113], v[176:179], v[62:65], v[66:69]
	v_mfma_f32_16x16x32_bf16 v[66:69], v[192:195], v[30:33], v[78:81]
	v_mfma_f32_16x16x32_bf16 v[106:109], v[196:199], v[62:65], v[66:69]
	v_mfma_f32_16x16x32_bf16 v[66:69], v[172:175], v[242:245], v[82:85]
	v_mfma_f32_16x16x32_bf16 v[94:97], v[176:179], v[246:249], v[66:69]
	v_mfma_f32_16x16x32_bf16 v[66:69], v[192:195], v[242:245], v[86:89]
	v_mfma_f32_16x16x32_bf16 v[90:93], v[196:199], v[246:249], v[66:69]
	v_mfma_f32_16x16x32_bf16 v[66:69], v[172:175], v[250:253], v[230:233]
	v_mfma_f32_16x16x32_bf16 v[78:81], v[176:179], v[208:211], v[66:69]
	v_mfma_f32_16x16x32_bf16 v[66:69], v[192:195], v[250:253], v[234:237]
	v_mfma_f32_16x16x32_bf16 v[74:77], v[196:199], v[208:211], v[66:69]
	s_setprio 0
	s_setprio 1
	v_mfma_f32_16x16x32_bf16 v[66:69], v[200:203], v[10:13], v[98:101]
	v_mfma_f32_16x16x32_bf16 v[10:13], v[226:229], v[10:13], v[102:105]
	v_mfma_f32_16x16x32_bf16 v[114:117], v[238:241], v[26:29], v[10:13]
	v_mfma_f32_16x16x32_bf16 v[10:13], v[200:203], v[30:33], v[180:183]
	v_mfma_f32_16x16x32_bf16 v[102:105], v[212:215], v[62:65], v[10:13]
	v_mfma_f32_16x16x32_bf16 v[10:13], v[226:229], v[30:33], v[42:45]
	v_mfma_f32_16x16x32_bf16 v[98:101], v[238:241], v[62:65], v[10:13]
	v_mfma_f32_16x16x32_bf16 v[10:13], v[200:203], v[242:245], v[46:49]
	v_mfma_f32_16x16x32_bf16 v[86:89], v[212:215], v[246:249], v[10:13]
	v_mfma_f32_16x16x32_bf16 v[10:13], v[226:229], v[242:245], v[50:53]
	v_mfma_f32_16x16x32_bf16 v[82:85], v[238:241], v[246:249], v[10:13]
	v_mfma_f32_16x16x32_bf16 v[10:13], v[200:203], v[250:253], v[54:57]
	v_mfma_f32_16x16x32_bf16 v[70:73], v[212:215], v[208:211], v[10:13]
	v_mfma_f32_16x16x32_bf16 v[10:13], v[226:229], v[250:253], v[58:61]
	v_mfma_f32_16x16x32_bf16 v[118:121], v[212:215], v[26:29], v[66:69]
	v_mfma_f32_16x16x32_bf16 v[66:69], v[238:241], v[208:211], v[10:13]
	s_setprio 0
	s_barrier
	s_mov_b32 m0, s79
	s_nop 2
	v_lshl_add_u64 v[10:11], v[152:153], 0, s[42:43]
	s_add_u32 s4, s20, 0x18080
	ds_read_b128 v[50:53], v155 offset:49152
	ds_read_b128 v[180:183], v155 offset:50176
	ds_read_b128 v[208:211], v155 offset:51200
	ds_read_b128 v[230:233], v155 offset:52224
	ds_read_b128 v[234:237], v155 offset:53248
	ds_read_b128 v[242:245], v155 offset:54272
	ds_read_b128 v[246:249], v155 offset:55296
	ds_read_b128 v[250:253], v155 offset:56320
	global_load_lds_dwordx4 v[10:11], off
	v_lshl_add_u64 v[10:11], v[216:217], 0, s[42:43]
	s_mov_b32 m0, s71
	s_addc_u32 s5, s21, 0
	global_load_lds_dwordx4 v[10:11], off
	s_mov_b32 m0, s72
	s_nop 0
	global_load_lds_dwordx4 v134, s[4:5]
	s_mov_b32 m0, s78
	s_nop 0
	global_load_lds_dwordx4 v130, s[4:5]
	v_lshl_add_u64 v[10:11], v[204:205], 0, s[42:43]
	s_mov_b32 m0, s40
	s_nop 0
	global_load_lds_dwordx4 v[10:11], off
	v_lshl_add_u64 v[10:11], v[206:207], 0, s[42:43]
	s_mov_b32 m0, s41
	s_nop 0
	global_load_lds_dwordx4 v[10:11], off
	s_waitcnt vmcnt(8)
	s_waitcnt lgkmcnt(0)
	s_setprio 1
	s_waitcnt lgkmcnt(0)
	v_mfma_f32_16x16x32_bf16 v[2:5], v[172:175], v[50:53], v[2:5]
	v_mfma_f32_16x16x32_bf16 v[62:65], v[176:179], v[180:183], v[2:5]
	v_mfma_f32_16x16x32_bf16 v[2:5], v[192:195], v[50:53], v[6:9]
	v_mfma_f32_16x16x32_bf16 v[58:61], v[196:199], v[180:183], v[2:5]
	s_barrier
	v_mfma_f32_16x16x32_bf16 v[2:5], v[172:175], v[208:211], v[156:159]
	v_mfma_f32_16x16x32_bf16 v[46:49], v[176:179], v[230:233], v[2:5]
	v_mfma_f32_16x16x32_bf16 v[2:5], v[192:195], v[208:211], v[160:163]
	v_mfma_f32_16x16x32_bf16 v[42:45], v[196:199], v[230:233], v[2:5]
	v_mfma_f32_16x16x32_bf16 v[2:5], v[172:175], v[234:237], v[164:167]
	v_mfma_f32_16x16x32_bf16 v[30:33], v[176:179], v[242:245], v[2:5]
	v_mfma_f32_16x16x32_bf16 v[2:5], v[192:195], v[234:237], v[168:171]
	v_mfma_f32_16x16x32_bf16 v[26:29], v[196:199], v[242:245], v[2:5]
	v_mfma_f32_16x16x32_bf16 v[2:5], v[172:175], v[246:249], v[14:17]
	v_mfma_f32_16x16x32_bf16 v[14:17], v[176:179], v[250:253], v[2:5]
	v_mfma_f32_16x16x32_bf16 v[2:5], v[192:195], v[246:249], v[18:21]
	v_mfma_f32_16x16x32_bf16 v[10:13], v[196:199], v[250:253], v[2:5]
	s_setprio 0
	s_setprio 1
	v_mfma_f32_16x16x32_bf16 v[2:5], v[200:203], v[50:53], v[22:25]
	v_mfma_f32_16x16x32_bf16 v[54:57], v[212:215], v[180:183], v[2:5]
	v_mfma_f32_16x16x32_bf16 v[2:5], v[226:229], v[50:53], v[34:37]
	v_mfma_f32_16x16x32_bf16 v[50:53], v[238:241], v[180:183], v[2:5]
	v_mfma_f32_16x16x32_bf16 v[2:5], v[200:203], v[208:211], v[38:41]
	v_mfma_f32_16x16x32_bf16 v[38:41], v[212:215], v[230:233], v[2:5]
	v_mfma_f32_16x16x32_bf16 v[2:5], v[226:229], v[208:211], v[138:141]
	v_mfma_f32_16x16x32_bf16 v[34:37], v[238:241], v[230:233], v[2:5]
	v_mfma_f32_16x16x32_bf16 v[2:5], v[200:203], v[234:237], v[184:187]
	v_mfma_f32_16x16x32_bf16 v[22:25], v[212:215], v[242:245], v[2:5]
	v_mfma_f32_16x16x32_bf16 v[2:5], v[226:229], v[234:237], v[188:191]
	v_mfma_f32_16x16x32_bf16 v[18:21], v[238:241], v[242:245], v[2:5]
	v_mfma_f32_16x16x32_bf16 v[2:5], v[200:203], v[246:249], v[142:145]
	v_mfma_f32_16x16x32_bf16 v[6:9], v[212:215], v[250:253], v[2:5]
	v_mfma_f32_16x16x32_bf16 v[2:5], v[226:229], v[246:249], v[146:149]
	v_mfma_f32_16x16x32_bf16 v[2:5], v[238:241], v[250:253], v[2:5]
	s_setprio 0
	s_barrier
	s_andn2_b64 vcc, exec, s[14:15]
	s_cbranch_vccnz .LBB0_311
	s_barrier

; #define PG8_STAGE(bufoff, gbase, voff) do { _Pragma("unroll") for (int _i = 0; _i < 2; ++_i) \
;         __builtin_amdgcn_global_load_lds((const unsigned*)((const char*)(gbase) + (voff)[_i]), (LAS unsigned*)(lds + (bufoff) + ldsw + _i * 8192), 16, 0, 0); } while (0)
; #define PG8_LDA(dst, b, h) do { _Pragma("unroll") for (int m = 0; m < 4; ++m) _Pragma("unroll") for (int k = 0; k < 2; ++k) dst[m][k] = *(const LAS bf16x8*)(lds + PG8_SA(b, h) + aoff + m * 2048 + k * 1024); } while (0)
; #define PG8_LDB(dst, b, h) do { _Pragma("unroll") for (int n = 0; n < 2; ++n) _Pragma("unroll") for (int k = 0; k < 2; ++k) dst[n][k] = *(const LAS bf16x8*)(lds + PG8_SB(b, h) + boff + n * 2048 + k * 1024); } while (0)
; #define PG8_MMA(ai, bj, At, Bt) do { __builtin_amdgcn_s_setprio(1); _Pragma("unroll") for (int m = 0; m < 4; ++m) _Pragma("unroll") for (int n = 0; n < 2; ++n) _Pragma("unroll") for (int k = 0; k < 2; ++k) \
;         acc[ai][bj][m][n] = __builtin_amdgcn_mfma_f32_16x16x32_bf16(Bt[n][k], At[m][k], acc[ai][bj][m][n], 0, 0, 0); __builtin_amdgcn_s_setprio(0); } while (0)
; #define PG8_BAR __builtin_amdgcn_s_barrier()
; template <class Epi>
; __device__ __forceinline__ void gemm_phase(LAS unsigned char* lds, const Gemm g, const StaticOrder& S, const Epi& E, int wave_s) {
;     ...
;         const bool has_next = S.next(ui + 1, nxt);
;         const char* nA = has_next ? (const char*)g.A + (size_t)nxt.pm * tstepA : cA; const char* nB = has_next ? (const char*)g.Bt + (size_t)nxt.pn * tstepB : cB;
;         for (int t = 0; t < nt; t += 2) {
;             const bool last = (t == nt - 2);
;             const char* a1 = cA + (size_t)(t + 1) * kstep;
;             const char* a2 = last ? nA : cA + (size_t)(t + 2) * kstep; const char* b2 = last ? nB : cB + (size_t)(t + 2) * kstep;
;             const char* a3 = a2 + kstep; const char* b3 = b2 + kstep;
;             PG8_LDB(B0, 0, 0); PG8_LDB(B1, 0, 1); PG8_SCHED; PG8_LDA(At, 0, 0); PG8_STAGE(PG8_SA(1, 1), a1 + hstepA, voffA);
;             PG8_WAIT_V(8); PG8_WAIT_L(0); PG8_BAR; PG8_MMA(0, 0, At, B0); PG8_MMA(0, 1, At, B1); PG8_BAR; PG8_SCHED;
;             PG8_LDA(At, 0, 1); PG8_STAGE(PG8_SB(0, 0), b2, voffB); PG8_STAGE(PG8_SB(0, 1), b2 + hstepB, voffB); PG8_STAGE(PG8_SA(0, 0), a2, voffA);
;             PG8_WAIT_V(8); PG8_WAIT_L(0); PG8_BAR; PG8_MMA(1, 0, At, B0); PG8_MMA(1, 1, At, B1); PG8_BAR; PG8_SCHED;
.LBB0_329:
	s_ashr_i32 s17, s16, 31
	s_lshl_b64 s[20:21], s[16:17], 17
	s_add_u32 s20, s28, s20
	s_addc_u32 s21, s29, s21
	s_and_b64 s[4:5], s[4:5], exec
	s_cselect_b32 s5, s21, s25
	s_cselect_b32 s4, s20, s24
	s_add_i32 s70, 0, 0x10000
	s_add_i32 s71, 0, 0x14000
	v_add_u32_e32 v212, s70, v144
	v_add_u32_e32 v213, s71, v144
	ds_read_b128 v[2:5], v212
	ds_read_b128 v[6:9], v212 offset:1024
	ds_read_b128 v[10:13], v212 offset:2048
	ds_read_b128 v[14:17], v212 offset:3072
	ds_read_b128 v[18:21], v213
	ds_read_b128 v[22:25], v213 offset:1024
	ds_read_b128 v[26:29], v213 offset:2048
	ds_read_b128 v[30:33], v213 offset:3072
	s_add_u32 s66, s22, 0x110080
	s_addc_u32 s67, s23, 0
	s_add_i32 s72, s31, 0xc000
	s_mov_b32 m0, s72
	s_add_i32 s17, s31, 0xe000
	ds_read_b128 v[34:37], v145
	ds_read_b128 v[38:41], v145 offset:1024
	ds_read_b128 v[42:45], v145 offset:2048
	ds_read_b128 v[46:49], v145 offset:3072
	ds_read_b128 v[50:53], v145 offset:4096
	ds_read_b128 v[54:57], v145 offset:5120
	ds_read_b128 v[58:61], v145 offset:6144
	ds_read_b128 v[62:65], v145 offset:7168
	global_load_lds_dwordx4 v134, s[66:67]
	v_lshl_add_u64 v[66:67], s[66:67], 0, v[132:133]
	s_mov_b32 m0, s17
	s_nop 0
	global_load_lds_dwordx4 v[66:67], off
	s_waitcnt vmcnt(8)
	s_waitcnt lgkmcnt(0)
	s_setprio 1
	s_waitcnt lgkmcnt(0)
	v_mfma_f32_16x16x32_bf16 v[66:69], v[2:5], v[34:37], 0
	v_mfma_f32_16x16x32_bf16 v[70:73], v[10:13], v[34:37], 0
	v_mfma_f32_16x16x32_bf16 v[74:77], v[2:5], v[42:45], 0
	v_mfma_f32_16x16x32_bf16 v[78:81], v[10:13], v[42:45], 0
	s_barrier
	v_mfma_f32_16x16x32_bf16 v[82:85], v[2:5], v[50:53], 0
	v_mfma_f32_16x16x32_bf16 v[86:89], v[10:13], v[50:53], 0
	v_mfma_f32_16x16x32_bf16 v[90:93], v[2:5], v[58:61], 0
	v_mfma_f32_16x16x32_bf16 v[94:97], v[10:13], v[58:61], 0
	v_mfma_f32_16x16x32_bf16 v[66:69], v[6:9], v[38:41], v[66:69]
	v_mfma_f32_16x16x32_bf16 v[70:73], v[14:17], v[38:41], v[70:73]
	v_mfma_f32_16x16x32_bf16 v[74:77], v[6:9], v[46:49], v[74:77]
	v_mfma_f32_16x16x32_bf16 v[78:81], v[14:17], v[46:49], v[78:81]
	v_mfma_f32_16x16x32_bf16 v[82:85], v[6:9], v[54:57], v[82:85]
	v_mfma_f32_16x16x32_bf16 v[86:89], v[14:17], v[54:57], v[86:89]
	v_mfma_f32_16x16x32_bf16 v[90:93], v[6:9], v[62:65], v[90:93]
	v_mfma_f32_16x16x32_bf16 v[94:97], v[14:17], v[62:65], v[94:97]
	s_setprio 0
	s_setprio 1
	v_mfma_f32_16x16x32_bf16 v[98:101], v[18:21], v[34:37], 0
	v_mfma_f32_16x16x32_bf16 v[34:37], v[26:29], v[34:37], 0
	v_mfma_f32_16x16x32_bf16 v[98:101], v[22:25], v[38:41], v[98:101]
	v_mfma_f32_16x16x32_bf16 v[34:37], v[30:33], v[38:41], v[34:37]
	v_mfma_f32_16x16x32_bf16 v[38:41], v[18:21], v[42:45], 0
	v_mfma_f32_16x16x32_bf16 v[42:45], v[26:29], v[42:45], 0
	v_mfma_f32_16x16x32_bf16 v[38:41], v[22:25], v[46:49], v[38:41]
	v_mfma_f32_16x16x32_bf16 v[42:45], v[30:33], v[46:49], v[42:45]
	v_mfma_f32_16x16x32_bf16 v[46:49], v[18:21], v[50:53], 0
	v_mfma_f32_16x16x32_bf16 v[50:53], v[26:29], v[50:53], 0
	v_mfma_f32_16x16x32_bf16 v[46:49], v[22:25], v[54:57], v[46:49]
	v_mfma_f32_16x16x32_bf16 v[50:53], v[30:33], v[54:57], v[50:53]
	v_mfma_f32_16x16x32_bf16 v[54:57], v[18:21], v[58:61], 0
	v_mfma_f32_16x16x32_bf16 v[58:61], v[26:29], v[58:61], 0
	v_mfma_f32_16x16x32_bf16 v[54:57], v[22:25], v[62:65], v[54:57]
	v_mfma_f32_16x16x32_bf16 v[58:61], v[30:33], v[62:65], v[58:61]
	s_setprio 0
	s_barrier
	s_add_i32 s70, s70, s30
	v_lshl_add_u64 v[202:203], s[24:25], 0, v[0:1]
	s_mov_b64 s[82:83], 0x100
	s_add_i32 s65, s70, 0x2000
	v_lshl_add_u64 v[136:137], v[202:203], 0, s[82:83]
	s_mov_b32 m0, s70
	v_lshl_add_u64 v[204:205], s[24:25], 0, v[130:131]
	s_add_u32 s78, s24, 0x10100
	ds_read_b128 v[62:65], v145 offset:16384
	ds_read_b128 v[102:105], v145 offset:17408
	ds_read_b128 v[106:109], v145 offset:18432
	ds_read_b128 v[110:113], v145 offset:19456
	ds_read_b128 v[114:117], v145 offset:20480
	ds_read_b128 v[118:121], v145 offset:21504
	ds_read_b128 v[122:125], v145 offset:22528
	ds_read_b128 v[126:129], v145 offset:23552
	global_load_lds_dwordx4 v[136:137], off
	v_lshl_add_u64 v[136:137], v[204:205], 0, s[82:83]
	s_mov_b32 m0, s65
	s_addc_u32 s79, s25, 0
	s_add_i32 s66, s71, s30
	global_load_lds_dwordx4 v[136:137], off
	s_mov_b32 m0, s66
	s_add_i32 s67, s66, 0x2000
	global_load_lds_dwordx4 v0, s[78:79]
	s_mov_b32 m0, s67
	v_lshl_add_u64 v[206:207], s[22:23], 0, v[134:135]
	global_load_lds_dwordx4 v130, s[78:79]
	v_lshl_add_u64 v[136:137], v[206:207], 0, s[82:83]
	s_mov_b32 m0, s31
	v_lshl_add_u64 v[208:209], s[22:23], 0, v[132:133]
	global_load_lds_dwordx4 v[136:137], off
	v_lshl_add_u64 v[136:137], v[208:209], 0, s[82:83]
	s_mov_b32 m0, s34
	s_nop 0
	global_load_lds_dwordx4 v[136:137], off
	s_waitcnt vmcnt(8)
	s_waitcnt lgkmcnt(0)
	s_setprio 1
	s_waitcnt lgkmcnt(0)
	v_mfma_f32_16x16x32_bf16 v[136:139], v[2:5], v[62:65], 0
	v_mfma_f32_16x16x32_bf16 v[146:149], v[2:5], v[106:109], 0
	v_mfma_f32_16x16x32_bf16 v[154:157], v[2:5], v[114:117], 0
	v_mfma_f32_16x16x32_bf16 v[2:5], v[2:5], v[122:125], 0
	s_barrier
; #define PG8_STAGE(bufoff, gbase, voff) do { _Pragma("unroll") for (int _i = 0; _i < 2; ++_i) \
;         __builtin_amdgcn_global_load_lds((const unsigned*)((const char*)(gbase) + (voff)[_i]), (LAS unsigned*)(lds + (bufoff) + ldsw + _i * 8192), 16, 0, 0); } while (0)
; #define PG8_LDA(dst, b, h) do { _Pragma("unroll") for (int m = 0; m < 4; ++m) _Pragma("unroll") for (int k = 0; k < 2; ++k) dst[m][k] = *(const LAS bf16x8*)(lds + PG8_SA(b, h) + aoff + m * 2048 + k * 1024); } while (0)
; #define PG8_LDB(dst, b, h) do { _Pragma("unroll") for (int n = 0; n < 2; ++n) _Pragma("unroll") for (int k = 0; k < 2; ++k) dst[n][k] = *(const LAS bf16x8*)(lds + PG8_SB(b, h) + boff + n * 2048 + k * 1024); } while (0)
; #define PG8_MMA(ai, bj, At, Bt) do { __builtin_amdgcn_s_setprio(1); _Pragma("unroll") for (int m = 0; m < 4; ++m) _Pragma("unroll") for (int n = 0; n < 2; ++n) _Pragma("unroll") for (int k = 0; k < 2; ++k) \
;         acc[ai][bj][m][n] = __builtin_amdgcn_mfma_f32_16x16x32_bf16(Bt[n][k], At[m][k], acc[ai][bj][m][n], 0, 0, 0); __builtin_amdgcn_s_setprio(0); } while (0)
; #define PG8_WAIT_V(n) asm volatile("s_waitcnt vmcnt(" #n ")" ::: "memory")
; #define PG8_WAIT_L(n) asm volatile("s_waitcnt lgkmcnt(" #n ")" ::: "memory")
; #define PG8_BAR __builtin_amdgcn_s_barrier()
; #define PG8_SCHED __builtin_amdgcn_sched_barrier(0)
; template <class Epi>
; __device__ __forceinline__ void gemm_phase(LAS unsigned char* lds, const Gemm g, const StaticOrder& S, const Epi& E, int wave_s) {
;     ...
;             PG8_WAIT_V(8); PG8_WAIT_L(0); PG8_BAR; PG8_MMA(0, 0, At, B0); PG8_MMA(0, 1, At, B1); PG8_BAR; PG8_SCHED;
;             PG8_LDA(At, 0, 1); PG8_STAGE(PG8_SB(0, 0), b2, voffB); PG8_STAGE(PG8_SB(0, 1), b2 + hstepB, voffB); PG8_STAGE(PG8_SA(0, 0), a2, voffA);
;             PG8_WAIT_V(8); PG8_WAIT_L(0); PG8_BAR; PG8_MMA(1, 0, At, B0); PG8_MMA(1, 1, At, B1); PG8_BAR; PG8_SCHED;
;             PG8_LDB(B0, 1, 0); PG8_LDB(B1, 1, 1); PG8_SCHED; PG8_LDA(At, 1, 0); PG8_STAGE(PG8_SA(0, 1), a2 + hstepA, voffA);
;             PG8_WAIT_V(8); PG8_WAIT_L(0); PG8_BAR; PG8_MMA(0, 0, At, B0); PG8_MMA(0, 1, At, B1); PG8_BAR; PG8_SCHED;
	v_mfma_f32_16x16x32_bf16 v[136:139], v[6:9], v[102:105], v[136:139]
	v_mfma_f32_16x16x32_bf16 v[146:149], v[6:9], v[110:113], v[146:149]
	v_mfma_f32_16x16x32_bf16 v[154:157], v[6:9], v[118:121], v[154:157]
	v_mfma_f32_16x16x32_bf16 v[2:5], v[6:9], v[126:129], v[2:5]
	v_mfma_f32_16x16x32_bf16 v[6:9], v[10:13], v[122:125], 0
	v_mfma_f32_16x16x32_bf16 v[140:143], v[10:13], v[62:65], 0
	v_mfma_f32_16x16x32_bf16 v[150:153], v[10:13], v[106:109], 0
	v_mfma_f32_16x16x32_bf16 v[158:161], v[10:13], v[114:117], 0
	v_mfma_f32_16x16x32_bf16 v[6:9], v[14:17], v[126:129], v[6:9]
	v_mfma_f32_16x16x32_bf16 v[140:143], v[14:17], v[102:105], v[140:143]
	v_mfma_f32_16x16x32_bf16 v[150:153], v[14:17], v[110:113], v[150:153]
	v_mfma_f32_16x16x32_bf16 v[158:161], v[14:17], v[118:121], v[158:161]
	s_setprio 0
	s_setprio 1
	v_mfma_f32_16x16x32_bf16 v[10:13], v[18:21], v[62:65], 0
	v_mfma_f32_16x16x32_bf16 v[14:17], v[26:29], v[62:65], 0
	v_mfma_f32_16x16x32_bf16 v[10:13], v[22:25], v[102:105], v[10:13]
	v_mfma_f32_16x16x32_bf16 v[14:17], v[30:33], v[102:105], v[14:17]
	v_mfma_f32_16x16x32_bf16 v[62:65], v[18:21], v[106:109], 0
	v_mfma_f32_16x16x32_bf16 v[102:105], v[26:29], v[106:109], 0
	v_mfma_f32_16x16x32_bf16 v[106:109], v[18:21], v[114:117], 0
	v_mfma_f32_16x16x32_bf16 v[18:21], v[18:21], v[122:125], 0
	v_mfma_f32_16x16x32_bf16 v[62:65], v[22:25], v[110:113], v[62:65]
	v_mfma_f32_16x16x32_bf16 v[102:105], v[30:33], v[110:113], v[102:105]
	v_mfma_f32_16x16x32_bf16 v[106:109], v[22:25], v[118:121], v[106:109]
	v_mfma_f32_16x16x32_bf16 v[110:113], v[26:29], v[114:117], 0
	v_mfma_f32_16x16x32_bf16 v[18:21], v[22:25], v[126:129], v[18:21]
	v_mfma_f32_16x16x32_bf16 v[22:25], v[26:29], v[122:125], 0
	v_mfma_f32_16x16x32_bf16 v[110:113], v[30:33], v[118:121], v[110:113]
	v_mfma_f32_16x16x32_bf16 v[22:25], v[30:33], v[126:129], v[22:25]
	s_setprio 0
	s_barrier
	s_add_i32 s73, 0, 0x18000
	s_add_i32 s82, 0, 0x1c000
	v_add_u32_e32 v225, s73, v144
	v_add_u32_e32 v226, s82, v144
	ds_read_b128 v[26:29], v225
	ds_read_b128 v[30:33], v225 offset:1024
	ds_read_b128 v[114:117], v225 offset:2048
	ds_read_b128 v[118:121], v225 offset:3072
	ds_read_b128 v[122:125], v226
	ds_read_b128 v[126:129], v226 offset:1024
	ds_read_b128 v[162:165], v226 offset:2048
	ds_read_b128 v[166:169], v226 offset:3072
	s_add_u32 s78, s22, 0x110100
	s_addc_u32 s79, s23, 0
	s_mov_b32 m0, s35
	ds_read_b128 v[170:173], v145 offset:32768
	ds_read_b128 v[174:177], v145 offset:33792
	ds_read_b128 v[178:181], v145 offset:34816
	ds_read_b128 v[182:185], v145 offset:35840
	ds_read_b128 v[186:189], v145 offset:36864
	ds_read_b128 v[190:193], v145 offset:37888
	ds_read_b128 v[194:197], v145 offset:38912
	ds_read_b128 v[198:201], v145 offset:39936
	global_load_lds_dwordx4 v134, s[78:79]
	v_lshl_add_u64 v[210:211], s[78:79], 0, v[132:133]
	s_mov_b32 m0, s37
	s_nop 0
	global_load_lds_dwordx4 v[210:211], off
	s_waitcnt vmcnt(8)
	s_waitcnt lgkmcnt(0)
	s_setprio 1
	s_waitcnt lgkmcnt(0)
	v_mfma_f32_16x16x32_bf16 v[66:69], v[26:29], v[170:173], v[66:69]
	v_mfma_f32_16x16x32_bf16 v[70:73], v[114:117], v[170:173], v[70:73]
	v_mfma_f32_16x16x32_bf16 v[74:77], v[26:29], v[178:181], v[74:77]
	v_mfma_f32_16x16x32_bf16 v[78:81], v[114:117], v[178:181], v[78:81]
	s_barrier
	v_mfma_f32_16x16x32_bf16 v[82:85], v[26:29], v[186:189], v[82:85]
	v_mfma_f32_16x16x32_bf16 v[86:89], v[114:117], v[186:189], v[86:89]
	v_mfma_f32_16x16x32_bf16 v[90:93], v[26:29], v[194:197], v[90:93]
	v_mfma_f32_16x16x32_bf16 v[94:97], v[114:117], v[194:197], v[94:97]
	v_mfma_f32_16x16x32_bf16 v[66:69], v[30:33], v[174:177], v[66:69]
	v_mfma_f32_16x16x32_bf16 v[70:73], v[118:121], v[174:177], v[70:73]
	v_mfma_f32_16x16x32_bf16 v[74:77], v[30:33], v[182:185], v[74:77]
	v_mfma_f32_16x16x32_bf16 v[78:81], v[118:121], v[182:185], v[78:81]
	v_mfma_f32_16x16x32_bf16 v[82:85], v[30:33], v[190:193], v[82:85]
	v_mfma_f32_16x16x32_bf16 v[86:89], v[118:121], v[190:193], v[86:89]
	v_mfma_f32_16x16x32_bf16 v[90:93], v[30:33], v[198:201], v[90:93]
	v_mfma_f32_16x16x32_bf16 v[94:97], v[118:121], v[198:201], v[94:97]
	s_setprio 0
	s_setprio 1
	v_mfma_f32_16x16x32_bf16 v[98:101], v[122:125], v[170:173], v[98:101]
	v_mfma_f32_16x16x32_bf16 v[34:37], v[162:165], v[170:173], v[34:37]
	v_mfma_f32_16x16x32_bf16 v[38:41], v[122:125], v[178:181], v[38:41]
	v_mfma_f32_16x16x32_bf16 v[42:45], v[162:165], v[178:181], v[42:45]
	v_mfma_f32_16x16x32_bf16 v[46:49], v[122:125], v[186:189], v[46:49]
	v_mfma_f32_16x16x32_bf16 v[50:53], v[162:165], v[186:189], v[50:53]
	v_mfma_f32_16x16x32_bf16 v[54:57], v[122:125], v[194:197], v[54:57]
	v_mfma_f32_16x16x32_bf16 v[58:61], v[162:165], v[194:197], v[58:61]
	v_mfma_f32_16x16x32_bf16 v[98:101], v[126:129], v[174:177], v[98:101]
	v_mfma_f32_16x16x32_bf16 v[34:37], v[166:169], v[174:177], v[34:37]
	v_mfma_f32_16x16x32_bf16 v[38:41], v[126:129], v[182:185], v[38:41]
	v_mfma_f32_16x16x32_bf16 v[42:45], v[166:169], v[182:185], v[42:45]
	v_mfma_f32_16x16x32_bf16 v[46:49], v[126:129], v[190:193], v[46:49]
	v_mfma_f32_16x16x32_bf16 v[50:53], v[166:169], v[190:193], v[50:53]
	v_mfma_f32_16x16x32_bf16 v[54:57], v[126:129], v[198:201], v[54:57]
	v_mfma_f32_16x16x32_bf16 v[58:61], v[166:169], v[198:201], v[58:61]
	s_setprio 0
	s_barrier
; #define PG8_STAGE(bufoff, gbase, voff) do { _Pragma("unroll") for (int _i = 0; _i < 2; ++_i) \
;         __builtin_amdgcn_global_load_lds((const unsigned*)((const char*)(gbase) + (voff)[_i]), (LAS unsigned*)(lds + (bufoff) + ldsw + _i * 8192), 16, 0, 0); } while (0)
; #define PG8_LDA(dst, b, h) do { _Pragma("unroll") for (int m = 0; m < 4; ++m) _Pragma("unroll") for (int k = 0; k < 2; ++k) dst[m][k] = *(const LAS bf16x8*)(lds + PG8_SA(b, h) + aoff + m * 2048 + k * 1024); } while (0)
; #define PG8_LDB(dst, b, h) do { _Pragma("unroll") for (int n = 0; n < 2; ++n) _Pragma("unroll") for (int k = 0; k < 2; ++k) dst[n][k] = *(const LAS bf16x8*)(lds + PG8_SB(b, h) + boff + n * 2048 + k * 1024); } while (0)
; #define PG8_MMA(ai, bj, At, Bt) do { __builtin_amdgcn_s_setprio(1); _Pragma("unroll") for (int m = 0; m < 4; ++m) _Pragma("unroll") for (int n = 0; n < 2; ++n) _Pragma("unroll") for (int k = 0; k < 2; ++k) \
;         acc[ai][bj][m][n] = __builtin_amdgcn_mfma_f32_16x16x32_bf16(Bt[n][k], At[m][k], acc[ai][bj][m][n], 0, 0, 0); __builtin_amdgcn_s_setprio(0); } while (0)
; #define PG8_WAIT_V(n) asm volatile("s_waitcnt vmcnt(" #n ")" ::: "memory")
; #define PG8_BAR __builtin_amdgcn_s_barrier()
; template <class Epi>
; __device__ __forceinline__ void gemm_phase(LAS unsigned char* lds, const Gemm g, const StaticOrder& S, const Epi& E, int wave_s) {
;     ...
;             PG8_LDB(B0, 0, 0); PG8_LDB(B1, 0, 1); PG8_SCHED; PG8_LDA(At, 0, 0); PG8_STAGE(PG8_SA(1, 1), a1 + hstepA, voffA);
;             PG8_WAIT_V(8); PG8_WAIT_L(0); PG8_BAR; PG8_MMA(0, 0, At, B0); PG8_MMA(0, 1, At, B1); PG8_BAR; PG8_SCHED;
;             PG8_LDA(At, 0, 1); PG8_STAGE(PG8_SB(0, 0), b2, voffB); PG8_STAGE(PG8_SB(0, 1), b2 + hstepB, voffB); PG8_STAGE(PG8_SA(0, 0), a2, voffA);
;             PG8_WAIT_V(8); PG8_WAIT_L(0); PG8_BAR; PG8_MMA(1, 0, At, B0); PG8_MMA(1, 1, At, B1); PG8_BAR; PG8_SCHED;
;             PG8_LDB(B0, 1, 0); PG8_LDB(B1, 1, 1); PG8_SCHED; PG8_LDA(At, 1, 0); PG8_STAGE(PG8_SA(0, 1), a2 + hstepA, voffA);
;             PG8_WAIT_V(8); PG8_WAIT_L(0); PG8_BAR; PG8_MMA(0, 0, At, B0); PG8_MMA(0, 1, At, B1); PG8_BAR; PG8_SCHED;
;             PG8_LDA(At, 1, 1); PG8_STAGE(PG8_SB(1, 0), b3, voffB); PG8_STAGE(PG8_SB(1, 1), b3 + hstepB, voffB); PG8_STAGE(PG8_SA(1, 0), a3, voffA);
;             PG8_WAIT_V(8); PG8_WAIT_L(0); PG8_BAR; PG8_MMA(1, 0, At, B0); PG8_MMA(1, 1, At, B1); PG8_BAR; PG8_SCHED;
	s_add_i32 s73, s73, s30
	s_mov_b64 s[88:89], 0x180
	s_add_i32 s71, s73, 0x2000
	v_lshl_add_u64 v[202:203], v[202:203], 0, s[88:89]
	s_mov_b32 m0, s73
	s_add_u32 s78, s24, 0x10180
	ds_read_b128 v[170:173], v145 offset:49152
	ds_read_b128 v[174:177], v145 offset:50176
	ds_read_b128 v[178:181], v145 offset:51200
	ds_read_b128 v[182:185], v145 offset:52224
	ds_read_b128 v[186:189], v145 offset:53248
	ds_read_b128 v[190:193], v145 offset:54272
	ds_read_b128 v[194:197], v145 offset:55296
	ds_read_b128 v[198:201], v145 offset:56320
	global_load_lds_dwordx4 v[202:203], off
	v_lshl_add_u64 v[202:203], v[204:205], 0, s[88:89]
	s_mov_b32 m0, s71
	s_addc_u32 s79, s25, 0
	s_add_i32 s24, s82, s30
	global_load_lds_dwordx4 v[202:203], off
	s_mov_b32 m0, s24
	s_add_i32 s25, s24, 0x2000
	global_load_lds_dwordx4 v0, s[78:79]
	s_mov_b32 m0, s25
	s_nop 0
	global_load_lds_dwordx4 v130, s[78:79]
	v_lshl_add_u64 v[202:203], v[206:207], 0, s[88:89]
	s_mov_b32 m0, s40
	s_nop 0
	global_load_lds_dwordx4 v[202:203], off
	v_lshl_add_u64 v[202:203], v[208:209], 0, s[88:89]
	s_mov_b32 m0, s41
	s_nop 0
	global_load_lds_dwordx4 v[202:203], off
	s_waitcnt vmcnt(8)
	s_waitcnt lgkmcnt(0)
	s_setprio 1
	s_waitcnt lgkmcnt(0)
	v_mfma_f32_16x16x32_bf16 v[2:5], v[26:29], v[194:197], v[2:5]
	v_mfma_f32_16x16x32_bf16 v[6:9], v[114:117], v[194:197], v[6:9]
	v_mfma_f32_16x16x32_bf16 v[136:139], v[26:29], v[170:173], v[136:139]
	v_mfma_f32_16x16x32_bf16 v[140:143], v[114:117], v[170:173], v[140:143]
	s_barrier
	v_mfma_f32_16x16x32_bf16 v[146:149], v[26:29], v[178:181], v[146:149]
	v_mfma_f32_16x16x32_bf16 v[150:153], v[114:117], v[178:181], v[150:153]
	v_mfma_f32_16x16x32_bf16 v[154:157], v[26:29], v[186:189], v[154:157]
	v_mfma_f32_16x16x32_bf16 v[158:161], v[114:117], v[186:189], v[158:161]
	v_mfma_f32_16x16x32_bf16 v[2:5], v[30:33], v[198:201], v[2:5]
	v_mfma_f32_16x16x32_bf16 v[6:9], v[118:121], v[198:201], v[6:9]
	v_mfma_f32_16x16x32_bf16 v[136:139], v[30:33], v[174:177], v[136:139]
	v_mfma_f32_16x16x32_bf16 v[140:143], v[118:121], v[174:177], v[140:143]
	v_mfma_f32_16x16x32_bf16 v[146:149], v[30:33], v[182:185], v[146:149]
	v_mfma_f32_16x16x32_bf16 v[150:153], v[118:121], v[182:185], v[150:153]
	v_mfma_f32_16x16x32_bf16 v[154:157], v[30:33], v[190:193], v[154:157]
	v_mfma_f32_16x16x32_bf16 v[158:161], v[118:121], v[190:193], v[158:161]
	s_setprio 0
	s_setprio 1
	v_mfma_f32_16x16x32_bf16 v[10:13], v[122:125], v[170:173], v[10:13]
	v_mfma_f32_16x16x32_bf16 v[14:17], v[162:165], v[170:173], v[14:17]
	v_mfma_f32_16x16x32_bf16 v[26:29], v[122:125], v[178:181], v[62:65]
	v_mfma_f32_16x16x32_bf16 v[30:33], v[162:165], v[178:181], v[102:105]
	v_mfma_f32_16x16x32_bf16 v[62:65], v[122:125], v[186:189], v[106:109]
	v_mfma_f32_16x16x32_bf16 v[102:105], v[162:165], v[186:189], v[110:113]
	v_mfma_f32_16x16x32_bf16 v[18:21], v[122:125], v[194:197], v[18:21]
	v_mfma_f32_16x16x32_bf16 v[22:25], v[162:165], v[194:197], v[22:25]
	v_mfma_f32_16x16x32_bf16 v[10:13], v[126:129], v[174:177], v[10:13]
	v_mfma_f32_16x16x32_bf16 v[14:17], v[166:169], v[174:177], v[14:17]
	v_mfma_f32_16x16x32_bf16 v[26:29], v[126:129], v[182:185], v[26:29]
	v_mfma_f32_16x16x32_bf16 v[30:33], v[166:169], v[182:185], v[30:33]
	v_mfma_f32_16x16x32_bf16 v[62:65], v[126:129], v[190:193], v[62:65]
	v_mfma_f32_16x16x32_bf16 v[102:105], v[166:169], v[190:193], v[102:105]
	v_mfma_f32_16x16x32_bf16 v[18:21], v[126:129], v[198:201], v[18:21]
	v_mfma_f32_16x16x32_bf16 v[22:25], v[166:169], v[198:201], v[22:25]
	s_setprio 0
	s_barrier
	ds_read_b128 v[106:109], v212
	ds_read_b128 v[110:113], v212 offset:1024
	ds_read_b128 v[114:117], v212 offset:2048
	ds_read_b128 v[118:121], v212 offset:3072
	ds_read_b128 v[122:125], v213
	ds_read_b128 v[126:129], v213 offset:1024
	ds_read_b128 v[162:165], v213 offset:2048
	ds_read_b128 v[166:169], v213 offset:3072
	s_add_u32 s22, s22, 0x110180
	s_addc_u32 s23, s23, 0
	s_mov_b32 m0, s72
	ds_read_b128 v[170:173], v145
	ds_read_b128 v[174:177], v145 offset:1024
	ds_read_b128 v[178:181], v145 offset:2048
	ds_read_b128 v[182:185], v145 offset:3072
	ds_read_b128 v[186:189], v145 offset:4096
	ds_read_b128 v[190:193], v145 offset:5120
	ds_read_b128 v[194:197], v145 offset:6144
	ds_read_b128 v[198:201], v145 offset:7168
	global_load_lds_dwordx4 v134, s[22:23]
	s_mov_b32 m0, s17
	s_nop 0
	global_load_lds_dwordx4 v132, s[22:23]
	s_waitcnt vmcnt(8)
	s_waitcnt lgkmcnt(0)
	s_setprio 1
	s_waitcnt lgkmcnt(0)
	v_mfma_f32_16x16x32_bf16 v[66:69], v[106:109], v[170:173], v[66:69]
	v_mfma_f32_16x16x32_bf16 v[70:73], v[114:117], v[170:173], v[70:73]
	v_mfma_f32_16x16x32_bf16 v[74:77], v[106:109], v[178:181], v[74:77]
	v_mfma_f32_16x16x32_bf16 v[78:81], v[114:117], v[178:181], v[78:81]
	s_barrier
; #define PG8_STAGE(bufoff, gbase, voff) do { _Pragma("unroll") for (int _i = 0; _i < 2; ++_i) \
;         __builtin_amdgcn_global_load_lds((const unsigned*)((const char*)(gbase) + (voff)[_i]), (LAS unsigned*)(lds + (bufoff) + ldsw + _i * 8192), 16, 0, 0); } while (0)
; #define PG8_LDA(dst, b, h) do { _Pragma("unroll") for (int m = 0; m < 4; ++m) _Pragma("unroll") for (int k = 0; k < 2; ++k) dst[m][k] = *(const LAS bf16x8*)(lds + PG8_SA(b, h) + aoff + m * 2048 + k * 1024); } while (0)
; #define PG8_LDB(dst, b, h) do { _Pragma("unroll") for (int n = 0; n < 2; ++n) _Pragma("unroll") for (int k = 0; k < 2; ++k) dst[n][k] = *(const LAS bf16x8*)(lds + PG8_SB(b, h) + boff + n * 2048 + k * 1024); } while (0)
; #define PG8_MMA(ai, bj, At, Bt) do { __builtin_amdgcn_s_setprio(1); _Pragma("unroll") for (int m = 0; m < 4; ++m) _Pragma("unroll") for (int n = 0; n < 2; ++n) _Pragma("unroll") for (int k = 0; k < 2; ++k) \
;         acc[ai][bj][m][n] = __builtin_amdgcn_mfma_f32_16x16x32_bf16(Bt[n][k], At[m][k], acc[ai][bj][m][n], 0, 0, 0); __builtin_amdgcn_s_setprio(0); } while (0)
; #define PG8_WAIT_V(n) asm volatile("s_waitcnt vmcnt(" #n ")" ::: "memory")
; #define PG8_WAIT_L(n) asm volatile("s_waitcnt lgkmcnt(" #n ")" ::: "memory")
; #define PG8_BAR __builtin_amdgcn_s_barrier()
; #define PG8_SCHED __builtin_amdgcn_sched_barrier(0)
; template <class Epi>
; __device__ __forceinline__ void gemm_phase(LAS unsigned char* lds, const Gemm g, const StaticOrder& S, const Epi& E, int wave_s) {
;     ...
;             PG8_LDB(B0, 0, 0); PG8_LDB(B1, 0, 1); PG8_SCHED; PG8_LDA(At, 0, 0); PG8_STAGE(PG8_SA(1, 1), a1 + hstepA, voffA);
;             PG8_WAIT_V(8); PG8_WAIT_L(0); PG8_BAR; PG8_MMA(0, 0, At, B0); PG8_MMA(0, 1, At, B1); PG8_BAR; PG8_SCHED;
;             PG8_LDA(At, 0, 1); PG8_STAGE(PG8_SB(0, 0), b2, voffB); PG8_STAGE(PG8_SB(0, 1), b2 + hstepB, voffB); PG8_STAGE(PG8_SA(0, 0), a2, voffA);
;             PG8_WAIT_V(8); PG8_WAIT_L(0); PG8_BAR; PG8_MMA(1, 0, At, B0); PG8_MMA(1, 1, At, B1); PG8_BAR; PG8_SCHED;
	v_mfma_f32_16x16x32_bf16 v[82:85], v[106:109], v[186:189], v[82:85]
	v_mfma_f32_16x16x32_bf16 v[86:89], v[114:117], v[186:189], v[86:89]
	v_mfma_f32_16x16x32_bf16 v[90:93], v[106:109], v[194:197], v[90:93]
	v_mfma_f32_16x16x32_bf16 v[94:97], v[114:117], v[194:197], v[94:97]
	v_mfma_f32_16x16x32_bf16 v[66:69], v[110:113], v[174:177], v[66:69]
	v_mfma_f32_16x16x32_bf16 v[70:73], v[118:121], v[174:177], v[70:73]
	v_mfma_f32_16x16x32_bf16 v[74:77], v[110:113], v[182:185], v[74:77]
	v_mfma_f32_16x16x32_bf16 v[78:81], v[118:121], v[182:185], v[78:81]
	v_mfma_f32_16x16x32_bf16 v[82:85], v[110:113], v[190:193], v[82:85]
	v_mfma_f32_16x16x32_bf16 v[86:89], v[118:121], v[190:193], v[86:89]
	v_mfma_f32_16x16x32_bf16 v[90:93], v[110:113], v[198:201], v[90:93]
	v_mfma_f32_16x16x32_bf16 v[94:97], v[118:121], v[198:201], v[94:97]
	s_setprio 0
	s_setprio 1
	v_mfma_f32_16x16x32_bf16 v[34:37], v[162:165], v[170:173], v[34:37]
	v_mfma_f32_16x16x32_bf16 v[38:41], v[122:125], v[178:181], v[38:41]
	v_mfma_f32_16x16x32_bf16 v[42:45], v[162:165], v[178:181], v[42:45]
	v_mfma_f32_16x16x32_bf16 v[46:49], v[122:125], v[186:189], v[46:49]
	v_mfma_f32_16x16x32_bf16 v[50:53], v[162:165], v[186:189], v[50:53]
	v_mfma_f32_16x16x32_bf16 v[54:57], v[122:125], v[194:197], v[54:57]
	v_mfma_f32_16x16x32_bf16 v[58:61], v[162:165], v[194:197], v[58:61]
	v_mfma_f32_16x16x32_bf16 v[98:101], v[122:125], v[170:173], v[98:101]
	v_mfma_f32_16x16x32_bf16 v[34:37], v[166:169], v[174:177], v[34:37]
	v_mfma_f32_16x16x32_bf16 v[38:41], v[126:129], v[182:185], v[38:41]
	v_mfma_f32_16x16x32_bf16 v[42:45], v[166:169], v[182:185], v[42:45]
	v_mfma_f32_16x16x32_bf16 v[46:49], v[126:129], v[190:193], v[46:49]
	v_mfma_f32_16x16x32_bf16 v[50:53], v[166:169], v[190:193], v[50:53]
	v_mfma_f32_16x16x32_bf16 v[54:57], v[126:129], v[198:201], v[54:57]
	v_mfma_f32_16x16x32_bf16 v[58:61], v[166:169], v[198:201], v[58:61]
	v_mfma_f32_16x16x32_bf16 v[208:211], v[126:129], v[174:177], v[98:101]
	s_setprio 0
	s_barrier
	s_mov_b32 m0, s70
	v_lshl_add_u64 v[202:203], s[4:5], 0, v[0:1]
	s_add_u32 s22, s4, 0x10000
	ds_read_b128 v[98:101], v145 offset:16384
	ds_read_b128 v[170:173], v145 offset:17408
	ds_read_b128 v[174:177], v145 offset:18432
	ds_read_b128 v[178:181], v145 offset:19456
	ds_read_b128 v[182:185], v145 offset:20480
	ds_read_b128 v[186:189], v145 offset:21504
	ds_read_b128 v[190:193], v145 offset:22528
	ds_read_b128 v[194:197], v145 offset:23552
	global_load_lds_dwordx4 v[202:203], off
	v_lshl_add_u64 v[204:205], s[4:5], 0, v[130:131]
	s_mov_b32 m0, s65
	s_addc_u32 s23, s5, 0
	global_load_lds_dwordx4 v[204:205], off
	s_mov_b32 m0, s66
	v_lshl_add_u64 v[206:207], s[18:19], 0, v[134:135]
	global_load_lds_dwordx4 v0, s[22:23]
	v_lshl_add_u64 v[198:199], s[22:23], 0, v[130:131]
	s_mov_b32 m0, s67
	v_lshl_add_u64 v[216:217], s[18:19], 0, v[132:133]
	global_load_lds_dwordx4 v[198:199], off
	s_mov_b32 m0, s31
	s_nop 0
	global_load_lds_dwordx4 v[206:207], off
	s_mov_b32 m0, s34
	s_nop 0
	global_load_lds_dwordx4 v[216:217], off
	s_waitcnt vmcnt(8)
	s_waitcnt lgkmcnt(0)
	s_setprio 1
	s_waitcnt lgkmcnt(0)
	v_mfma_f32_16x16x32_bf16 v[2:5], v[106:109], v[190:193], v[2:5]
	v_mfma_f32_16x16x32_bf16 v[6:9], v[114:117], v[190:193], v[6:9]
	v_mfma_f32_16x16x32_bf16 v[136:139], v[106:109], v[98:101], v[136:139]
	v_mfma_f32_16x16x32_bf16 v[140:143], v[114:117], v[98:101], v[140:143]
	s_barrier
	v_mfma_f32_16x16x32_bf16 v[146:149], v[106:109], v[174:177], v[146:149]
	v_mfma_f32_16x16x32_bf16 v[150:153], v[114:117], v[174:177], v[150:153]
	v_mfma_f32_16x16x32_bf16 v[154:157], v[106:109], v[182:185], v[154:157]
	v_mfma_f32_16x16x32_bf16 v[158:161], v[114:117], v[182:185], v[158:161]
	v_mfma_f32_16x16x32_bf16 v[2:5], v[110:113], v[194:197], v[2:5]
	v_mfma_f32_16x16x32_bf16 v[6:9], v[118:121], v[194:197], v[6:9]
	v_mfma_f32_16x16x32_bf16 v[136:139], v[110:113], v[170:173], v[136:139]
	v_mfma_f32_16x16x32_bf16 v[140:143], v[118:121], v[170:173], v[140:143]
	v_mfma_f32_16x16x32_bf16 v[146:149], v[110:113], v[178:181], v[146:149]
	v_mfma_f32_16x16x32_bf16 v[150:153], v[118:121], v[178:181], v[150:153]
	v_mfma_f32_16x16x32_bf16 v[154:157], v[110:113], v[186:189], v[154:157]
	v_mfma_f32_16x16x32_bf16 v[158:161], v[118:121], v[186:189], v[158:161]
	s_setprio 0
	s_setprio 1
	v_mfma_f32_16x16x32_bf16 v[10:13], v[122:125], v[98:101], v[10:13]
	v_mfma_f32_16x16x32_bf16 v[198:201], v[126:129], v[170:173], v[10:13]
	v_mfma_f32_16x16x32_bf16 v[10:13], v[162:165], v[98:101], v[14:17]
	v_mfma_f32_16x16x32_bf16 v[170:173], v[166:169], v[170:173], v[10:13]
	v_mfma_f32_16x16x32_bf16 v[10:13], v[122:125], v[174:177], v[26:29]
	v_mfma_f32_16x16x32_bf16 v[212:215], v[126:129], v[178:181], v[10:13]
	v_mfma_f32_16x16x32_bf16 v[10:13], v[162:165], v[174:177], v[30:33]
	v_mfma_f32_16x16x32_bf16 v[174:177], v[166:169], v[178:181], v[10:13]
	v_mfma_f32_16x16x32_bf16 v[10:13], v[122:125], v[182:185], v[62:65]
	v_mfma_f32_16x16x32_bf16 v[178:181], v[126:129], v[186:189], v[10:13]
	v_mfma_f32_16x16x32_bf16 v[10:13], v[162:165], v[182:185], v[102:105]
	v_mfma_f32_16x16x32_bf16 v[182:185], v[166:169], v[186:189], v[10:13]
	v_mfma_f32_16x16x32_bf16 v[10:13], v[122:125], v[190:193], v[18:21]
	v_mfma_f32_16x16x32_bf16 v[186:189], v[126:129], v[194:197], v[10:13]
	v_mfma_f32_16x16x32_bf16 v[10:13], v[162:165], v[190:193], v[22:25]
	v_mfma_f32_16x16x32_bf16 v[162:165], v[166:169], v[194:197], v[10:13]
	s_setprio 0
	s_barrier
; #define PG8_STAGE(bufoff, gbase, voff) do { _Pragma("unroll") for (int _i = 0; _i < 2; ++_i) \
;         __builtin_amdgcn_global_load_lds((const unsigned*)((const char*)(gbase) + (voff)[_i]), (LAS unsigned*)(lds + (bufoff) + ldsw + _i * 8192), 16, 0, 0); } while (0)
; #define PG8_LDA(dst, b, h) do { _Pragma("unroll") for (int m = 0; m < 4; ++m) _Pragma("unroll") for (int k = 0; k < 2; ++k) dst[m][k] = *(const LAS bf16x8*)(lds + PG8_SA(b, h) + aoff + m * 2048 + k * 1024); } while (0)
; #define PG8_LDB(dst, b, h) do { _Pragma("unroll") for (int n = 0; n < 2; ++n) _Pragma("unroll") for (int k = 0; k < 2; ++k) dst[n][k] = *(const LAS bf16x8*)(lds + PG8_SB(b, h) + boff + n * 2048 + k * 1024); } while (0)
; #define PG8_MMA(ai, bj, At, Bt) do { __builtin_amdgcn_s_setprio(1); _Pragma("unroll") for (int m = 0; m < 4; ++m) _Pragma("unroll") for (int n = 0; n < 2; ++n) _Pragma("unroll") for (int k = 0; k < 2; ++k) \
;         acc[ai][bj][m][n] = __builtin_amdgcn_mfma_f32_16x16x32_bf16(Bt[n][k], At[m][k], acc[ai][bj][m][n], 0, 0, 0); __builtin_amdgcn_s_setprio(0); } while (0)
; #define PG8_WAIT_V(n) asm volatile("s_waitcnt vmcnt(" #n ")" ::: "memory")
; #define PG8_WAIT_L(n) asm volatile("s_waitcnt lgkmcnt(" #n ")" ::: "memory")
; #define PG8_BAR __builtin_amdgcn_s_barrier()
; #define PG8_SCHED __builtin_amdgcn_sched_barrier(0)
; template <class Epi>
; __device__ __forceinline__ void gemm_phase(LAS unsigned char* lds, const Gemm g, const StaticOrder& S, const Epi& E, int wave_s) {
;     ...
;             PG8_LDB(B0, 1, 0); PG8_LDB(B1, 1, 1); PG8_SCHED; PG8_LDA(At, 1, 0); PG8_STAGE(PG8_SA(0, 1), a2 + hstepA, voffA);
;             PG8_WAIT_V(8); PG8_WAIT_L(0); PG8_BAR; PG8_MMA(0, 0, At, B0); PG8_MMA(0, 1, At, B1); PG8_BAR; PG8_SCHED;
;             PG8_LDA(At, 1, 1); PG8_STAGE(PG8_SB(1, 0), b3, voffB); PG8_STAGE(PG8_SB(1, 1), b3 + hstepB, voffB); PG8_STAGE(PG8_SA(1, 0), a3, voffA);
;             PG8_WAIT_V(8); PG8_WAIT_L(0); PG8_BAR; PG8_MMA(1, 0, At, B0); PG8_MMA(1, 1, At, B1); PG8_BAR; PG8_SCHED;
;         }
;         if (wr == 0) PG8_BAR;
	s_nop 4
	ds_read_b128 v[10:13], v225
	ds_read_b128 v[14:17], v225 offset:1024
	ds_read_b128 v[18:21], v225 offset:2048
	ds_read_b128 v[22:25], v225 offset:3072
	ds_read_b128 v[166:169], v226
	ds_read_b128 v[190:193], v226 offset:1024
	ds_read_b128 v[194:197], v226 offset:2048
	ds_read_b128 v[226:229], v226 offset:3072
	s_add_u32 s22, s18, 0x110000
	s_addc_u32 s23, s19, 0
	s_mov_b32 m0, s35
	ds_read_b128 v[26:29], v145 offset:32768
	ds_read_b128 v[30:33], v145 offset:33792
	ds_read_b128 v[62:65], v145 offset:34816
	ds_read_b128 v[110:113], v145 offset:35840
	ds_read_b128 v[230:233], v145 offset:36864
	ds_read_b128 v[234:237], v145 offset:37888
	ds_read_b128 v[238:241], v145 offset:38912
	ds_read_b128 v[242:245], v145 offset:39936
	global_load_lds_dwordx4 v134, s[22:23]
	v_lshl_add_u64 v[98:99], s[22:23], 0, v[132:133]
	s_mov_b32 m0, s37
	s_nop 0
	global_load_lds_dwordx4 v[98:99], off
	s_waitcnt vmcnt(8)
	s_waitcnt lgkmcnt(0)
	s_setprio 1
	s_waitcnt lgkmcnt(0)
	v_mfma_f32_16x16x32_bf16 v[66:69], v[10:13], v[26:29], v[66:69]
	v_mfma_f32_16x16x32_bf16 v[114:117], v[14:17], v[30:33], v[66:69]
	v_mfma_f32_16x16x32_bf16 v[66:69], v[18:21], v[26:29], v[70:73]
	v_mfma_f32_16x16x32_bf16 v[118:121], v[22:25], v[30:33], v[66:69]
	s_barrier
	v_mfma_f32_16x16x32_bf16 v[66:69], v[10:13], v[62:65], v[74:77]
	v_mfma_f32_16x16x32_bf16 v[98:101], v[14:17], v[110:113], v[66:69]
	v_mfma_f32_16x16x32_bf16 v[66:69], v[18:21], v[62:65], v[78:81]
	v_mfma_f32_16x16x32_bf16 v[102:105], v[22:25], v[110:113], v[66:69]
	v_mfma_f32_16x16x32_bf16 v[66:69], v[10:13], v[230:233], v[82:85]
	v_mfma_f32_16x16x32_bf16 v[82:85], v[14:17], v[234:237], v[66:69]
	v_mfma_f32_16x16x32_bf16 v[66:69], v[18:21], v[230:233], v[86:89]
	v_mfma_f32_16x16x32_bf16 v[86:89], v[22:25], v[234:237], v[66:69]
	v_mfma_f32_16x16x32_bf16 v[66:69], v[10:13], v[238:241], v[90:93]
	v_mfma_f32_16x16x32_bf16 v[78:81], v[14:17], v[242:245], v[66:69]
	v_mfma_f32_16x16x32_bf16 v[66:69], v[18:21], v[238:241], v[94:97]
	v_mfma_f32_16x16x32_bf16 v[74:77], v[22:25], v[242:245], v[66:69]
	s_setprio 0
	s_setprio 1
	v_mfma_f32_16x16x32_bf16 v[66:69], v[166:169], v[26:29], v[208:211]
	v_mfma_f32_16x16x32_bf16 v[26:29], v[194:197], v[26:29], v[34:37]
	v_mfma_f32_16x16x32_bf16 v[126:129], v[226:229], v[30:33], v[26:29]
	v_mfma_f32_16x16x32_bf16 v[26:29], v[166:169], v[62:65], v[38:41]
	v_mfma_f32_16x16x32_bf16 v[106:109], v[190:193], v[110:113], v[26:29]
	v_mfma_f32_16x16x32_bf16 v[26:29], v[194:197], v[62:65], v[42:45]
	v_mfma_f32_16x16x32_bf16 v[110:113], v[226:229], v[110:113], v[26:29]
	v_mfma_f32_16x16x32_bf16 v[26:29], v[166:169], v[230:233], v[46:49]
	v_mfma_f32_16x16x32_bf16 v[90:93], v[190:193], v[234:237], v[26:29]
	v_mfma_f32_16x16x32_bf16 v[26:29], v[194:197], v[230:233], v[50:53]
	v_mfma_f32_16x16x32_bf16 v[94:97], v[226:229], v[234:237], v[26:29]
	v_mfma_f32_16x16x32_bf16 v[26:29], v[166:169], v[238:241], v[54:57]
	v_mfma_f32_16x16x32_bf16 v[70:73], v[190:193], v[242:245], v[26:29]
	v_mfma_f32_16x16x32_bf16 v[26:29], v[194:197], v[238:241], v[58:61]
	v_mfma_f32_16x16x32_bf16 v[122:125], v[190:193], v[30:33], v[66:69]
	v_mfma_f32_16x16x32_bf16 v[66:69], v[226:229], v[242:245], v[26:29]
	s_setprio 0
	s_barrier
	s_mov_b32 m0, s73
	s_nop 2
	v_lshl_add_u64 v[26:27], v[202:203], 0, s[42:43]
	s_add_u32 s4, s4, 0x10080
	ds_read_b128 v[34:37], v145 offset:49152
	ds_read_b128 v[38:41], v145 offset:50176
	ds_read_b128 v[208:211], v145 offset:51200
	ds_read_b128 v[230:233], v145 offset:52224
	ds_read_b128 v[234:237], v145 offset:53248
	ds_read_b128 v[238:241], v145 offset:54272
	ds_read_b128 v[242:245], v145 offset:55296
	ds_read_b128 v[246:249], v145 offset:56320
	global_load_lds_dwordx4 v[26:27], off
	v_lshl_add_u64 v[26:27], v[204:205], 0, s[42:43]
	s_mov_b32 m0, s71
	s_addc_u32 s5, s5, 0
	global_load_lds_dwordx4 v[26:27], off
	s_mov_b32 m0, s24
	s_nop 0
	global_load_lds_dwordx4 v0, s[4:5]
	s_mov_b32 m0, s25
	s_nop 0
	global_load_lds_dwordx4 v130, s[4:5]
	v_lshl_add_u64 v[26:27], v[206:207], 0, s[42:43]
	s_mov_b32 m0, s40
	s_nop 0
	global_load_lds_dwordx4 v[26:27], off
	v_lshl_add_u64 v[26:27], v[216:217], 0, s[42:43]
	s_mov_b32 m0, s41
	s_nop 0
	global_load_lds_dwordx4 v[26:27], off
	s_waitcnt vmcnt(8)
	s_waitcnt lgkmcnt(0)
	s_setprio 1
	s_waitcnt lgkmcnt(0)
	v_mfma_f32_16x16x32_bf16 v[26:29], v[10:13], v[34:37], v[136:139]
	v_mfma_f32_16x16x32_bf16 v[58:61], v[14:17], v[38:41], v[26:29]
	v_mfma_f32_16x16x32_bf16 v[26:29], v[18:21], v[34:37], v[140:143]
	v_mfma_f32_16x16x32_bf16 v[62:65], v[22:25], v[38:41], v[26:29]
	s_barrier
	v_mfma_f32_16x16x32_bf16 v[26:29], v[10:13], v[208:211], v[146:149]
	v_mfma_f32_16x16x32_bf16 v[42:45], v[14:17], v[230:233], v[26:29]
	v_mfma_f32_16x16x32_bf16 v[26:29], v[18:21], v[208:211], v[150:153]
	v_mfma_f32_16x16x32_bf16 v[2:5], v[10:13], v[242:245], v[2:5]
	v_mfma_f32_16x16x32_bf16 v[46:49], v[22:25], v[230:233], v[26:29]
	v_mfma_f32_16x16x32_bf16 v[26:29], v[10:13], v[234:237], v[154:157]
	v_mfma_f32_16x16x32_bf16 v[30:33], v[18:21], v[234:237], v[158:161]
	v_mfma_f32_16x16x32_bf16 v[10:13], v[14:17], v[246:249], v[2:5]
	v_mfma_f32_16x16x32_bf16 v[2:5], v[18:21], v[242:245], v[6:9]
	v_mfma_f32_16x16x32_bf16 v[26:29], v[14:17], v[238:241], v[26:29]
	v_mfma_f32_16x16x32_bf16 v[30:33], v[22:25], v[238:241], v[30:33]
	v_mfma_f32_16x16x32_bf16 v[14:17], v[22:25], v[246:249], v[2:5]
	s_setprio 0
	s_setprio 1
	v_mfma_f32_16x16x32_bf16 v[2:5], v[166:169], v[34:37], v[198:201]
	v_mfma_f32_16x16x32_bf16 v[50:53], v[190:193], v[38:41], v[2:5]
	v_mfma_f32_16x16x32_bf16 v[2:5], v[194:197], v[34:37], v[170:173]
	v_mfma_f32_16x16x32_bf16 v[54:57], v[226:229], v[38:41], v[2:5]
	v_mfma_f32_16x16x32_bf16 v[2:5], v[166:169], v[208:211], v[212:215]
	v_mfma_f32_16x16x32_bf16 v[38:41], v[190:193], v[230:233], v[2:5]
	v_mfma_f32_16x16x32_bf16 v[2:5], v[194:197], v[208:211], v[174:177]
	v_mfma_f32_16x16x32_bf16 v[34:37], v[226:229], v[230:233], v[2:5]
	v_mfma_f32_16x16x32_bf16 v[2:5], v[166:169], v[234:237], v[178:181]
	v_mfma_f32_16x16x32_bf16 v[18:21], v[190:193], v[238:241], v[2:5]
	v_mfma_f32_16x16x32_bf16 v[2:5], v[194:197], v[234:237], v[182:185]
	v_mfma_f32_16x16x32_bf16 v[22:25], v[226:229], v[238:241], v[2:5]
	v_mfma_f32_16x16x32_bf16 v[2:5], v[166:169], v[242:245], v[186:189]
	v_mfma_f32_16x16x32_bf16 v[6:9], v[190:193], v[246:249], v[2:5]
	v_mfma_f32_16x16x32_bf16 v[2:5], v[194:197], v[242:245], v[162:165]
	v_mfma_f32_16x16x32_bf16 v[2:5], v[226:229], v[246:249], v[2:5]
	s_setprio 0
	s_barrier
	s_andn2_b64 vcc, exec, s[12:13]
	s_cbranch_vccnz .LBB0_331
	s_barrier

; #define PG8_STAGE(bufoff, gbase, voff) do { _Pragma("unroll") for (int _i = 0; _i < 2; ++_i) \
;         __builtin_amdgcn_global_load_lds((const unsigned*)((const char*)(gbase) + (voff)[_i]), (LAS unsigned*)(lds + (bufoff) + ldsw + _i * 8192), 16, 0, 0); } while (0)
; #define PG8_LDA(dst, b, h) do { _Pragma("unroll") for (int m = 0; m < 4; ++m) _Pragma("unroll") for (int k = 0; k < 2; ++k) dst[m][k] = *(const LAS bf16x8*)(lds + PG8_SA(b, h) + aoff + m * 2048 + k * 1024); } while (0)
; #define PG8_LDB(dst, b, h) do { _Pragma("unroll") for (int n = 0; n < 2; ++n) _Pragma("unroll") for (int k = 0; k < 2; ++k) dst[n][k] = *(const LAS bf16x8*)(lds + PG8_SB(b, h) + boff + n * 2048 + k * 1024); } while (0)
; #define PG8_MMA(ai, bj, At, Bt) do { __builtin_amdgcn_s_setprio(1); _Pragma("unroll") for (int m = 0; m < 4; ++m) _Pragma("unroll") for (int n = 0; n < 2; ++n) _Pragma("unroll") for (int k = 0; k < 2; ++k) \
;         acc[ai][bj][m][n] = __builtin_amdgcn_mfma_f32_16x16x32_bf16(Bt[n][k], At[m][k], acc[ai][bj][m][n], 0, 0, 0); __builtin_amdgcn_s_setprio(0); } while (0)
; #define PG8_WAIT_V(n) asm volatile("s_waitcnt vmcnt(" #n ")" ::: "memory")
; #define PG8_WAIT_L(n) asm volatile("s_waitcnt lgkmcnt(" #n ")" ::: "memory")
; #define PG8_BAR __builtin_amdgcn_s_barrier()
; #define PG8_SCHED __builtin_amdgcn_sched_barrier(0)
; template <class Epi>
; __device__ __forceinline__ void gemm_phase(LAS unsigned char* lds, const Gemm g, const StaticOrder& S, const Epi& E, int wave_s) {
;     ...
;         for (int t = 0; t < nt; t += 2) {
;             const bool last = (t == nt - 2);
;             const char* a1 = cA + (size_t)(t + 1) * kstep;
;             const char* a2 = last ? nA : cA + (size_t)(t + 2) * kstep; const char* b2 = last ? nB : cB + (size_t)(t + 2) * kstep;
;             const char* a3 = a2 + kstep; const char* b3 = b2 + kstep;
;             PG8_LDB(B0, 0, 0); PG8_LDB(B1, 0, 1); PG8_SCHED; PG8_LDA(At, 0, 0); PG8_STAGE(PG8_SA(1, 1), a1 + hstepA, voffA);
;             PG8_WAIT_V(8); PG8_WAIT_L(0); PG8_BAR; PG8_MMA(0, 0, At, B0); PG8_MMA(0, 1, At, B1); PG8_BAR; PG8_SCHED;
;             PG8_LDA(At, 0, 1); PG8_STAGE(PG8_SB(0, 0), b2, voffB); PG8_STAGE(PG8_SB(0, 1), b2 + hstepB, voffB); PG8_STAGE(PG8_SA(0, 0), a2, voffA);
;             PG8_WAIT_V(8); PG8_WAIT_L(0); PG8_BAR; PG8_MMA(1, 0, At, B0); PG8_MMA(1, 1, At, B1); PG8_BAR; PG8_SCHED;
.LBB0_921:
	s_add_u32 s24, s22, 0xfff80080
	s_addc_u32 s25, s23, -1
	s_add_i32 s78, 0, 0x10000
	s_cmp_eq_u32 s73, 28
	s_cselect_b32 s27, s17, s25
	s_cselect_b32 s26, s67, s24
	s_cselect_b32 s25, s15, s72
	s_cselect_b32 s24, s70, s71
	s_add_i32 s82, 0, 0x14000
	v_add_u32_e32 v142, s78, v158
	v_add_u32_e32 v156, s82, v158
	ds_read_b128 v[130:133], v142
	ds_read_b128 v[134:137], v142 offset:1024
	ds_read_b128 v[138:141], v142 offset:2048
	ds_read_b128 v[142:145], v142 offset:3072
	ds_read_b128 v[152:155], v156
	ds_read_b128 v[160:163], v156 offset:1024
	ds_read_b128 v[164:167], v156 offset:2048
	ds_read_b128 v[168:171], v156 offset:3072
	v_lshl_add_u64 v[156:157], s[22:23], 0, v[150:151]
	s_add_i32 m0, s35, 0xc000
	ds_read_b128 v[172:175], v159
	ds_read_b128 v[176:179], v159 offset:1024
	ds_read_b128 v[180:183], v159 offset:2048
	ds_read_b128 v[184:187], v159 offset:3072
	ds_read_b128 v[188:191], v159 offset:4096
	ds_read_b128 v[192:195], v159 offset:5120
	ds_read_b128 v[196:199], v159 offset:6144
	ds_read_b128 v[200:203], v159 offset:7168
	global_load_lds_dwordx4 v[156:157], off
	v_lshl_add_u64 v[156:157], s[22:23], 0, v[148:149]
	s_add_i32 m0, s35, 0xe000
	s_nop 0
	global_load_lds_dwordx4 v[156:157], off
	s_waitcnt vmcnt(8)
	s_waitcnt lgkmcnt(0)
	s_setprio 1
	s_waitcnt lgkmcnt(0)
	v_mfma_f32_16x16x32_bf16 v[126:129], v[130:133], v[172:175], v[126:129]
	v_mfma_f32_16x16x32_bf16 v[122:125], v[138:141], v[172:175], v[122:125]
	v_mfma_f32_16x16x32_bf16 v[118:121], v[130:133], v[180:183], v[118:121]
	v_mfma_f32_16x16x32_bf16 v[114:117], v[138:141], v[180:183], v[114:117]
	s_barrier
	v_mfma_f32_16x16x32_bf16 v[110:113], v[130:133], v[188:191], v[110:113]
	v_mfma_f32_16x16x32_bf16 v[98:101], v[138:141], v[188:191], v[98:101]
	v_mfma_f32_16x16x32_bf16 v[82:85], v[130:133], v[196:199], v[82:85]
	v_mfma_f32_16x16x32_bf16 v[74:77], v[138:141], v[196:199], v[74:77]
	v_mfma_f32_16x16x32_bf16 v[126:129], v[134:137], v[176:179], v[126:129]
	v_mfma_f32_16x16x32_bf16 v[122:125], v[142:145], v[176:179], v[122:125]
	v_mfma_f32_16x16x32_bf16 v[118:121], v[134:137], v[184:187], v[118:121]
	v_mfma_f32_16x16x32_bf16 v[114:117], v[142:145], v[184:187], v[114:117]
	v_mfma_f32_16x16x32_bf16 v[110:113], v[134:137], v[192:195], v[110:113]
	v_mfma_f32_16x16x32_bf16 v[98:101], v[142:145], v[192:195], v[98:101]
	v_mfma_f32_16x16x32_bf16 v[82:85], v[134:137], v[200:203], v[82:85]
	v_mfma_f32_16x16x32_bf16 v[74:77], v[142:145], v[200:203], v[74:77]
	s_setprio 0
	s_setprio 1
	v_mfma_f32_16x16x32_bf16 v[106:109], v[152:155], v[172:175], v[106:109]
	v_mfma_f32_16x16x32_bf16 v[102:105], v[164:167], v[172:175], v[102:105]
	v_mfma_f32_16x16x32_bf16 v[94:97], v[152:155], v[180:183], v[94:97]
	v_mfma_f32_16x16x32_bf16 v[90:93], v[164:167], v[180:183], v[90:93]
	v_mfma_f32_16x16x32_bf16 v[86:89], v[152:155], v[188:191], v[86:89]
	v_mfma_f32_16x16x32_bf16 v[78:81], v[164:167], v[188:191], v[78:81]
	v_mfma_f32_16x16x32_bf16 v[70:73], v[152:155], v[196:199], v[70:73]
	v_mfma_f32_16x16x32_bf16 v[66:69], v[164:167], v[196:199], v[66:69]
	v_mfma_f32_16x16x32_bf16 v[106:109], v[160:163], v[176:179], v[106:109]
	v_mfma_f32_16x16x32_bf16 v[102:105], v[168:171], v[176:179], v[102:105]
	v_mfma_f32_16x16x32_bf16 v[94:97], v[160:163], v[184:187], v[94:97]
	v_mfma_f32_16x16x32_bf16 v[90:93], v[168:171], v[184:187], v[90:93]
	v_mfma_f32_16x16x32_bf16 v[86:89], v[160:163], v[192:195], v[86:89]
	v_mfma_f32_16x16x32_bf16 v[78:81], v[168:171], v[192:195], v[78:81]
	v_mfma_f32_16x16x32_bf16 v[70:73], v[160:163], v[200:203], v[70:73]
	v_mfma_f32_16x16x32_bf16 v[66:69], v[168:171], v[200:203], v[66:69]
	s_setprio 0
	s_barrier
	s_add_i32 s78, s78, s34
	v_lshl_add_u64 v[156:157], s[24:25], 0, v[0:1]
	s_mov_b32 m0, s78
	ds_read_b128 v[172:175], v159 offset:16384
	ds_read_b128 v[176:179], v159 offset:17408
	ds_read_b128 v[180:183], v159 offset:18432
	ds_read_b128 v[184:187], v159 offset:19456
	ds_read_b128 v[188:191], v159 offset:20480
	ds_read_b128 v[192:195], v159 offset:21504
	ds_read_b128 v[196:199], v159 offset:22528
	ds_read_b128 v[200:203], v159 offset:23552
	global_load_lds_dwordx4 v[156:157], off
	s_add_i32 m0, s78, 0x2000
	s_add_u32 s78, s24, 0x80000
	v_lshl_add_u64 v[204:205], s[24:25], 0, v[146:147]
	s_addc_u32 s79, s25, 0
	s_add_i32 s82, s82, s34
	global_load_lds_dwordx4 v[204:205], off
	s_mov_b32 m0, s82
	v_lshl_add_u64 v[208:209], s[26:27], 0, v[146:147]
	global_load_lds_dwordx4 v0, s[78:79]
	v_lshl_add_u64 v[206:207], s[78:79], 0, v[146:147]
	s_add_i32 m0, s82, 0x2000
	s_nop 0
	global_load_lds_dwordx4 v[206:207], off
	v_lshl_add_u64 v[206:207], s[26:27], 0, v[0:1]
	s_mov_b32 m0, s35
	s_nop 0
	global_load_lds_dwordx4 v[206:207], off
	s_mov_b32 m0, s37
	s_nop 0
	global_load_lds_dwordx4 v[208:209], off
	s_waitcnt vmcnt(8)
	s_waitcnt lgkmcnt(0)
	s_setprio 1
	s_waitcnt lgkmcnt(0)
	v_mfma_f32_16x16x32_bf16 v[62:65], v[130:133], v[172:175], v[62:65]
	v_mfma_f32_16x16x32_bf16 v[58:61], v[138:141], v[172:175], v[58:61]
	v_mfma_f32_16x16x32_bf16 v[54:57], v[130:133], v[180:183], v[54:57]
	v_mfma_f32_16x16x32_bf16 v[50:53], v[138:141], v[180:183], v[50:53]
	s_barrier
; #define PG8_STAGE(bufoff, gbase, voff) do { _Pragma("unroll") for (int _i = 0; _i < 2; ++_i) \
;         __builtin_amdgcn_global_load_lds((const unsigned*)((const char*)(gbase) + (voff)[_i]), (LAS unsigned*)(lds + (bufoff) + ldsw + _i * 8192), 16, 0, 0); } while (0)
; #define PG8_LDA(dst, b, h) do { _Pragma("unroll") for (int m = 0; m < 4; ++m) _Pragma("unroll") for (int k = 0; k < 2; ++k) dst[m][k] = *(const LAS bf16x8*)(lds + PG8_SA(b, h) + aoff + m * 2048 + k * 1024); } while (0)
; #define PG8_LDB(dst, b, h) do { _Pragma("unroll") for (int n = 0; n < 2; ++n) _Pragma("unroll") for (int k = 0; k < 2; ++k) dst[n][k] = *(const LAS bf16x8*)(lds + PG8_SB(b, h) + boff + n * 2048 + k * 1024); } while (0)
; #define PG8_MMA(ai, bj, At, Bt) do { __builtin_amdgcn_s_setprio(1); _Pragma("unroll") for (int m = 0; m < 4; ++m) _Pragma("unroll") for (int n = 0; n < 2; ++n) _Pragma("unroll") for (int k = 0; k < 2; ++k) \
;         acc[ai][bj][m][n] = __builtin_amdgcn_mfma_f32_16x16x32_bf16(Bt[n][k], At[m][k], acc[ai][bj][m][n], 0, 0, 0); __builtin_amdgcn_s_setprio(0); } while (0)
; #define PG8_WAIT_V(n) asm volatile("s_waitcnt vmcnt(" #n ")" ::: "memory")
; #define PG8_WAIT_L(n) asm volatile("s_waitcnt lgkmcnt(" #n ")" ::: "memory")
; #define PG8_BAR __builtin_amdgcn_s_barrier()
; #define PG8_SCHED __builtin_amdgcn_sched_barrier(0)
; template <class Epi>
; __device__ __forceinline__ void gemm_phase(LAS unsigned char* lds, const Gemm g, const StaticOrder& S, const Epi& E, int wave_s) {
;     ...
;             PG8_WAIT_V(8); PG8_WAIT_L(0); PG8_BAR; PG8_MMA(0, 0, At, B0); PG8_MMA(0, 1, At, B1); PG8_BAR; PG8_SCHED;
;             PG8_LDA(At, 0, 1); PG8_STAGE(PG8_SB(0, 0), b2, voffB); PG8_STAGE(PG8_SB(0, 1), b2 + hstepB, voffB); PG8_STAGE(PG8_SA(0, 0), a2, voffA);
;             PG8_WAIT_V(8); PG8_WAIT_L(0); PG8_BAR; PG8_MMA(1, 0, At, B0); PG8_MMA(1, 1, At, B1); PG8_BAR; PG8_SCHED;
;             PG8_LDB(B0, 1, 0); PG8_LDB(B1, 1, 1); PG8_SCHED; PG8_LDA(At, 1, 0); PG8_STAGE(PG8_SA(0, 1), a2 + hstepA, voffA);
;             PG8_WAIT_V(8); PG8_WAIT_L(0); PG8_BAR; PG8_MMA(0, 0, At, B0); PG8_MMA(0, 1, At, B1); PG8_BAR; PG8_SCHED;
	v_mfma_f32_16x16x32_bf16 v[46:49], v[130:133], v[188:191], v[46:49]
	v_mfma_f32_16x16x32_bf16 v[34:37], v[138:141], v[188:191], v[34:37]
	v_mfma_f32_16x16x32_bf16 v[22:25], v[130:133], v[196:199], v[22:25]
	v_mfma_f32_16x16x32_bf16 v[14:17], v[138:141], v[196:199], v[14:17]
	v_mfma_f32_16x16x32_bf16 v[62:65], v[134:137], v[176:179], v[62:65]
	v_mfma_f32_16x16x32_bf16 v[58:61], v[142:145], v[176:179], v[58:61]
	v_mfma_f32_16x16x32_bf16 v[54:57], v[134:137], v[184:187], v[54:57]
	v_mfma_f32_16x16x32_bf16 v[50:53], v[142:145], v[184:187], v[50:53]
	v_mfma_f32_16x16x32_bf16 v[46:49], v[134:137], v[192:195], v[46:49]
	v_mfma_f32_16x16x32_bf16 v[34:37], v[142:145], v[192:195], v[34:37]
	v_mfma_f32_16x16x32_bf16 v[22:25], v[134:137], v[200:203], v[22:25]
	v_mfma_f32_16x16x32_bf16 v[14:17], v[142:145], v[200:203], v[14:17]
	s_setprio 0
	s_setprio 1
	v_mfma_f32_16x16x32_bf16 v[42:45], v[152:155], v[172:175], v[42:45]
	v_mfma_f32_16x16x32_bf16 v[38:41], v[164:167], v[172:175], v[38:41]
	v_mfma_f32_16x16x32_bf16 v[30:33], v[152:155], v[180:183], v[30:33]
	v_mfma_f32_16x16x32_bf16 v[26:29], v[164:167], v[180:183], v[26:29]
	v_mfma_f32_16x16x32_bf16 v[18:21], v[152:155], v[188:191], v[18:21]
	v_mfma_f32_16x16x32_bf16 v[10:13], v[164:167], v[188:191], v[10:13]
	v_mfma_f32_16x16x32_bf16 v[6:9], v[152:155], v[196:199], v[6:9]
	v_mfma_f32_16x16x32_bf16 v[2:5], v[164:167], v[196:199], v[2:5]
	v_mfma_f32_16x16x32_bf16 v[42:45], v[160:163], v[176:179], v[42:45]
	v_mfma_f32_16x16x32_bf16 v[38:41], v[168:171], v[176:179], v[38:41]
	v_mfma_f32_16x16x32_bf16 v[30:33], v[160:163], v[184:187], v[30:33]
	v_mfma_f32_16x16x32_bf16 v[26:29], v[168:171], v[184:187], v[26:29]
	v_mfma_f32_16x16x32_bf16 v[18:21], v[160:163], v[192:195], v[18:21]
	v_mfma_f32_16x16x32_bf16 v[10:13], v[168:171], v[192:195], v[10:13]
	v_mfma_f32_16x16x32_bf16 v[6:9], v[160:163], v[200:203], v[6:9]
	v_mfma_f32_16x16x32_bf16 v[2:5], v[168:171], v[200:203], v[2:5]
	s_setprio 0
	s_barrier
	s_add_i32 s78, 0, 0x18000
	s_add_i32 s79, 0, 0x1c000
	v_add_u32_e32 v142, s78, v158
	v_add_u32_e32 v168, s79, v158
	ds_read_b128 v[130:133], v142
	ds_read_b128 v[134:137], v142 offset:1024
	ds_read_b128 v[138:141], v142 offset:2048
	ds_read_b128 v[142:145], v142 offset:3072
	ds_read_b128 v[152:155], v168
	ds_read_b128 v[160:163], v168 offset:1024
	ds_read_b128 v[164:167], v168 offset:2048
	ds_read_b128 v[168:171], v168 offset:3072
	s_add_u32 s26, s26, 0x80000
	s_addc_u32 s27, s27, 0
	s_mov_b32 m0, s38
	ds_read_b128 v[172:175], v159 offset:32768
	ds_read_b128 v[176:179], v159 offset:33792
	ds_read_b128 v[180:183], v159 offset:34816
	ds_read_b128 v[184:187], v159 offset:35840
	ds_read_b128 v[188:191], v159 offset:36864
	ds_read_b128 v[192:195], v159 offset:37888
	ds_read_b128 v[196:199], v159 offset:38912
	ds_read_b128 v[200:203], v159 offset:39936
	global_load_lds_dwordx4 v0, s[26:27]
	v_lshl_add_u64 v[210:211], s[26:27], 0, v[146:147]
	s_mov_b32 m0, s39
	s_nop 0
	global_load_lds_dwordx4 v[210:211], off
	s_waitcnt vmcnt(8)
	s_waitcnt lgkmcnt(0)
	s_setprio 1
	s_waitcnt lgkmcnt(0)
	v_mfma_f32_16x16x32_bf16 v[126:129], v[130:133], v[172:175], v[126:129]
	v_mfma_f32_16x16x32_bf16 v[122:125], v[138:141], v[172:175], v[122:125]
	v_mfma_f32_16x16x32_bf16 v[118:121], v[130:133], v[180:183], v[118:121]
	v_mfma_f32_16x16x32_bf16 v[114:117], v[138:141], v[180:183], v[114:117]
	s_barrier
	v_mfma_f32_16x16x32_bf16 v[110:113], v[130:133], v[188:191], v[110:113]
	v_mfma_f32_16x16x32_bf16 v[98:101], v[138:141], v[188:191], v[98:101]
	v_mfma_f32_16x16x32_bf16 v[82:85], v[130:133], v[196:199], v[82:85]
	v_mfma_f32_16x16x32_bf16 v[74:77], v[138:141], v[196:199], v[74:77]
	v_mfma_f32_16x16x32_bf16 v[126:129], v[134:137], v[176:179], v[126:129]
	v_mfma_f32_16x16x32_bf16 v[122:125], v[142:145], v[176:179], v[122:125]
	v_mfma_f32_16x16x32_bf16 v[118:121], v[134:137], v[184:187], v[118:121]
	v_mfma_f32_16x16x32_bf16 v[114:117], v[142:145], v[184:187], v[114:117]
	v_mfma_f32_16x16x32_bf16 v[110:113], v[134:137], v[192:195], v[110:113]
	v_mfma_f32_16x16x32_bf16 v[98:101], v[142:145], v[192:195], v[98:101]
	v_mfma_f32_16x16x32_bf16 v[82:85], v[134:137], v[200:203], v[82:85]
	v_mfma_f32_16x16x32_bf16 v[74:77], v[142:145], v[200:203], v[74:77]
	s_setprio 0
	s_setprio 1
	v_mfma_f32_16x16x32_bf16 v[106:109], v[152:155], v[172:175], v[106:109]
	v_mfma_f32_16x16x32_bf16 v[102:105], v[164:167], v[172:175], v[102:105]
	v_mfma_f32_16x16x32_bf16 v[94:97], v[152:155], v[180:183], v[94:97]
	v_mfma_f32_16x16x32_bf16 v[90:93], v[164:167], v[180:183], v[90:93]
	v_mfma_f32_16x16x32_bf16 v[86:89], v[152:155], v[188:191], v[86:89]
	v_mfma_f32_16x16x32_bf16 v[78:81], v[164:167], v[188:191], v[78:81]
	v_mfma_f32_16x16x32_bf16 v[70:73], v[152:155], v[196:199], v[70:73]
	v_mfma_f32_16x16x32_bf16 v[66:69], v[164:167], v[196:199], v[66:69]
	v_mfma_f32_16x16x32_bf16 v[106:109], v[160:163], v[176:179], v[106:109]
	v_mfma_f32_16x16x32_bf16 v[102:105], v[168:171], v[176:179], v[102:105]
	v_mfma_f32_16x16x32_bf16 v[94:97], v[160:163], v[184:187], v[94:97]
	v_mfma_f32_16x16x32_bf16 v[90:93], v[168:171], v[184:187], v[90:93]
	v_mfma_f32_16x16x32_bf16 v[86:89], v[160:163], v[192:195], v[86:89]
	v_mfma_f32_16x16x32_bf16 v[78:81], v[168:171], v[192:195], v[78:81]
	v_mfma_f32_16x16x32_bf16 v[70:73], v[160:163], v[200:203], v[70:73]
	v_mfma_f32_16x16x32_bf16 v[66:69], v[168:171], v[200:203], v[66:69]
	s_setprio 0
	s_barrier
; #define PG8_STAGE(bufoff, gbase, voff) do { _Pragma("unroll") for (int _i = 0; _i < 2; ++_i) \
;         __builtin_amdgcn_global_load_lds((const unsigned*)((const char*)(gbase) + (voff)[_i]), (LAS unsigned*)(lds + (bufoff) + ldsw + _i * 8192), 16, 0, 0); } while (0)
; #define PG8_LDA(dst, b, h) do { _Pragma("unroll") for (int m = 0; m < 4; ++m) _Pragma("unroll") for (int k = 0; k < 2; ++k) dst[m][k] = *(const LAS bf16x8*)(lds + PG8_SA(b, h) + aoff + m * 2048 + k * 1024); } while (0)
; #define PG8_MMA(ai, bj, At, Bt) do { __builtin_amdgcn_s_setprio(1); _Pragma("unroll") for (int m = 0; m < 4; ++m) _Pragma("unroll") for (int n = 0; n < 2; ++n) _Pragma("unroll") for (int k = 0; k < 2; ++k) \
;         acc[ai][bj][m][n] = __builtin_amdgcn_mfma_f32_16x16x32_bf16(Bt[n][k], At[m][k], acc[ai][bj][m][n], 0, 0, 0); __builtin_amdgcn_s_setprio(0); } while (0)
; #define PG8_WAIT_V(n) asm volatile("s_waitcnt vmcnt(" #n ")" ::: "memory")
; #define PG8_WAIT_L(n) asm volatile("s_waitcnt lgkmcnt(" #n ")" ::: "memory")
; #define PG8_BAR __builtin_amdgcn_s_barrier()
; #define PG8_SCHED __builtin_amdgcn_sched_barrier(0)
; template <class Epi>
; __device__ __forceinline__ void gemm_phase(LAS unsigned char* lds, const Gemm g, const StaticOrder& S, const Epi& E, int wave_s) {
;     ...
;             PG8_WAIT_V(8); PG8_WAIT_L(0); PG8_BAR; PG8_MMA(0, 0, At, B0); PG8_MMA(0, 1, At, B1); PG8_BAR; PG8_SCHED;
;             PG8_LDA(At, 1, 1); PG8_STAGE(PG8_SB(1, 0), b3, voffB); PG8_STAGE(PG8_SB(1, 1), b3 + hstepB, voffB); PG8_STAGE(PG8_SA(1, 0), a3, voffA);
;             PG8_WAIT_V(8); PG8_WAIT_L(0); PG8_BAR; PG8_MMA(1, 0, At, B0); PG8_MMA(1, 1, At, B1); PG8_BAR; PG8_SCHED;
;         }
;         if (wr == 0) PG8_BAR;
	s_add_i32 s26, s78, s34
	v_lshl_add_u64 v[156:157], v[156:157], 0, s[42:43]
	s_mov_b32 m0, s26
	ds_read_b128 v[172:175], v159 offset:49152
	ds_read_b128 v[176:179], v159 offset:50176
	ds_read_b128 v[180:183], v159 offset:51200
	ds_read_b128 v[184:187], v159 offset:52224
	ds_read_b128 v[188:191], v159 offset:53248
	ds_read_b128 v[192:195], v159 offset:54272
	ds_read_b128 v[196:199], v159 offset:55296
	ds_read_b128 v[200:203], v159 offset:56320
	global_load_lds_dwordx4 v[156:157], off
	s_add_i32 m0, s26, 0x2000
	s_add_u32 s24, s24, 0x80080
	v_lshl_add_u64 v[156:157], v[204:205], 0, s[42:43]
	s_addc_u32 s25, s25, 0
	s_add_i32 s26, s79, s34
	global_load_lds_dwordx4 v[156:157], off
	s_mov_b32 m0, s26
	s_nop 0
	global_load_lds_dwordx4 v0, s[24:25]
	v_lshl_add_u64 v[156:157], s[24:25], 0, v[146:147]
	s_add_i32 m0, s26, 0x2000
	s_nop 0
	global_load_lds_dwordx4 v[156:157], off
	v_lshl_add_u64 v[156:157], v[206:207], 0, s[42:43]
	s_mov_b32 m0, s57
	s_nop 0
	global_load_lds_dwordx4 v[156:157], off
	v_lshl_add_u64 v[156:157], v[208:209], 0, s[42:43]
	s_mov_b32 m0, s64
	s_nop 0
	global_load_lds_dwordx4 v[156:157], off
	s_waitcnt vmcnt(8)
	s_waitcnt lgkmcnt(0)
	s_setprio 1
	s_waitcnt lgkmcnt(0)
	v_mfma_f32_16x16x32_bf16 v[62:65], v[130:133], v[172:175], v[62:65]
	v_mfma_f32_16x16x32_bf16 v[58:61], v[138:141], v[172:175], v[58:61]
	v_mfma_f32_16x16x32_bf16 v[54:57], v[130:133], v[180:183], v[54:57]
	v_mfma_f32_16x16x32_bf16 v[50:53], v[138:141], v[180:183], v[50:53]
	s_barrier
	v_mfma_f32_16x16x32_bf16 v[46:49], v[130:133], v[188:191], v[46:49]
	v_mfma_f32_16x16x32_bf16 v[34:37], v[138:141], v[188:191], v[34:37]
	v_mfma_f32_16x16x32_bf16 v[22:25], v[130:133], v[196:199], v[22:25]
	v_mfma_f32_16x16x32_bf16 v[14:17], v[138:141], v[196:199], v[14:17]
	v_mfma_f32_16x16x32_bf16 v[62:65], v[134:137], v[176:179], v[62:65]
	v_mfma_f32_16x16x32_bf16 v[58:61], v[142:145], v[176:179], v[58:61]
	v_mfma_f32_16x16x32_bf16 v[54:57], v[134:137], v[184:187], v[54:57]
	v_mfma_f32_16x16x32_bf16 v[50:53], v[142:145], v[184:187], v[50:53]
	v_mfma_f32_16x16x32_bf16 v[46:49], v[134:137], v[192:195], v[46:49]
	v_mfma_f32_16x16x32_bf16 v[34:37], v[142:145], v[192:195], v[34:37]
	v_mfma_f32_16x16x32_bf16 v[22:25], v[134:137], v[200:203], v[22:25]
	v_mfma_f32_16x16x32_bf16 v[14:17], v[142:145], v[200:203], v[14:17]
	s_setprio 0
	s_setprio 1
	v_mfma_f32_16x16x32_bf16 v[42:45], v[152:155], v[172:175], v[42:45]
	v_mfma_f32_16x16x32_bf16 v[38:41], v[164:167], v[172:175], v[38:41]
	v_mfma_f32_16x16x32_bf16 v[30:33], v[152:155], v[180:183], v[30:33]
	v_mfma_f32_16x16x32_bf16 v[26:29], v[164:167], v[180:183], v[26:29]
	v_mfma_f32_16x16x32_bf16 v[18:21], v[152:155], v[188:191], v[18:21]
	v_mfma_f32_16x16x32_bf16 v[10:13], v[164:167], v[188:191], v[10:13]
	v_mfma_f32_16x16x32_bf16 v[6:9], v[152:155], v[196:199], v[6:9]
	v_mfma_f32_16x16x32_bf16 v[2:5], v[164:167], v[196:199], v[2:5]
	v_mfma_f32_16x16x32_bf16 v[42:45], v[160:163], v[176:179], v[42:45]
	v_mfma_f32_16x16x32_bf16 v[38:41], v[168:171], v[176:179], v[38:41]
	v_mfma_f32_16x16x32_bf16 v[30:33], v[160:163], v[184:187], v[30:33]
	v_mfma_f32_16x16x32_bf16 v[26:29], v[168:171], v[184:187], v[26:29]
	v_mfma_f32_16x16x32_bf16 v[18:21], v[160:163], v[192:195], v[18:21]
	v_mfma_f32_16x16x32_bf16 v[10:13], v[168:171], v[192:195], v[10:13]
	v_mfma_f32_16x16x32_bf16 v[6:9], v[160:163], v[200:203], v[6:9]
	v_mfma_f32_16x16x32_bf16 v[2:5], v[168:171], v[200:203], v[2:5]
	s_setprio 0
	s_barrier
	s_add_i32 s73, s73, 2
	s_add_u32 s71, s71, 0x100
	s_addc_u32 s72, s72, 0
	s_add_u32 s22, s22, 0x100
	s_addc_u32 s23, s23, 0
	s_cmp_gt_u32 s73, 29
	s_cbranch_scc0 .LBB0_921
	s_and_b64 vcc, exec, s[12:13]
	s_cbranch_vccz .LBB0_924
	s_barrier

; #define PG8_STAGE(bufoff, gbase, voff) do { _Pragma("unroll") for (int _i = 0; _i < 2; ++_i) \
;         __builtin_amdgcn_global_load_lds((const unsigned*)((const char*)(gbase) + (voff)[_i]), (LAS unsigned*)(lds + (bufoff) + ldsw + _i * 8192), 16, 0, 0); } while (0)
; #define PG8_LDA(dst, b, h) do { _Pragma("unroll") for (int m = 0; m < 4; ++m) _Pragma("unroll") for (int k = 0; k < 2; ++k) dst[m][k] = *(const LAS bf16x8*)(lds + PG8_SA(b, h) + aoff + m * 2048 + k * 1024); } while (0)
; #define PG8_LDB(dst, b, h) do { _Pragma("unroll") for (int n = 0; n < 2; ++n) _Pragma("unroll") for (int k = 0; k < 2; ++k) dst[n][k] = *(const LAS bf16x8*)(lds + PG8_SB(b, h) + boff + n * 2048 + k * 1024); } while (0)
; #define PG8_MMA(ai, bj, At, Bt) do { __builtin_amdgcn_s_setprio(1); _Pragma("unroll") for (int m = 0; m < 4; ++m) _Pragma("unroll") for (int n = 0; n < 2; ++n) _Pragma("unroll") for (int k = 0; k < 2; ++k) \
;         acc[ai][bj][m][n] = __builtin_amdgcn_mfma_f32_16x16x32_bf16(Bt[n][k], At[m][k], acc[ai][bj][m][n], 0, 0, 0); __builtin_amdgcn_s_setprio(0); } while (0)
; #define PG8_WAIT_V(n) asm volatile("s_waitcnt vmcnt(" #n ")" ::: "memory")
; #define PG8_WAIT_L(n) asm volatile("s_waitcnt lgkmcnt(" #n ")" ::: "memory")
; #define PG8_BAR __builtin_amdgcn_s_barrier()
; #define PG8_SCHED __builtin_amdgcn_sched_barrier(0)
; template <class Epi>
; __device__ __forceinline__ void gemm_phase(LAS unsigned char* lds, const Gemm g, const StaticOrder& S, const Epi& E, int wave_s) {
;     ...
;         for (int t = 0; t < nt; t += 2) {
;             const bool last = (t == nt - 2);
;             const char* a1 = cA + (size_t)(t + 1) * kstep;
;             const char* a2 = last ? nA : cA + (size_t)(t + 2) * kstep; const char* b2 = last ? nB : cB + (size_t)(t + 2) * kstep;
;             const char* a3 = a2 + kstep; const char* b3 = b2 + kstep;
;             PG8_LDB(B0, 0, 0); PG8_LDB(B1, 0, 1); PG8_SCHED; PG8_LDA(At, 0, 0); PG8_STAGE(PG8_SA(1, 1), a1 + hstepA, voffA);
;             PG8_WAIT_V(8); PG8_WAIT_L(0); PG8_BAR; PG8_MMA(0, 0, At, B0); PG8_MMA(0, 1, At, B1); PG8_BAR; PG8_SCHED;
;             PG8_LDA(At, 0, 1); PG8_STAGE(PG8_SB(0, 0), b2, voffB); PG8_STAGE(PG8_SB(0, 1), b2 + hstepB, voffB); PG8_STAGE(PG8_SA(0, 0), a2, voffA);
;             PG8_WAIT_V(8); PG8_WAIT_L(0); PG8_BAR; PG8_MMA(1, 0, At, B0); PG8_MMA(1, 1, At, B1); PG8_BAR; PG8_SCHED;
.LBB0_1034:
	s_add_u32 s22, s20, 0xfff80080
	s_addc_u32 s23, s21, -1
	s_add_i32 s72, 0, 0x10000
	s_cmp_eq_u32 s71, 28
	s_cselect_b32 s25, s15, s23
	s_cselect_b32 s24, s65, s22
	v_add_u32_e32 v140, s72, v142
	s_cselect_b32 s23, s13, s70
	s_cselect_b32 s22, s66, s67
	s_add_i32 s78, 0, 0x14000
	ds_read_b128 v[144:147], v140
	ds_read_b128 v[148:151], v140 offset:1024
	ds_read_b128 v[152:155], v140 offset:2048
	ds_read_b128 v[156:159], v140 offset:3072
	v_add_u32_e32 v140, s78, v142
	ds_read_b128 v[160:163], v140
	ds_read_b128 v[164:167], v140 offset:1024
	ds_read_b128 v[168:171], v140 offset:2048
	ds_read_b128 v[172:175], v140 offset:3072
	s_add_i32 m0, s31, 0xc000
	ds_read_b128 v[176:179], v143
	ds_read_b128 v[180:183], v143 offset:1024
	ds_read_b128 v[184:187], v143 offset:2048
	ds_read_b128 v[188:191], v143 offset:3072
	ds_read_b128 v[192:195], v143 offset:4096
	ds_read_b128 v[196:199], v143 offset:5120
	ds_read_b128 v[200:203], v143 offset:6144
	ds_read_b128 v[208:211], v143 offset:7168
	global_load_lds_dwordx4 v138, s[20:21]
	s_add_i32 m0, s31, 0xe000
	s_nop 0
	global_load_lds_dwordx4 v136, s[20:21]
	s_waitcnt vmcnt(8)
	s_waitcnt lgkmcnt(0)
	s_setprio 1
	s_waitcnt lgkmcnt(0)
	v_mfma_f32_16x16x32_bf16 v[126:129], v[144:147], v[176:179], v[126:129]
	v_mfma_f32_16x16x32_bf16 v[122:125], v[152:155], v[176:179], v[122:125]
	v_mfma_f32_16x16x32_bf16 v[110:113], v[144:147], v[184:187], v[110:113]
	v_mfma_f32_16x16x32_bf16 v[106:109], v[152:155], v[184:187], v[106:109]
	s_barrier
	v_mfma_f32_16x16x32_bf16 v[94:97], v[144:147], v[192:195], v[94:97]
	v_mfma_f32_16x16x32_bf16 v[90:93], v[152:155], v[192:195], v[90:93]
	v_mfma_f32_16x16x32_bf16 v[78:81], v[144:147], v[200:203], v[78:81]
	v_mfma_f32_16x16x32_bf16 v[74:77], v[152:155], v[200:203], v[74:77]
	v_mfma_f32_16x16x32_bf16 v[126:129], v[148:151], v[180:183], v[126:129]
	v_mfma_f32_16x16x32_bf16 v[122:125], v[156:159], v[180:183], v[122:125]
	v_mfma_f32_16x16x32_bf16 v[110:113], v[148:151], v[188:191], v[110:113]
	v_mfma_f32_16x16x32_bf16 v[106:109], v[156:159], v[188:191], v[106:109]
	v_mfma_f32_16x16x32_bf16 v[94:97], v[148:151], v[196:199], v[94:97]
	v_mfma_f32_16x16x32_bf16 v[90:93], v[156:159], v[196:199], v[90:93]
	v_mfma_f32_16x16x32_bf16 v[78:81], v[148:151], v[208:211], v[78:81]
	v_mfma_f32_16x16x32_bf16 v[74:77], v[156:159], v[208:211], v[74:77]
	s_setprio 0
	s_setprio 1
	v_mfma_f32_16x16x32_bf16 v[118:121], v[160:163], v[176:179], v[118:121]
	v_mfma_f32_16x16x32_bf16 v[114:117], v[168:171], v[176:179], v[114:117]
	v_mfma_f32_16x16x32_bf16 v[102:105], v[160:163], v[184:187], v[102:105]
	v_mfma_f32_16x16x32_bf16 v[98:101], v[168:171], v[184:187], v[98:101]
	v_mfma_f32_16x16x32_bf16 v[86:89], v[160:163], v[192:195], v[86:89]
	v_mfma_f32_16x16x32_bf16 v[82:85], v[168:171], v[192:195], v[82:85]
	v_mfma_f32_16x16x32_bf16 v[70:73], v[160:163], v[200:203], v[70:73]
	v_mfma_f32_16x16x32_bf16 v[66:69], v[168:171], v[200:203], v[66:69]
	v_mfma_f32_16x16x32_bf16 v[118:121], v[164:167], v[180:183], v[118:121]
	v_mfma_f32_16x16x32_bf16 v[114:117], v[172:175], v[180:183], v[114:117]
	v_mfma_f32_16x16x32_bf16 v[102:105], v[164:167], v[188:191], v[102:105]
	v_mfma_f32_16x16x32_bf16 v[98:101], v[172:175], v[188:191], v[98:101]
	v_mfma_f32_16x16x32_bf16 v[86:89], v[164:167], v[196:199], v[86:89]
	v_mfma_f32_16x16x32_bf16 v[82:85], v[172:175], v[196:199], v[82:85]
	v_mfma_f32_16x16x32_bf16 v[70:73], v[164:167], v[208:211], v[70:73]
	v_mfma_f32_16x16x32_bf16 v[66:69], v[172:175], v[208:211], v[66:69]
	s_setprio 0
	s_barrier
	s_add_i32 s72, s72, s30
	v_lshl_add_u64 v[140:141], s[22:23], 0, v[0:1]
	s_mov_b32 m0, s72
	ds_read_b128 v[176:179], v143 offset:16384
	ds_read_b128 v[180:183], v143 offset:17408
	ds_read_b128 v[184:187], v143 offset:18432
	ds_read_b128 v[188:191], v143 offset:19456
	ds_read_b128 v[192:195], v143 offset:20480
	ds_read_b128 v[196:199], v143 offset:21504
	ds_read_b128 v[200:203], v143 offset:22528
	ds_read_b128 v[208:211], v143 offset:23552
	global_load_lds_dwordx4 v[140:141], off
	s_add_i32 m0, s72, 0x2000
	s_add_u32 s72, s22, 0x80000
	v_lshl_add_u64 v[204:205], s[22:23], 0, v[130:131]
	s_addc_u32 s73, s23, 0
	s_add_i32 s78, s78, s30
	global_load_lds_dwordx4 v[204:205], off
	s_mov_b32 m0, s78
	v_lshl_add_u64 v[212:213], s[24:25], 0, v[132:133]
	global_load_lds_dwordx4 v0, s[72:73]
	s_add_i32 m0, s78, 0x2000
	s_nop 0
	global_load_lds_dwordx4 v130, s[72:73]
	v_lshl_add_u64 v[206:207], s[24:25], 0, v[134:135]
	s_mov_b32 m0, s31
	s_nop 0
	global_load_lds_dwordx4 v[206:207], off
	s_mov_b32 m0, s34
	s_nop 0
	global_load_lds_dwordx4 v[212:213], off
	s_waitcnt vmcnt(8)
	s_waitcnt lgkmcnt(0)
	s_setprio 1
	s_waitcnt lgkmcnt(0)
	v_mfma_f32_16x16x32_bf16 v[62:65], v[144:147], v[176:179], v[62:65]
	v_mfma_f32_16x16x32_bf16 v[58:61], v[152:155], v[176:179], v[58:61]
	v_mfma_f32_16x16x32_bf16 v[46:49], v[144:147], v[184:187], v[46:49]
	v_mfma_f32_16x16x32_bf16 v[42:45], v[152:155], v[184:187], v[42:45]
	s_barrier
; #define PG8_STAGE(bufoff, gbase, voff) do { _Pragma("unroll") for (int _i = 0; _i < 2; ++_i) \
;         __builtin_amdgcn_global_load_lds((const unsigned*)((const char*)(gbase) + (voff)[_i]), (LAS unsigned*)(lds + (bufoff) + ldsw + _i * 8192), 16, 0, 0); } while (0)
; #define PG8_LDA(dst, b, h) do { _Pragma("unroll") for (int m = 0; m < 4; ++m) _Pragma("unroll") for (int k = 0; k < 2; ++k) dst[m][k] = *(const LAS bf16x8*)(lds + PG8_SA(b, h) + aoff + m * 2048 + k * 1024); } while (0)
; #define PG8_LDB(dst, b, h) do { _Pragma("unroll") for (int n = 0; n < 2; ++n) _Pragma("unroll") for (int k = 0; k < 2; ++k) dst[n][k] = *(const LAS bf16x8*)(lds + PG8_SB(b, h) + boff + n * 2048 + k * 1024); } while (0)
; #define PG8_MMA(ai, bj, At, Bt) do { __builtin_amdgcn_s_setprio(1); _Pragma("unroll") for (int m = 0; m < 4; ++m) _Pragma("unroll") for (int n = 0; n < 2; ++n) _Pragma("unroll") for (int k = 0; k < 2; ++k) \
;         acc[ai][bj][m][n] = __builtin_amdgcn_mfma_f32_16x16x32_bf16(Bt[n][k], At[m][k], acc[ai][bj][m][n], 0, 0, 0); __builtin_amdgcn_s_setprio(0); } while (0)
; #define PG8_WAIT_V(n) asm volatile("s_waitcnt vmcnt(" #n ")" ::: "memory")
; #define PG8_WAIT_L(n) asm volatile("s_waitcnt lgkmcnt(" #n ")" ::: "memory")
; #define PG8_BAR __builtin_amdgcn_s_barrier()
; #define PG8_SCHED __builtin_amdgcn_sched_barrier(0)
; template <class Epi>
; __device__ __forceinline__ void gemm_phase(LAS unsigned char* lds, const Gemm g, const StaticOrder& S, const Epi& E, int wave_s) {
;     ...
;             PG8_WAIT_V(8); PG8_WAIT_L(0); PG8_BAR; PG8_MMA(0, 0, At, B0); PG8_MMA(0, 1, At, B1); PG8_BAR; PG8_SCHED;
;             PG8_LDA(At, 0, 1); PG8_STAGE(PG8_SB(0, 0), b2, voffB); PG8_STAGE(PG8_SB(0, 1), b2 + hstepB, voffB); PG8_STAGE(PG8_SA(0, 0), a2, voffA);
;             PG8_WAIT_V(8); PG8_WAIT_L(0); PG8_BAR; PG8_MMA(1, 0, At, B0); PG8_MMA(1, 1, At, B1); PG8_BAR; PG8_SCHED;
;             PG8_LDB(B0, 1, 0); PG8_LDB(B1, 1, 1); PG8_SCHED; PG8_LDA(At, 1, 0); PG8_STAGE(PG8_SA(0, 1), a2 + hstepA, voffA);
;             PG8_WAIT_V(8); PG8_WAIT_L(0); PG8_BAR; PG8_MMA(0, 0, At, B0); PG8_MMA(0, 1, At, B1); PG8_BAR; PG8_SCHED;
	v_mfma_f32_16x16x32_bf16 v[30:33], v[144:147], v[192:195], v[30:33]
	v_mfma_f32_16x16x32_bf16 v[26:29], v[152:155], v[192:195], v[26:29]
	v_mfma_f32_16x16x32_bf16 v[14:17], v[144:147], v[200:203], v[14:17]
	v_mfma_f32_16x16x32_bf16 v[10:13], v[152:155], v[200:203], v[10:13]
	v_mfma_f32_16x16x32_bf16 v[62:65], v[148:151], v[180:183], v[62:65]
	v_mfma_f32_16x16x32_bf16 v[58:61], v[156:159], v[180:183], v[58:61]
	v_mfma_f32_16x16x32_bf16 v[46:49], v[148:151], v[188:191], v[46:49]
	v_mfma_f32_16x16x32_bf16 v[42:45], v[156:159], v[188:191], v[42:45]
	v_mfma_f32_16x16x32_bf16 v[30:33], v[148:151], v[196:199], v[30:33]
	v_mfma_f32_16x16x32_bf16 v[26:29], v[156:159], v[196:199], v[26:29]
	v_mfma_f32_16x16x32_bf16 v[14:17], v[148:151], v[208:211], v[14:17]
	v_mfma_f32_16x16x32_bf16 v[10:13], v[156:159], v[208:211], v[10:13]
	s_setprio 0
	s_setprio 1
	v_mfma_f32_16x16x32_bf16 v[54:57], v[160:163], v[176:179], v[54:57]
	v_mfma_f32_16x16x32_bf16 v[50:53], v[168:171], v[176:179], v[50:53]
	v_mfma_f32_16x16x32_bf16 v[38:41], v[160:163], v[184:187], v[38:41]
	v_mfma_f32_16x16x32_bf16 v[34:37], v[168:171], v[184:187], v[34:37]
	v_mfma_f32_16x16x32_bf16 v[22:25], v[160:163], v[192:195], v[22:25]
	v_mfma_f32_16x16x32_bf16 v[18:21], v[168:171], v[192:195], v[18:21]
	v_mfma_f32_16x16x32_bf16 v[6:9], v[160:163], v[200:203], v[6:9]
	v_mfma_f32_16x16x32_bf16 v[2:5], v[168:171], v[200:203], v[2:5]
	v_mfma_f32_16x16x32_bf16 v[54:57], v[164:167], v[180:183], v[54:57]
	v_mfma_f32_16x16x32_bf16 v[50:53], v[172:175], v[180:183], v[50:53]
	v_mfma_f32_16x16x32_bf16 v[38:41], v[164:167], v[188:191], v[38:41]
	v_mfma_f32_16x16x32_bf16 v[34:37], v[172:175], v[188:191], v[34:37]
	v_mfma_f32_16x16x32_bf16 v[22:25], v[164:167], v[196:199], v[22:25]
	v_mfma_f32_16x16x32_bf16 v[18:21], v[172:175], v[196:199], v[18:21]
	v_mfma_f32_16x16x32_bf16 v[6:9], v[164:167], v[208:211], v[6:9]
	v_mfma_f32_16x16x32_bf16 v[2:5], v[172:175], v[208:211], v[2:5]
	s_setprio 0
	s_barrier
	s_add_i32 s72, 0, 0x18000
	s_add_i32 s73, 0, 0x1c000
	v_add_u32_e32 v156, s72, v142
	v_add_u32_e32 v172, s73, v142
	ds_read_b128 v[144:147], v156
	ds_read_b128 v[148:151], v156 offset:1024
	ds_read_b128 v[152:155], v156 offset:2048
	ds_read_b128 v[156:159], v156 offset:3072
	ds_read_b128 v[160:163], v172
	ds_read_b128 v[164:167], v172 offset:1024
	ds_read_b128 v[168:171], v172 offset:2048
	ds_read_b128 v[172:175], v172 offset:3072
	s_add_u32 s24, s24, 0x80000
	s_addc_u32 s25, s25, 0
	s_mov_b32 m0, s35
	ds_read_b128 v[176:179], v143 offset:32768
	ds_read_b128 v[180:183], v143 offset:33792
	ds_read_b128 v[184:187], v143 offset:34816
	ds_read_b128 v[188:191], v143 offset:35840
	ds_read_b128 v[192:195], v143 offset:36864
	ds_read_b128 v[196:199], v143 offset:37888
	ds_read_b128 v[200:203], v143 offset:38912
	ds_read_b128 v[208:211], v143 offset:39936
	global_load_lds_dwordx4 v134, s[24:25]
	v_lshl_add_u64 v[214:215], s[24:25], 0, v[132:133]
	s_mov_b32 m0, s37
	s_nop 0
	global_load_lds_dwordx4 v[214:215], off
	s_waitcnt vmcnt(8)
	s_waitcnt lgkmcnt(0)
	s_setprio 1
	s_waitcnt lgkmcnt(0)
	v_mfma_f32_16x16x32_bf16 v[126:129], v[144:147], v[176:179], v[126:129]
	v_mfma_f32_16x16x32_bf16 v[122:125], v[152:155], v[176:179], v[122:125]
	v_mfma_f32_16x16x32_bf16 v[110:113], v[144:147], v[184:187], v[110:113]
	v_mfma_f32_16x16x32_bf16 v[106:109], v[152:155], v[184:187], v[106:109]
	s_barrier
	v_mfma_f32_16x16x32_bf16 v[94:97], v[144:147], v[192:195], v[94:97]
	v_mfma_f32_16x16x32_bf16 v[90:93], v[152:155], v[192:195], v[90:93]
	v_mfma_f32_16x16x32_bf16 v[78:81], v[144:147], v[200:203], v[78:81]
	v_mfma_f32_16x16x32_bf16 v[74:77], v[152:155], v[200:203], v[74:77]
	v_mfma_f32_16x16x32_bf16 v[126:129], v[148:151], v[180:183], v[126:129]
	v_mfma_f32_16x16x32_bf16 v[122:125], v[156:159], v[180:183], v[122:125]
	v_mfma_f32_16x16x32_bf16 v[110:113], v[148:151], v[188:191], v[110:113]
	v_mfma_f32_16x16x32_bf16 v[106:109], v[156:159], v[188:191], v[106:109]
	v_mfma_f32_16x16x32_bf16 v[94:97], v[148:151], v[196:199], v[94:97]
	v_mfma_f32_16x16x32_bf16 v[90:93], v[156:159], v[196:199], v[90:93]
	v_mfma_f32_16x16x32_bf16 v[78:81], v[148:151], v[208:211], v[78:81]
	v_mfma_f32_16x16x32_bf16 v[74:77], v[156:159], v[208:211], v[74:77]
	s_setprio 0
	s_setprio 1
	v_mfma_f32_16x16x32_bf16 v[118:121], v[160:163], v[176:179], v[118:121]
	v_mfma_f32_16x16x32_bf16 v[114:117], v[168:171], v[176:179], v[114:117]
	v_mfma_f32_16x16x32_bf16 v[102:105], v[160:163], v[184:187], v[102:105]
	v_mfma_f32_16x16x32_bf16 v[98:101], v[168:171], v[184:187], v[98:101]
	v_mfma_f32_16x16x32_bf16 v[86:89], v[160:163], v[192:195], v[86:89]
	v_mfma_f32_16x16x32_bf16 v[82:85], v[168:171], v[192:195], v[82:85]
	v_mfma_f32_16x16x32_bf16 v[70:73], v[160:163], v[200:203], v[70:73]
	v_mfma_f32_16x16x32_bf16 v[66:69], v[168:171], v[200:203], v[66:69]
	v_mfma_f32_16x16x32_bf16 v[118:121], v[164:167], v[180:183], v[118:121]
	v_mfma_f32_16x16x32_bf16 v[114:117], v[172:175], v[180:183], v[114:117]
	v_mfma_f32_16x16x32_bf16 v[102:105], v[164:167], v[188:191], v[102:105]
	v_mfma_f32_16x16x32_bf16 v[98:101], v[172:175], v[188:191], v[98:101]
	v_mfma_f32_16x16x32_bf16 v[86:89], v[164:167], v[196:199], v[86:89]
	v_mfma_f32_16x16x32_bf16 v[82:85], v[172:175], v[196:199], v[82:85]
	v_mfma_f32_16x16x32_bf16 v[70:73], v[164:167], v[208:211], v[70:73]
	v_mfma_f32_16x16x32_bf16 v[66:69], v[172:175], v[208:211], v[66:69]
	s_setprio 0
	s_barrier
; #define PG8_STAGE(bufoff, gbase, voff) do { _Pragma("unroll") for (int _i = 0; _i < 2; ++_i) \
;         __builtin_amdgcn_global_load_lds((const unsigned*)((const char*)(gbase) + (voff)[_i]), (LAS unsigned*)(lds + (bufoff) + ldsw + _i * 8192), 16, 0, 0); } while (0)
; #define PG8_LDA(dst, b, h) do { _Pragma("unroll") for (int m = 0; m < 4; ++m) _Pragma("unroll") for (int k = 0; k < 2; ++k) dst[m][k] = *(const LAS bf16x8*)(lds + PG8_SA(b, h) + aoff + m * 2048 + k * 1024); } while (0)
; #define PG8_MMA(ai, bj, At, Bt) do { __builtin_amdgcn_s_setprio(1); _Pragma("unroll") for (int m = 0; m < 4; ++m) _Pragma("unroll") for (int n = 0; n < 2; ++n) _Pragma("unroll") for (int k = 0; k < 2; ++k) \
;         acc[ai][bj][m][n] = __builtin_amdgcn_mfma_f32_16x16x32_bf16(Bt[n][k], At[m][k], acc[ai][bj][m][n], 0, 0, 0); __builtin_amdgcn_s_setprio(0); } while (0)
; #define PG8_WAIT_V(n) asm volatile("s_waitcnt vmcnt(" #n ")" ::: "memory")
; #define PG8_WAIT_L(n) asm volatile("s_waitcnt lgkmcnt(" #n ")" ::: "memory")
; #define PG8_BAR __builtin_amdgcn_s_barrier()
; #define PG8_SCHED __builtin_amdgcn_sched_barrier(0)
; template <class Epi>
; __device__ __forceinline__ void gemm_phase(LAS unsigned char* lds, const Gemm g, const StaticOrder& S, const Epi& E, int wave_s) {
;     ...
;             PG8_WAIT_V(8); PG8_WAIT_L(0); PG8_BAR; PG8_MMA(0, 0, At, B0); PG8_MMA(0, 1, At, B1); PG8_BAR; PG8_SCHED;
;             PG8_LDA(At, 1, 1); PG8_STAGE(PG8_SB(1, 0), b3, voffB); PG8_STAGE(PG8_SB(1, 1), b3 + hstepB, voffB); PG8_STAGE(PG8_SA(1, 0), a3, voffA);
;             PG8_WAIT_V(8); PG8_WAIT_L(0); PG8_BAR; PG8_MMA(1, 0, At, B0); PG8_MMA(1, 1, At, B1); PG8_BAR; PG8_SCHED;
;         }
;         if (wr == 0) PG8_BAR;
	s_add_i32 s24, s72, s30
	v_lshl_add_u64 v[140:141], v[140:141], 0, s[42:43]
	s_mov_b32 m0, s24
	ds_read_b128 v[176:179], v143 offset:49152
	ds_read_b128 v[180:183], v143 offset:50176
	ds_read_b128 v[184:187], v143 offset:51200
	ds_read_b128 v[188:191], v143 offset:52224
	ds_read_b128 v[192:195], v143 offset:53248
	ds_read_b128 v[196:199], v143 offset:54272
	ds_read_b128 v[200:203], v143 offset:55296
	ds_read_b128 v[208:211], v143 offset:56320
	global_load_lds_dwordx4 v[140:141], off
	s_add_i32 m0, s24, 0x2000
	s_add_u32 s22, s22, 0x80080
	v_lshl_add_u64 v[140:141], v[204:205], 0, s[42:43]
	s_addc_u32 s23, s23, 0
	s_add_i32 s24, s73, s30
	global_load_lds_dwordx4 v[140:141], off
	s_mov_b32 m0, s24
	s_nop 0
	global_load_lds_dwordx4 v0, s[22:23]
	s_add_i32 m0, s24, 0x2000
	s_nop 0
	global_load_lds_dwordx4 v130, s[22:23]
	v_lshl_add_u64 v[140:141], v[206:207], 0, s[42:43]
	s_mov_b32 m0, s40
	s_nop 0
	global_load_lds_dwordx4 v[140:141], off
	v_lshl_add_u64 v[140:141], v[212:213], 0, s[42:43]
	s_mov_b32 m0, s41
	s_nop 0
	global_load_lds_dwordx4 v[140:141], off
	s_waitcnt vmcnt(8)
	s_waitcnt lgkmcnt(0)
	s_setprio 1
	s_waitcnt lgkmcnt(0)
	v_mfma_f32_16x16x32_bf16 v[62:65], v[144:147], v[176:179], v[62:65]
	v_mfma_f32_16x16x32_bf16 v[58:61], v[152:155], v[176:179], v[58:61]
	v_mfma_f32_16x16x32_bf16 v[46:49], v[144:147], v[184:187], v[46:49]
	v_mfma_f32_16x16x32_bf16 v[42:45], v[152:155], v[184:187], v[42:45]
	s_barrier
	v_mfma_f32_16x16x32_bf16 v[30:33], v[144:147], v[192:195], v[30:33]
	v_mfma_f32_16x16x32_bf16 v[26:29], v[152:155], v[192:195], v[26:29]
	v_mfma_f32_16x16x32_bf16 v[14:17], v[144:147], v[200:203], v[14:17]
	v_mfma_f32_16x16x32_bf16 v[10:13], v[152:155], v[200:203], v[10:13]
	v_mfma_f32_16x16x32_bf16 v[62:65], v[148:151], v[180:183], v[62:65]
	v_mfma_f32_16x16x32_bf16 v[58:61], v[156:159], v[180:183], v[58:61]
	v_mfma_f32_16x16x32_bf16 v[46:49], v[148:151], v[188:191], v[46:49]
	v_mfma_f32_16x16x32_bf16 v[42:45], v[156:159], v[188:191], v[42:45]
	v_mfma_f32_16x16x32_bf16 v[30:33], v[148:151], v[196:199], v[30:33]
	v_mfma_f32_16x16x32_bf16 v[26:29], v[156:159], v[196:199], v[26:29]
	v_mfma_f32_16x16x32_bf16 v[14:17], v[148:151], v[208:211], v[14:17]
	v_mfma_f32_16x16x32_bf16 v[10:13], v[156:159], v[208:211], v[10:13]
	s_setprio 0
	s_setprio 1
	v_mfma_f32_16x16x32_bf16 v[54:57], v[160:163], v[176:179], v[54:57]
	v_mfma_f32_16x16x32_bf16 v[50:53], v[168:171], v[176:179], v[50:53]
	v_mfma_f32_16x16x32_bf16 v[38:41], v[160:163], v[184:187], v[38:41]
	v_mfma_f32_16x16x32_bf16 v[34:37], v[168:171], v[184:187], v[34:37]
	v_mfma_f32_16x16x32_bf16 v[22:25], v[160:163], v[192:195], v[22:25]
	v_mfma_f32_16x16x32_bf16 v[18:21], v[168:171], v[192:195], v[18:21]
	v_mfma_f32_16x16x32_bf16 v[6:9], v[160:163], v[200:203], v[6:9]
	v_mfma_f32_16x16x32_bf16 v[2:5], v[168:171], v[200:203], v[2:5]
	v_mfma_f32_16x16x32_bf16 v[54:57], v[164:167], v[180:183], v[54:57]
	v_mfma_f32_16x16x32_bf16 v[50:53], v[172:175], v[180:183], v[50:53]
	v_mfma_f32_16x16x32_bf16 v[38:41], v[164:167], v[188:191], v[38:41]
	v_mfma_f32_16x16x32_bf16 v[34:37], v[172:175], v[188:191], v[34:37]
	v_mfma_f32_16x16x32_bf16 v[22:25], v[164:167], v[196:199], v[22:25]
	v_mfma_f32_16x16x32_bf16 v[18:21], v[172:175], v[196:199], v[18:21]
	v_mfma_f32_16x16x32_bf16 v[6:9], v[164:167], v[208:211], v[6:9]
	v_mfma_f32_16x16x32_bf16 v[2:5], v[172:175], v[208:211], v[2:5]
	s_setprio 0
	s_barrier
	s_add_i32 s71, s71, 2
	s_add_u32 s67, s67, 0x100
	s_addc_u32 s70, s70, 0
	s_add_u32 s20, s20, 0x100
	s_addc_u32 s21, s21, 0
	s_cmp_gt_u32 s71, 29
	s_cbranch_scc0 .LBB0_1034
	s_and_b64 vcc, exec, s[10:11]
	s_cbranch_vccz .LBB0_1037
	s_barrier

; #define PG8_STAGE(bufoff, gbase, voff) do { _Pragma("unroll") for (int _i = 0; _i < 2; ++_i) \
;         __builtin_amdgcn_global_load_lds((const unsigned*)((const char*)(gbase) + (voff)[_i]), (LAS unsigned*)(lds + (bufoff) + ldsw + _i * 8192), 16, 0, 0); } while (0)
; #define PG8_LDA(dst, b, h) do { _Pragma("unroll") for (int m = 0; m < 4; ++m) _Pragma("unroll") for (int k = 0; k < 2; ++k) dst[m][k] = *(const LAS bf16x8*)(lds + PG8_SA(b, h) + aoff + m * 2048 + k * 1024); } while (0)
; #define PG8_LDB(dst, b, h) do { _Pragma("unroll") for (int n = 0; n < 2; ++n) _Pragma("unroll") for (int k = 0; k < 2; ++k) dst[n][k] = *(const LAS bf16x8*)(lds + PG8_SB(b, h) + boff + n * 2048 + k * 1024); } while (0)
; #define PG8_MMA(ai, bj, At, Bt) do { __builtin_amdgcn_s_setprio(1); _Pragma("unroll") for (int m = 0; m < 4; ++m) _Pragma("unroll") for (int n = 0; n < 2; ++n) _Pragma("unroll") for (int k = 0; k < 2; ++k) \
;         acc[ai][bj][m][n] = __builtin_amdgcn_mfma_f32_16x16x32_bf16(Bt[n][k], At[m][k], acc[ai][bj][m][n], 0, 0, 0); __builtin_amdgcn_s_setprio(0); } while (0)
; #define PG8_WAIT_V(n) asm volatile("s_waitcnt vmcnt(" #n ")" ::: "memory")
; #define PG8_WAIT_L(n) asm volatile("s_waitcnt lgkmcnt(" #n ")" ::: "memory")
; #define PG8_BAR __builtin_amdgcn_s_barrier()
; #define PG8_SCHED __builtin_amdgcn_sched_barrier(0)
; template <class Epi>
; __device__ __forceinline__ void gemm_phase(LAS unsigned char* lds, const Gemm g, const StaticOrder& S, const Epi& E, int wave_s) {
;     ...
;         for (int t = 0; t < nt; t += 2) {
;             const bool last = (t == nt - 2);
;             const char* a1 = cA + (size_t)(t + 1) * kstep;
;             const char* a2 = last ? nA : cA + (size_t)(t + 2) * kstep; const char* b2 = last ? nB : cB + (size_t)(t + 2) * kstep;
;             const char* a3 = a2 + kstep; const char* b3 = b2 + kstep;
;             PG8_LDB(B0, 0, 0); PG8_LDB(B1, 0, 1); PG8_SCHED; PG8_LDA(At, 0, 0); PG8_STAGE(PG8_SA(1, 1), a1 + hstepA, voffA);
;             PG8_WAIT_V(8); PG8_WAIT_L(0); PG8_BAR; PG8_MMA(0, 0, At, B0); PG8_MMA(0, 1, At, B1); PG8_BAR; PG8_SCHED;
;             PG8_LDA(At, 0, 1); PG8_STAGE(PG8_SB(0, 0), b2, voffB); PG8_STAGE(PG8_SB(0, 1), b2 + hstepB, voffB); PG8_STAGE(PG8_SA(0, 0), a2, voffA);
;             PG8_WAIT_V(8); PG8_WAIT_L(0); PG8_BAR; PG8_MMA(1, 0, At, B0); PG8_MMA(1, 1, At, B1); PG8_BAR; PG8_SCHED;
.LBB0_1098:
	s_add_u32 s20, s18, 0xffe00080
	s_addc_u32 s21, s19, -1
	s_add_i32 s70, 0, 0x10000
	s_cmpk_eq_i32 s67, 0x7c
	s_cselect_b32 s23, s13, s21
	s_cselect_b32 s22, s57, s20
	s_cselect_b32 s21, s11, s66
	s_cselect_b32 s20, s64, s65
	s_add_i32 s72, 0, 0x14000
	v_add_u32_e32 v142, s70, v158
	v_add_u32_e32 v156, s72, v158
	ds_read_b128 v[130:133], v142
	ds_read_b128 v[134:137], v142 offset:1024
	ds_read_b128 v[138:141], v142 offset:2048
	ds_read_b128 v[142:145], v142 offset:3072
	ds_read_b128 v[152:155], v156
	ds_read_b128 v[160:163], v156 offset:1024
	ds_read_b128 v[164:167], v156 offset:2048
	ds_read_b128 v[168:171], v156 offset:3072
	v_lshl_add_u64 v[156:157], s[18:19], 0, v[150:151]
	s_add_i32 m0, s29, 0xc000
	ds_read_b128 v[172:175], v159
	ds_read_b128 v[176:179], v159 offset:1024
	ds_read_b128 v[180:183], v159 offset:2048
	ds_read_b128 v[184:187], v159 offset:3072
	ds_read_b128 v[188:191], v159 offset:4096
	ds_read_b128 v[192:195], v159 offset:5120
	ds_read_b128 v[196:199], v159 offset:6144
	ds_read_b128 v[200:203], v159 offset:7168
	global_load_lds_dwordx4 v[156:157], off
	v_lshl_add_u64 v[156:157], s[18:19], 0, v[148:149]
	s_add_i32 m0, s29, 0xe000
	s_nop 0
	global_load_lds_dwordx4 v[156:157], off
	s_waitcnt vmcnt(8)
	s_waitcnt lgkmcnt(0)
	s_setprio 1
	s_waitcnt lgkmcnt(0)
	v_mfma_f32_16x16x32_bf16 v[126:129], v[130:133], v[172:175], v[126:129]
	v_mfma_f32_16x16x32_bf16 v[122:125], v[138:141], v[172:175], v[122:125]
	v_mfma_f32_16x16x32_bf16 v[118:121], v[130:133], v[180:183], v[118:121]
	v_mfma_f32_16x16x32_bf16 v[114:117], v[138:141], v[180:183], v[114:117]
	s_barrier
	v_mfma_f32_16x16x32_bf16 v[110:113], v[130:133], v[188:191], v[110:113]
	v_mfma_f32_16x16x32_bf16 v[98:101], v[138:141], v[188:191], v[98:101]
	v_mfma_f32_16x16x32_bf16 v[82:85], v[130:133], v[196:199], v[82:85]
	v_mfma_f32_16x16x32_bf16 v[74:77], v[138:141], v[196:199], v[74:77]
	v_mfma_f32_16x16x32_bf16 v[126:129], v[134:137], v[176:179], v[126:129]
	v_mfma_f32_16x16x32_bf16 v[122:125], v[142:145], v[176:179], v[122:125]
	v_mfma_f32_16x16x32_bf16 v[118:121], v[134:137], v[184:187], v[118:121]
	v_mfma_f32_16x16x32_bf16 v[114:117], v[142:145], v[184:187], v[114:117]
	v_mfma_f32_16x16x32_bf16 v[110:113], v[134:137], v[192:195], v[110:113]
	v_mfma_f32_16x16x32_bf16 v[98:101], v[142:145], v[192:195], v[98:101]
	v_mfma_f32_16x16x32_bf16 v[82:85], v[134:137], v[200:203], v[82:85]
	v_mfma_f32_16x16x32_bf16 v[74:77], v[142:145], v[200:203], v[74:77]
	s_setprio 0
	s_setprio 1
	v_mfma_f32_16x16x32_bf16 v[106:109], v[152:155], v[172:175], v[106:109]
	v_mfma_f32_16x16x32_bf16 v[102:105], v[164:167], v[172:175], v[102:105]
	v_mfma_f32_16x16x32_bf16 v[94:97], v[152:155], v[180:183], v[94:97]
	v_mfma_f32_16x16x32_bf16 v[90:93], v[164:167], v[180:183], v[90:93]
	v_mfma_f32_16x16x32_bf16 v[86:89], v[152:155], v[188:191], v[86:89]
	v_mfma_f32_16x16x32_bf16 v[78:81], v[164:167], v[188:191], v[78:81]
	v_mfma_f32_16x16x32_bf16 v[70:73], v[152:155], v[196:199], v[70:73]
	v_mfma_f32_16x16x32_bf16 v[66:69], v[164:167], v[196:199], v[66:69]
	v_mfma_f32_16x16x32_bf16 v[106:109], v[160:163], v[176:179], v[106:109]
	v_mfma_f32_16x16x32_bf16 v[102:105], v[168:171], v[176:179], v[102:105]
	v_mfma_f32_16x16x32_bf16 v[94:97], v[160:163], v[184:187], v[94:97]
	v_mfma_f32_16x16x32_bf16 v[90:93], v[168:171], v[184:187], v[90:93]
	v_mfma_f32_16x16x32_bf16 v[86:89], v[160:163], v[192:195], v[86:89]
	v_mfma_f32_16x16x32_bf16 v[78:81], v[168:171], v[192:195], v[78:81]
	v_mfma_f32_16x16x32_bf16 v[70:73], v[160:163], v[200:203], v[70:73]
	v_mfma_f32_16x16x32_bf16 v[66:69], v[168:171], v[200:203], v[66:69]
	s_setprio 0
	s_barrier
	s_add_i32 s70, s70, s28
	v_lshl_add_u64 v[156:157], s[20:21], 0, v[0:1]
	s_mov_b32 m0, s70
	ds_read_b128 v[172:175], v159 offset:16384
	ds_read_b128 v[176:179], v159 offset:17408
	ds_read_b128 v[180:183], v159 offset:18432
	ds_read_b128 v[184:187], v159 offset:19456
	ds_read_b128 v[188:191], v159 offset:20480
	ds_read_b128 v[192:195], v159 offset:21504
	ds_read_b128 v[196:199], v159 offset:22528
	ds_read_b128 v[200:203], v159 offset:23552
	global_load_lds_dwordx4 v[156:157], off
	s_add_i32 m0, s70, 0x2000
	s_add_u32 s70, s20, 0x200000
	v_lshl_add_u64 v[204:205], s[20:21], 0, v[146:147]
	s_addc_u32 s71, s21, 0
	s_add_i32 s72, s72, s28
	global_load_lds_dwordx4 v[204:205], off
	s_mov_b32 m0, s72
	v_lshl_add_u64 v[208:209], s[22:23], 0, v[146:147]
	global_load_lds_dwordx4 v0, s[70:71]
	v_lshl_add_u64 v[206:207], s[70:71], 0, v[146:147]
	s_add_i32 m0, s72, 0x2000
	s_nop 0
	global_load_lds_dwordx4 v[206:207], off
	v_lshl_add_u64 v[206:207], s[22:23], 0, v[0:1]
	s_mov_b32 m0, s29
	s_nop 0
	global_load_lds_dwordx4 v[206:207], off
	s_mov_b32 m0, s30
	s_nop 0
	global_load_lds_dwordx4 v[208:209], off
	s_waitcnt vmcnt(8)
	s_waitcnt lgkmcnt(0)
	s_setprio 1
	s_waitcnt lgkmcnt(0)
	v_mfma_f32_16x16x32_bf16 v[62:65], v[130:133], v[172:175], v[62:65]
	v_mfma_f32_16x16x32_bf16 v[58:61], v[138:141], v[172:175], v[58:61]
	v_mfma_f32_16x16x32_bf16 v[54:57], v[130:133], v[180:183], v[54:57]
	v_mfma_f32_16x16x32_bf16 v[50:53], v[138:141], v[180:183], v[50:53]
	s_barrier
; #define PG8_STAGE(bufoff, gbase, voff) do { _Pragma("unroll") for (int _i = 0; _i < 2; ++_i) \
;         __builtin_amdgcn_global_load_lds((const unsigned*)((const char*)(gbase) + (voff)[_i]), (LAS unsigned*)(lds + (bufoff) + ldsw + _i * 8192), 16, 0, 0); } while (0)
; #define PG8_LDA(dst, b, h) do { _Pragma("unroll") for (int m = 0; m < 4; ++m) _Pragma("unroll") for (int k = 0; k < 2; ++k) dst[m][k] = *(const LAS bf16x8*)(lds + PG8_SA(b, h) + aoff + m * 2048 + k * 1024); } while (0)
; #define PG8_LDB(dst, b, h) do { _Pragma("unroll") for (int n = 0; n < 2; ++n) _Pragma("unroll") for (int k = 0; k < 2; ++k) dst[n][k] = *(const LAS bf16x8*)(lds + PG8_SB(b, h) + boff + n * 2048 + k * 1024); } while (0)
; #define PG8_MMA(ai, bj, At, Bt) do { __builtin_amdgcn_s_setprio(1); _Pragma("unroll") for (int m = 0; m < 4; ++m) _Pragma("unroll") for (int n = 0; n < 2; ++n) _Pragma("unroll") for (int k = 0; k < 2; ++k) \
;         acc[ai][bj][m][n] = __builtin_amdgcn_mfma_f32_16x16x32_bf16(Bt[n][k], At[m][k], acc[ai][bj][m][n], 0, 0, 0); __builtin_amdgcn_s_setprio(0); } while (0)
; #define PG8_WAIT_V(n) asm volatile("s_waitcnt vmcnt(" #n ")" ::: "memory")
; #define PG8_WAIT_L(n) asm volatile("s_waitcnt lgkmcnt(" #n ")" ::: "memory")
; #define PG8_BAR __builtin_amdgcn_s_barrier()
; #define PG8_SCHED __builtin_amdgcn_sched_barrier(0)
; template <class Epi>
; __device__ __forceinline__ void gemm_phase(LAS unsigned char* lds, const Gemm g, const StaticOrder& S, const Epi& E, int wave_s) {
;     ...
;             PG8_WAIT_V(8); PG8_WAIT_L(0); PG8_BAR; PG8_MMA(0, 0, At, B0); PG8_MMA(0, 1, At, B1); PG8_BAR; PG8_SCHED;
;             PG8_LDA(At, 0, 1); PG8_STAGE(PG8_SB(0, 0), b2, voffB); PG8_STAGE(PG8_SB(0, 1), b2 + hstepB, voffB); PG8_STAGE(PG8_SA(0, 0), a2, voffA);
;             PG8_WAIT_V(8); PG8_WAIT_L(0); PG8_BAR; PG8_MMA(1, 0, At, B0); PG8_MMA(1, 1, At, B1); PG8_BAR; PG8_SCHED;
;             PG8_LDB(B0, 1, 0); PG8_LDB(B1, 1, 1); PG8_SCHED; PG8_LDA(At, 1, 0); PG8_STAGE(PG8_SA(0, 1), a2 + hstepA, voffA);
;             PG8_WAIT_V(8); PG8_WAIT_L(0); PG8_BAR; PG8_MMA(0, 0, At, B0); PG8_MMA(0, 1, At, B1); PG8_BAR; PG8_SCHED;
	v_mfma_f32_16x16x32_bf16 v[46:49], v[130:133], v[188:191], v[46:49]
	v_mfma_f32_16x16x32_bf16 v[34:37], v[138:141], v[188:191], v[34:37]
	v_mfma_f32_16x16x32_bf16 v[22:25], v[130:133], v[196:199], v[22:25]
	v_mfma_f32_16x16x32_bf16 v[14:17], v[138:141], v[196:199], v[14:17]
	v_mfma_f32_16x16x32_bf16 v[62:65], v[134:137], v[176:179], v[62:65]
	v_mfma_f32_16x16x32_bf16 v[58:61], v[142:145], v[176:179], v[58:61]
	v_mfma_f32_16x16x32_bf16 v[54:57], v[134:137], v[184:187], v[54:57]
	v_mfma_f32_16x16x32_bf16 v[50:53], v[142:145], v[184:187], v[50:53]
	v_mfma_f32_16x16x32_bf16 v[46:49], v[134:137], v[192:195], v[46:49]
	v_mfma_f32_16x16x32_bf16 v[34:37], v[142:145], v[192:195], v[34:37]
	v_mfma_f32_16x16x32_bf16 v[22:25], v[134:137], v[200:203], v[22:25]
	v_mfma_f32_16x16x32_bf16 v[14:17], v[142:145], v[200:203], v[14:17]
	s_setprio 0
	s_setprio 1
	v_mfma_f32_16x16x32_bf16 v[42:45], v[152:155], v[172:175], v[42:45]
	v_mfma_f32_16x16x32_bf16 v[38:41], v[164:167], v[172:175], v[38:41]
	v_mfma_f32_16x16x32_bf16 v[30:33], v[152:155], v[180:183], v[30:33]
	v_mfma_f32_16x16x32_bf16 v[26:29], v[164:167], v[180:183], v[26:29]
	v_mfma_f32_16x16x32_bf16 v[18:21], v[152:155], v[188:191], v[18:21]
	v_mfma_f32_16x16x32_bf16 v[10:13], v[164:167], v[188:191], v[10:13]
	v_mfma_f32_16x16x32_bf16 v[6:9], v[152:155], v[196:199], v[6:9]
	v_mfma_f32_16x16x32_bf16 v[2:5], v[164:167], v[196:199], v[2:5]
	v_mfma_f32_16x16x32_bf16 v[42:45], v[160:163], v[176:179], v[42:45]
	v_mfma_f32_16x16x32_bf16 v[38:41], v[168:171], v[176:179], v[38:41]
	v_mfma_f32_16x16x32_bf16 v[30:33], v[160:163], v[184:187], v[30:33]
	v_mfma_f32_16x16x32_bf16 v[26:29], v[168:171], v[184:187], v[26:29]
	v_mfma_f32_16x16x32_bf16 v[18:21], v[160:163], v[192:195], v[18:21]
	v_mfma_f32_16x16x32_bf16 v[10:13], v[168:171], v[192:195], v[10:13]
	v_mfma_f32_16x16x32_bf16 v[6:9], v[160:163], v[200:203], v[6:9]
	v_mfma_f32_16x16x32_bf16 v[2:5], v[168:171], v[200:203], v[2:5]
	s_setprio 0
	s_barrier
	s_add_i32 s70, 0, 0x18000
	s_add_i32 s71, 0, 0x1c000
	v_add_u32_e32 v142, s70, v158
	v_add_u32_e32 v168, s71, v158
	ds_read_b128 v[130:133], v142
	ds_read_b128 v[134:137], v142 offset:1024
	ds_read_b128 v[138:141], v142 offset:2048
	ds_read_b128 v[142:145], v142 offset:3072
	ds_read_b128 v[152:155], v168
	ds_read_b128 v[160:163], v168 offset:1024
	ds_read_b128 v[164:167], v168 offset:2048
	ds_read_b128 v[168:171], v168 offset:3072
	s_add_u32 s22, s22, 0x200000
	s_addc_u32 s23, s23, 0
	s_mov_b32 m0, s31
	ds_read_b128 v[172:175], v159 offset:32768
	ds_read_b128 v[176:179], v159 offset:33792
	ds_read_b128 v[180:183], v159 offset:34816
	ds_read_b128 v[184:187], v159 offset:35840
	ds_read_b128 v[188:191], v159 offset:36864
	ds_read_b128 v[192:195], v159 offset:37888
	ds_read_b128 v[196:199], v159 offset:38912
	ds_read_b128 v[200:203], v159 offset:39936
	global_load_lds_dwordx4 v0, s[22:23]
	v_lshl_add_u64 v[210:211], s[22:23], 0, v[146:147]
	s_mov_b32 m0, s34
	s_nop 0
	global_load_lds_dwordx4 v[210:211], off
	s_waitcnt vmcnt(8)
	s_waitcnt lgkmcnt(0)
	s_setprio 1
	s_waitcnt lgkmcnt(0)
	v_mfma_f32_16x16x32_bf16 v[126:129], v[130:133], v[172:175], v[126:129]
	v_mfma_f32_16x16x32_bf16 v[122:125], v[138:141], v[172:175], v[122:125]
	v_mfma_f32_16x16x32_bf16 v[118:121], v[130:133], v[180:183], v[118:121]
	v_mfma_f32_16x16x32_bf16 v[114:117], v[138:141], v[180:183], v[114:117]
	s_barrier
	v_mfma_f32_16x16x32_bf16 v[110:113], v[130:133], v[188:191], v[110:113]
	v_mfma_f32_16x16x32_bf16 v[98:101], v[138:141], v[188:191], v[98:101]
	v_mfma_f32_16x16x32_bf16 v[82:85], v[130:133], v[196:199], v[82:85]
	v_mfma_f32_16x16x32_bf16 v[74:77], v[138:141], v[196:199], v[74:77]
	v_mfma_f32_16x16x32_bf16 v[126:129], v[134:137], v[176:179], v[126:129]
	v_mfma_f32_16x16x32_bf16 v[122:125], v[142:145], v[176:179], v[122:125]
	v_mfma_f32_16x16x32_bf16 v[118:121], v[134:137], v[184:187], v[118:121]
	v_mfma_f32_16x16x32_bf16 v[114:117], v[142:145], v[184:187], v[114:117]
	v_mfma_f32_16x16x32_bf16 v[110:113], v[134:137], v[192:195], v[110:113]
	v_mfma_f32_16x16x32_bf16 v[98:101], v[142:145], v[192:195], v[98:101]
	v_mfma_f32_16x16x32_bf16 v[82:85], v[134:137], v[200:203], v[82:85]
	v_mfma_f32_16x16x32_bf16 v[74:77], v[142:145], v[200:203], v[74:77]
	s_setprio 0
	s_setprio 1
	v_mfma_f32_16x16x32_bf16 v[106:109], v[152:155], v[172:175], v[106:109]
	v_mfma_f32_16x16x32_bf16 v[102:105], v[164:167], v[172:175], v[102:105]
	v_mfma_f32_16x16x32_bf16 v[94:97], v[152:155], v[180:183], v[94:97]
	v_mfma_f32_16x16x32_bf16 v[90:93], v[164:167], v[180:183], v[90:93]
	v_mfma_f32_16x16x32_bf16 v[86:89], v[152:155], v[188:191], v[86:89]
	v_mfma_f32_16x16x32_bf16 v[78:81], v[164:167], v[188:191], v[78:81]
	v_mfma_f32_16x16x32_bf16 v[70:73], v[152:155], v[196:199], v[70:73]
	v_mfma_f32_16x16x32_bf16 v[66:69], v[164:167], v[196:199], v[66:69]
	v_mfma_f32_16x16x32_bf16 v[106:109], v[160:163], v[176:179], v[106:109]
	v_mfma_f32_16x16x32_bf16 v[102:105], v[168:171], v[176:179], v[102:105]
	v_mfma_f32_16x16x32_bf16 v[94:97], v[160:163], v[184:187], v[94:97]
	v_mfma_f32_16x16x32_bf16 v[90:93], v[168:171], v[184:187], v[90:93]
	v_mfma_f32_16x16x32_bf16 v[86:89], v[160:163], v[192:195], v[86:89]
	v_mfma_f32_16x16x32_bf16 v[78:81], v[168:171], v[192:195], v[78:81]
	v_mfma_f32_16x16x32_bf16 v[70:73], v[160:163], v[200:203], v[70:73]
	v_mfma_f32_16x16x32_bf16 v[66:69], v[168:171], v[200:203], v[66:69]
	s_setprio 0
	s_barrier
; #define PG8_STAGE(bufoff, gbase, voff) do { _Pragma("unroll") for (int _i = 0; _i < 2; ++_i) \
;         __builtin_amdgcn_global_load_lds((const unsigned*)((const char*)(gbase) + (voff)[_i]), (LAS unsigned*)(lds + (bufoff) + ldsw + _i * 8192), 16, 0, 0); } while (0)
; #define PG8_LDA(dst, b, h) do { _Pragma("unroll") for (int m = 0; m < 4; ++m) _Pragma("unroll") for (int k = 0; k < 2; ++k) dst[m][k] = *(const LAS bf16x8*)(lds + PG8_SA(b, h) + aoff + m * 2048 + k * 1024); } while (0)
; #define PG8_MMA(ai, bj, At, Bt) do { __builtin_amdgcn_s_setprio(1); _Pragma("unroll") for (int m = 0; m < 4; ++m) _Pragma("unroll") for (int n = 0; n < 2; ++n) _Pragma("unroll") for (int k = 0; k < 2; ++k) \
;         acc[ai][bj][m][n] = __builtin_amdgcn_mfma_f32_16x16x32_bf16(Bt[n][k], At[m][k], acc[ai][bj][m][n], 0, 0, 0); __builtin_amdgcn_s_setprio(0); } while (0)
; #define PG8_WAIT_V(n) asm volatile("s_waitcnt vmcnt(" #n ")" ::: "memory")
; #define PG8_WAIT_L(n) asm volatile("s_waitcnt lgkmcnt(" #n ")" ::: "memory")
; #define PG8_BAR __builtin_amdgcn_s_barrier()
; #define PG8_SCHED __builtin_amdgcn_sched_barrier(0)
; template <class Epi>
; __device__ __forceinline__ void gemm_phase(LAS unsigned char* lds, const Gemm g, const StaticOrder& S, const Epi& E, int wave_s) {
;     ...
;             PG8_WAIT_V(8); PG8_WAIT_L(0); PG8_BAR; PG8_MMA(0, 0, At, B0); PG8_MMA(0, 1, At, B1); PG8_BAR; PG8_SCHED;
;             PG8_LDA(At, 1, 1); PG8_STAGE(PG8_SB(1, 0), b3, voffB); PG8_STAGE(PG8_SB(1, 1), b3 + hstepB, voffB); PG8_STAGE(PG8_SA(1, 0), a3, voffA);
;             PG8_WAIT_V(8); PG8_WAIT_L(0); PG8_BAR; PG8_MMA(1, 0, At, B0); PG8_MMA(1, 1, At, B1); PG8_BAR; PG8_SCHED;
;         }
;         if (wr == 0) PG8_BAR;
	s_add_i32 s22, s70, s28
	v_lshl_add_u64 v[156:157], v[156:157], 0, s[42:43]
	s_mov_b32 m0, s22
	ds_read_b128 v[172:175], v159 offset:49152
	ds_read_b128 v[176:179], v159 offset:50176
	ds_read_b128 v[180:183], v159 offset:51200
	ds_read_b128 v[184:187], v159 offset:52224
	ds_read_b128 v[188:191], v159 offset:53248
	ds_read_b128 v[192:195], v159 offset:54272
	ds_read_b128 v[196:199], v159 offset:55296
	ds_read_b128 v[200:203], v159 offset:56320
	global_load_lds_dwordx4 v[156:157], off
	s_add_i32 m0, s22, 0x2000
	s_add_u32 s20, s20, 0x200080
	v_lshl_add_u64 v[156:157], v[204:205], 0, s[42:43]
	s_addc_u32 s21, s21, 0
	s_add_i32 s22, s71, s28
	global_load_lds_dwordx4 v[156:157], off
	s_mov_b32 m0, s22
	s_nop 0
	global_load_lds_dwordx4 v0, s[20:21]
	v_lshl_add_u64 v[156:157], s[20:21], 0, v[146:147]
	s_add_i32 m0, s22, 0x2000
	s_nop 0
	global_load_lds_dwordx4 v[156:157], off
	v_lshl_add_u64 v[156:157], v[206:207], 0, s[42:43]
	s_mov_b32 m0, s38
	s_nop 0
	global_load_lds_dwordx4 v[156:157], off
	v_lshl_add_u64 v[156:157], v[208:209], 0, s[42:43]
	s_mov_b32 m0, s39
	s_nop 0
	global_load_lds_dwordx4 v[156:157], off
	s_waitcnt vmcnt(8)
	s_waitcnt lgkmcnt(0)
	s_setprio 1
	s_waitcnt lgkmcnt(0)
	v_mfma_f32_16x16x32_bf16 v[62:65], v[130:133], v[172:175], v[62:65]
	v_mfma_f32_16x16x32_bf16 v[58:61], v[138:141], v[172:175], v[58:61]
	v_mfma_f32_16x16x32_bf16 v[54:57], v[130:133], v[180:183], v[54:57]
	v_mfma_f32_16x16x32_bf16 v[50:53], v[138:141], v[180:183], v[50:53]
	s_barrier
	v_mfma_f32_16x16x32_bf16 v[46:49], v[130:133], v[188:191], v[46:49]
	v_mfma_f32_16x16x32_bf16 v[34:37], v[138:141], v[188:191], v[34:37]
	v_mfma_f32_16x16x32_bf16 v[22:25], v[130:133], v[196:199], v[22:25]
	v_mfma_f32_16x16x32_bf16 v[14:17], v[138:141], v[196:199], v[14:17]
	v_mfma_f32_16x16x32_bf16 v[62:65], v[134:137], v[176:179], v[62:65]
	v_mfma_f32_16x16x32_bf16 v[58:61], v[142:145], v[176:179], v[58:61]
	v_mfma_f32_16x16x32_bf16 v[54:57], v[134:137], v[184:187], v[54:57]
	v_mfma_f32_16x16x32_bf16 v[50:53], v[142:145], v[184:187], v[50:53]
	v_mfma_f32_16x16x32_bf16 v[46:49], v[134:137], v[192:195], v[46:49]
	v_mfma_f32_16x16x32_bf16 v[34:37], v[142:145], v[192:195], v[34:37]
	v_mfma_f32_16x16x32_bf16 v[22:25], v[134:137], v[200:203], v[22:25]
	v_mfma_f32_16x16x32_bf16 v[14:17], v[142:145], v[200:203], v[14:17]
	s_setprio 0
	s_setprio 1
	v_mfma_f32_16x16x32_bf16 v[42:45], v[152:155], v[172:175], v[42:45]
	v_mfma_f32_16x16x32_bf16 v[38:41], v[164:167], v[172:175], v[38:41]
	v_mfma_f32_16x16x32_bf16 v[30:33], v[152:155], v[180:183], v[30:33]
	v_mfma_f32_16x16x32_bf16 v[26:29], v[164:167], v[180:183], v[26:29]
	v_mfma_f32_16x16x32_bf16 v[18:21], v[152:155], v[188:191], v[18:21]
	v_mfma_f32_16x16x32_bf16 v[10:13], v[164:167], v[188:191], v[10:13]
	v_mfma_f32_16x16x32_bf16 v[6:9], v[152:155], v[196:199], v[6:9]
	v_mfma_f32_16x16x32_bf16 v[2:5], v[164:167], v[196:199], v[2:5]
	v_mfma_f32_16x16x32_bf16 v[42:45], v[160:163], v[176:179], v[42:45]
	v_mfma_f32_16x16x32_bf16 v[38:41], v[168:171], v[176:179], v[38:41]
	v_mfma_f32_16x16x32_bf16 v[30:33], v[160:163], v[184:187], v[30:33]
	v_mfma_f32_16x16x32_bf16 v[26:29], v[168:171], v[184:187], v[26:29]
	v_mfma_f32_16x16x32_bf16 v[18:21], v[160:163], v[192:195], v[18:21]
	v_mfma_f32_16x16x32_bf16 v[10:13], v[168:171], v[192:195], v[10:13]
	v_mfma_f32_16x16x32_bf16 v[6:9], v[160:163], v[200:203], v[6:9]
	v_mfma_f32_16x16x32_bf16 v[2:5], v[168:171], v[200:203], v[2:5]
	s_setprio 0
	s_barrier
	s_add_i32 s67, s67, 2
	s_add_u32 s65, s65, 0x100
	s_addc_u32 s66, s66, 0
	s_add_u32 s18, s18, 0x100
	s_addc_u32 s19, s19, 0
	s_cmpk_gt_u32 s67, 0x7d
	s_cbranch_scc0 .LBB0_1098
	s_and_b64 vcc, exec, s[8:9]
	s_cbranch_vccz .LBB0_1101
	s_barrier
